# K-loops: per-segment s_setprio toggling removed (all waves stay at priority 0)
# speedup vs baseline: 1.0052x; 1.0052x over previous
; #define PG8_STAGE(bufoff, gbase, voff) do { _Pragma("unroll") for (int _i = 0; _i < 2; ++_i) \
;         __builtin_amdgcn_global_load_lds((const unsigned*)((const char*)(gbase) + (voff)[_i]), (PG8_LAS unsigned*)(lds + (bufoff) + ldsw + _i * 8192), 16, 0, 0); } while (0)
; #define PG8_LDA(dst, b, h) do { _Pragma("unroll") for (int m = 0; m < 4; ++m) _Pragma("unroll") for (int k = 0; k < 2; ++k) dst[m][k] = *(const PG8_LAS bf16x8*)(lds + PG8_SA(b, h) + aoff + m * 2048 + k * 1024); } while (0)
; #define PG8_MMA(ai, bj, At, Bt) do { __builtin_amdgcn_s_setprio(1); _Pragma("unroll") for (int m = 0; m < 4; ++m) _Pragma("unroll") for (int n = 0; n < 2; ++n) _Pragma("unroll") for (int k = 0; k < 2; ++k) \
;         acc[ai][bj][m][n] = __builtin_amdgcn_mfma_f32_16x16x32_bf16(Bt[n][k], At[m][k], acc[ai][bj][m][n], 0, 0, 0); __builtin_amdgcn_s_setprio(0); } while (0)
; #define PG8_WAIT_V(n) asm volatile("s_waitcnt vmcnt(" #n ")" ::: "memory")
; #define PG8_WAIT_L(n) asm volatile("s_waitcnt lgkmcnt(" #n ")" ::: "memory")
; #define PG8_BAR __builtin_amdgcn_s_barrier()
; #define PG8_SCHED __builtin_amdgcn_sched_barrier(0)
; template <class Epi, class Sched, bool ALIGN_EPI = false, bool SP2 = false>
; __device__ __forceinline__ void gemm_phase(PG8_LAS unsigned char* lds, const Gemm g, const Sched& S, const Epi& E) {
;     ...
;             PG8_WAIT_V(8); PG8_WAIT_L(0); PG8_BAR; PG8_MMA(0, 0, At, B0); PG8_MMA(0, 1, At, B1); PG8_BAR; PG8_SCHED;
;             PG8_LDA(At, 0, 1); PG8_STAGE(PG8_SB(0, 0), b2, voffB); PG8_STAGE(PG8_SB(0, 1), b2 + hstep, voffB); PG8_STAGE(PG8_SA(0, 0), a2, voffA);
;             PG8_WAIT_V(8); PG8_WAIT_L(0); PG8_BAR; PG8_MMA(1, 0, At, B0); PG8_MMA(1, 1, At, B1); PG8_BAR; PG8_SCHED;
.Lpw_110_0:
	s_waitcnt lgkmcnt(0)
	s_barrier
	s_waitcnt lgkmcnt(0)
	v_mfma_f32_16x16x32_bf16 v[126:129], v[146:149], v[186:189], 0
	v_mfma_f32_16x16x32_bf16 v[122:125], v[154:157], v[186:189], 0
	v_mfma_f32_16x16x32_bf16 v[118:121], v[146:149], v[194:197], 0
	v_mfma_f32_16x16x32_bf16 v[114:117], v[154:157], v[194:197], 0
	v_mfma_f32_16x16x32_bf16 v[110:113], v[146:149], v[202:205], 0
	v_mfma_f32_16x16x32_bf16 v[106:109], v[154:157], v[202:205], 0
	v_mfma_f32_16x16x32_bf16 v[102:105], v[146:149], v[212:215], 0
	v_mfma_f32_16x16x32_bf16 v[98:101], v[154:157], v[212:215], 0
	v_mfma_f32_16x16x32_bf16 v[126:129], v[150:153], v[190:193], v[126:129]
	v_mfma_f32_16x16x32_bf16 v[122:125], v[166:169], v[190:193], v[122:125]
	v_mfma_f32_16x16x32_bf16 v[118:121], v[150:153], v[198:201], v[118:121]
	v_mfma_f32_16x16x32_bf16 v[114:117], v[166:169], v[198:201], v[114:117]
	v_mfma_f32_16x16x32_bf16 v[110:113], v[150:153], v[208:211], v[110:113]
	v_mfma_f32_16x16x32_bf16 v[106:109], v[166:169], v[208:211], v[106:109]
	v_mfma_f32_16x16x32_bf16 v[102:105], v[150:153], v[216:219], v[102:105]
	v_mfma_f32_16x16x32_bf16 v[98:101], v[166:169], v[216:219], v[98:101]
	v_mfma_f32_16x16x32_bf16 v[62:65], v[170:173], v[186:189], 0
	v_mfma_f32_16x16x32_bf16 v[58:61], v[178:181], v[186:189], 0
	v_mfma_f32_16x16x32_bf16 v[54:57], v[170:173], v[194:197], 0
	v_mfma_f32_16x16x32_bf16 v[50:53], v[178:181], v[194:197], 0
	v_mfma_f32_16x16x32_bf16 v[46:49], v[170:173], v[202:205], 0
	v_mfma_f32_16x16x32_bf16 v[42:45], v[178:181], v[202:205], 0
	v_mfma_f32_16x16x32_bf16 v[38:41], v[170:173], v[212:215], 0
	v_mfma_f32_16x16x32_bf16 v[34:37], v[178:181], v[212:215], 0
	v_mfma_f32_16x16x32_bf16 v[62:65], v[174:177], v[190:193], v[62:65]
	v_mfma_f32_16x16x32_bf16 v[58:61], v[182:185], v[190:193], v[58:61]
	v_mfma_f32_16x16x32_bf16 v[54:57], v[174:177], v[198:201], v[54:57]
	v_mfma_f32_16x16x32_bf16 v[50:53], v[182:185], v[198:201], v[50:53]
	v_mfma_f32_16x16x32_bf16 v[46:49], v[174:177], v[208:211], v[46:49]
	v_mfma_f32_16x16x32_bf16 v[42:45], v[182:185], v[208:211], v[42:45]
	v_mfma_f32_16x16x32_bf16 v[38:41], v[174:177], v[216:219], v[38:41]
	v_mfma_f32_16x16x32_bf16 v[34:37], v[182:185], v[216:219], v[34:37]
	s_barrier
	s_add_i32 s85, s30, s87
	s_mov_b32 m0, s85
	ds_read_b128 v[186:189], v162 offset:16384
	ds_read_b128 v[190:193], v162 offset:17408
	ds_read_b128 v[194:197], v162 offset:18432
	ds_read_b128 v[198:201], v162 offset:19456
	ds_read_b128 v[202:205], v162 offset:20480
	ds_read_b128 v[208:211], v162 offset:21504
	ds_read_b128 v[212:215], v162 offset:22528
	ds_read_b128 v[216:219], v162 offset:23552
	global_load_lds_dwordx4 v132, s[8:9]
	s_add_i32 m0, s85, 0x2000
	s_add_u32 vcc_lo, s8, 0x40000
	v_lshl_add_u64 v[222:223], s[8:9], 0, v[136:137]
	s_addc_u32 vcc_hi, s9, 0
	s_add_i32 s85, s31, s87
	global_load_lds_dwordx4 v136, s[8:9]
	s_mov_b32 m0, s85
	v_lshl_add_u64 v[226:227], s[82:83], 0, v[134:135]
	global_load_lds_dwordx4 v132, vcc
	s_add_i32 m0, s85, 0x2000
	s_nop 0
	global_load_lds_dwordx4 v136, vcc
	v_lshl_add_u64 v[224:225], s[82:83], 0, v[130:131]
	s_mov_b32 m0, s81
	s_nop 0
	global_load_lds_dwordx4 v130, s[82:83]
	s_mov_b32 m0, s88
	s_nop 0
	global_load_lds_dwordx4 v134, s[82:83]
	s_waitcnt vmcnt(24)
	s_cmp_gt_u32 s91, 1
	s_cbranch_scc1 .Lpw_110_1
	s_waitcnt vmcnt(8)
.Lpw_110_1:
	s_waitcnt lgkmcnt(0)
	s_barrier
	s_waitcnt lgkmcnt(0)
	v_mfma_f32_16x16x32_bf16 v[94:97], v[146:149], v[186:189], 0
	v_mfma_f32_16x16x32_bf16 v[90:93], v[154:157], v[186:189], 0
	v_mfma_f32_16x16x32_bf16 v[86:89], v[146:149], v[194:197], 0
	v_mfma_f32_16x16x32_bf16 v[82:85], v[154:157], v[194:197], 0
	v_mfma_f32_16x16x32_bf16 v[78:81], v[146:149], v[202:205], 0
	v_mfma_f32_16x16x32_bf16 v[74:77], v[154:157], v[202:205], 0
	v_mfma_f32_16x16x32_bf16 v[70:73], v[146:149], v[212:215], 0
	v_mfma_f32_16x16x32_bf16 v[66:69], v[154:157], v[212:215], 0
	v_mfma_f32_16x16x32_bf16 v[94:97], v[150:153], v[190:193], v[94:97]
	v_mfma_f32_16x16x32_bf16 v[90:93], v[166:169], v[190:193], v[90:93]
	v_mfma_f32_16x16x32_bf16 v[86:89], v[150:153], v[198:201], v[86:89]
	v_mfma_f32_16x16x32_bf16 v[82:85], v[166:169], v[198:201], v[82:85]
	v_mfma_f32_16x16x32_bf16 v[78:81], v[150:153], v[208:211], v[78:81]
	v_mfma_f32_16x16x32_bf16 v[74:77], v[166:169], v[208:211], v[74:77]
	v_mfma_f32_16x16x32_bf16 v[70:73], v[150:153], v[216:219], v[70:73]
	v_mfma_f32_16x16x32_bf16 v[66:69], v[166:169], v[216:219], v[66:69]
	v_mfma_f32_16x16x32_bf16 v[30:33], v[170:173], v[186:189], 0
	v_mfma_f32_16x16x32_bf16 v[26:29], v[178:181], v[186:189], 0
	v_mfma_f32_16x16x32_bf16 v[22:25], v[170:173], v[194:197], 0
	v_mfma_f32_16x16x32_bf16 v[18:21], v[178:181], v[194:197], 0
	v_mfma_f32_16x16x32_bf16 v[14:17], v[170:173], v[202:205], 0
	v_mfma_f32_16x16x32_bf16 v[10:13], v[178:181], v[202:205], 0
	v_mfma_f32_16x16x32_bf16 v[6:9], v[170:173], v[212:215], 0
	v_mfma_f32_16x16x32_bf16 v[2:5], v[178:181], v[212:215], 0
	v_mfma_f32_16x16x32_bf16 v[30:33], v[174:177], v[190:193], v[30:33]
	v_mfma_f32_16x16x32_bf16 v[26:29], v[182:185], v[190:193], v[26:29]
	v_mfma_f32_16x16x32_bf16 v[22:25], v[174:177], v[198:201], v[22:25]
	v_mfma_f32_16x16x32_bf16 v[18:21], v[182:185], v[198:201], v[18:21]
	v_mfma_f32_16x16x32_bf16 v[14:17], v[174:177], v[208:211], v[14:17]
	v_mfma_f32_16x16x32_bf16 v[10:13], v[182:185], v[208:211], v[10:13]
	v_mfma_f32_16x16x32_bf16 v[6:9], v[174:177], v[216:219], v[6:9]
	v_mfma_f32_16x16x32_bf16 v[2:5], v[182:185], v[216:219], v[2:5]
	s_barrier
; #define PG8_STAGE(bufoff, gbase, voff) do { _Pragma("unroll") for (int _i = 0; _i < 2; ++_i) \
;         __builtin_amdgcn_global_load_lds((const unsigned*)((const char*)(gbase) + (voff)[_i]), (PG8_LAS unsigned*)(lds + (bufoff) + ldsw + _i * 8192), 16, 0, 0); } while (0)
; #define PG8_LDA(dst, b, h) do { _Pragma("unroll") for (int m = 0; m < 4; ++m) _Pragma("unroll") for (int k = 0; k < 2; ++k) dst[m][k] = *(const PG8_LAS bf16x8*)(lds + PG8_SA(b, h) + aoff + m * 2048 + k * 1024); } while (0)
; #define PG8_LDB(dst, b, h) do { _Pragma("unroll") for (int n = 0; n < 2; ++n) _Pragma("unroll") for (int k = 0; k < 2; ++k) dst[n][k] = *(const PG8_LAS bf16x8*)(lds + PG8_SB(b, h) + boff + n * 2048 + k * 1024); } while (0)
; #define PG8_MMA(ai, bj, At, Bt) do { __builtin_amdgcn_s_setprio(1); _Pragma("unroll") for (int m = 0; m < 4; ++m) _Pragma("unroll") for (int n = 0; n < 2; ++n) _Pragma("unroll") for (int k = 0; k < 2; ++k) \
;         acc[ai][bj][m][n] = __builtin_amdgcn_mfma_f32_16x16x32_bf16(Bt[n][k], At[m][k], acc[ai][bj][m][n], 0, 0, 0); __builtin_amdgcn_s_setprio(0); } while (0)
; #define PG8_WAIT_V(n) asm volatile("s_waitcnt vmcnt(" #n ")" ::: "memory")
; #define PG8_WAIT_L(n) asm volatile("s_waitcnt lgkmcnt(" #n ")" ::: "memory")
; #define PG8_BAR __builtin_amdgcn_s_barrier()
; #define PG8_SCHED __builtin_amdgcn_sched_barrier(0)
; template <class Epi, class Sched, bool ALIGN_EPI = false, bool SP2 = false>
; __device__ __forceinline__ void gemm_phase(PG8_LAS unsigned char* lds, const Gemm g, const Sched& S, const Epi& E) {
;     ...
;             PG8_LDB(B0, 1, 0); PG8_LDB(B1, 1, 1); PG8_SCHED; PG8_LDA(At, 1, 0); PG8_STAGE(PG8_SA(0, 1), a2 + hstep, voffA);
;             PG8_WAIT_V(8); PG8_WAIT_L(0); PG8_BAR; PG8_MMA(0, 0, At, B0); PG8_MMA(0, 1, At, B1); PG8_BAR; PG8_SCHED;
;             PG8_LDA(At, 1, 1); PG8_STAGE(PG8_SB(1, 0), b3, voffB); PG8_STAGE(PG8_SB(1, 1), b3 + hstep, voffB); PG8_STAGE(PG8_SA(1, 0), a3, voffA);
;             PG8_WAIT_V(8); PG8_WAIT_L(0); PG8_BAR; PG8_MMA(1, 0, At, B0); PG8_MMA(1, 1, At, B1); PG8_BAR; PG8_SCHED;
	s_add_i32 s85, 0, 0x18000
	v_add_u32_e32 v165, s85, v158
	s_add_i32 vcc_lo, 0, 0x1c000
	ds_read_b128 v[146:149], v165
	ds_read_b128 v[150:153], v165 offset:1024
	ds_read_b128 v[154:157], v165 offset:2048
	ds_read_b128 v[166:169], v165 offset:3072
	v_add_u32_e32 v165, vcc_lo, v158
	ds_read_b128 v[170:173], v165
	ds_read_b128 v[174:177], v165 offset:1024
	ds_read_b128 v[178:181], v165 offset:2048
	ds_read_b128 v[182:185], v165 offset:3072
	s_add_u32 s82, s82, 0x40000
	s_addc_u32 s83, s83, 0
	s_mov_b32 m0, s89
	ds_read_b128 v[186:189], v162 offset:32768
	ds_read_b128 v[190:193], v162 offset:33792
	ds_read_b128 v[194:197], v162 offset:34816
	ds_read_b128 v[198:201], v162 offset:35840
	ds_read_b128 v[202:205], v162 offset:36864
	ds_read_b128 v[208:211], v162 offset:37888
	ds_read_b128 v[212:215], v162 offset:38912
	ds_read_b128 v[216:219], v162 offset:39936
	global_load_lds_dwordx4 v130, s[82:83]
	s_mov_b32 m0, s90
	s_nop 0
	global_load_lds_dwordx4 v134, s[82:83]
	s_waitcnt vmcnt(8)
	s_waitcnt lgkmcnt(0)
	s_barrier
	s_waitcnt lgkmcnt(0)
	v_mfma_f32_16x16x32_bf16 v[126:129], v[146:149], v[186:189], v[126:129]
	v_mfma_f32_16x16x32_bf16 v[122:125], v[154:157], v[186:189], v[122:125]
	v_mfma_f32_16x16x32_bf16 v[118:121], v[146:149], v[194:197], v[118:121]
	v_mfma_f32_16x16x32_bf16 v[114:117], v[154:157], v[194:197], v[114:117]
	v_mfma_f32_16x16x32_bf16 v[110:113], v[146:149], v[202:205], v[110:113]
	v_mfma_f32_16x16x32_bf16 v[106:109], v[154:157], v[202:205], v[106:109]
	v_mfma_f32_16x16x32_bf16 v[102:105], v[146:149], v[212:215], v[102:105]
	v_mfma_f32_16x16x32_bf16 v[98:101], v[154:157], v[212:215], v[98:101]
	v_mfma_f32_16x16x32_bf16 v[126:129], v[150:153], v[190:193], v[126:129]
	v_mfma_f32_16x16x32_bf16 v[122:125], v[166:169], v[190:193], v[122:125]
	v_mfma_f32_16x16x32_bf16 v[118:121], v[150:153], v[198:201], v[118:121]
	v_mfma_f32_16x16x32_bf16 v[114:117], v[166:169], v[198:201], v[114:117]
	v_mfma_f32_16x16x32_bf16 v[110:113], v[150:153], v[208:211], v[110:113]
	v_mfma_f32_16x16x32_bf16 v[106:109], v[166:169], v[208:211], v[106:109]
	v_mfma_f32_16x16x32_bf16 v[102:105], v[150:153], v[216:219], v[102:105]
	v_mfma_f32_16x16x32_bf16 v[98:101], v[166:169], v[216:219], v[98:101]
	v_mfma_f32_16x16x32_bf16 v[62:65], v[170:173], v[186:189], v[62:65]
	v_mfma_f32_16x16x32_bf16 v[58:61], v[178:181], v[186:189], v[58:61]
	v_mfma_f32_16x16x32_bf16 v[54:57], v[170:173], v[194:197], v[54:57]
	v_mfma_f32_16x16x32_bf16 v[50:53], v[178:181], v[194:197], v[50:53]
	v_mfma_f32_16x16x32_bf16 v[46:49], v[170:173], v[202:205], v[46:49]
	v_mfma_f32_16x16x32_bf16 v[42:45], v[178:181], v[202:205], v[42:45]
	v_mfma_f32_16x16x32_bf16 v[38:41], v[170:173], v[212:215], v[38:41]
	v_mfma_f32_16x16x32_bf16 v[34:37], v[178:181], v[212:215], v[34:37]
	v_mfma_f32_16x16x32_bf16 v[62:65], v[174:177], v[190:193], v[62:65]
	v_mfma_f32_16x16x32_bf16 v[58:61], v[182:185], v[190:193], v[58:61]
	v_mfma_f32_16x16x32_bf16 v[54:57], v[174:177], v[198:201], v[54:57]
	v_mfma_f32_16x16x32_bf16 v[50:53], v[182:185], v[198:201], v[50:53]
	v_mfma_f32_16x16x32_bf16 v[46:49], v[174:177], v[208:211], v[46:49]
	v_mfma_f32_16x16x32_bf16 v[42:45], v[182:185], v[208:211], v[42:45]
	v_mfma_f32_16x16x32_bf16 v[38:41], v[174:177], v[216:219], v[38:41]
	v_mfma_f32_16x16x32_bf16 v[34:37], v[182:185], v[216:219], v[34:37]
	s_barrier
	s_add_i32 s82, s85, s87
	s_mov_b32 m0, s82
	ds_read_b128 v[186:189], v162 offset:49152
	ds_read_b128 v[190:193], v162 offset:50176
	ds_read_b128 v[194:197], v162 offset:51200
	ds_read_b128 v[198:201], v162 offset:52224
	ds_read_b128 v[202:205], v162 offset:53248
	ds_read_b128 v[208:211], v162 offset:54272
	ds_read_b128 v[212:215], v162 offset:55296
	ds_read_b128 v[216:219], v162 offset:56320
	s_add_u32 s98, s8, s26
	s_addc_u32 s99, s9, s27
	global_load_lds_dwordx4 v132, s[98:99]
	s_add_i32 m0, s82, 0x2000
	s_add_u32 s8, s8, 0x40080
	v_lshl_add_u64 v[220:221], v[222:223], 0, s[26:27]
	s_addc_u32 s9, s9, 0
	s_add_i32 s82, vcc_lo, s87
	global_load_lds_dwordx4 v[220:221], off
	s_mov_b32 m0, s82
	s_nop 0
	global_load_lds_dwordx4 v132, s[8:9]
	s_add_i32 m0, s82, 0x2000
	s_nop 0
	global_load_lds_dwordx4 v136, s[8:9]
	v_lshl_add_u64 v[220:221], v[224:225], 0, s[26:27]
	s_mov_b32 m0, s92
	s_nop 0
	global_load_lds_dwordx4 v[220:221], off
	v_lshl_add_u64 v[220:221], v[226:227], 0, s[26:27]
	s_mov_b32 m0, s93
	s_nop 0
	global_load_lds_dwordx4 v[220:221], off
	s_waitcnt vmcnt(8)
	s_waitcnt lgkmcnt(0)
	s_barrier
	s_waitcnt lgkmcnt(0)
	v_mfma_f32_16x16x32_bf16 v[94:97], v[146:149], v[186:189], v[94:97]
	v_mfma_f32_16x16x32_bf16 v[90:93], v[154:157], v[186:189], v[90:93]
	v_mfma_f32_16x16x32_bf16 v[86:89], v[146:149], v[194:197], v[86:89]
	v_mfma_f32_16x16x32_bf16 v[82:85], v[154:157], v[194:197], v[82:85]
	v_mfma_f32_16x16x32_bf16 v[78:81], v[146:149], v[202:205], v[78:81]
	v_mfma_f32_16x16x32_bf16 v[74:77], v[154:157], v[202:205], v[74:77]
	v_mfma_f32_16x16x32_bf16 v[70:73], v[146:149], v[212:215], v[70:73]
	v_mfma_f32_16x16x32_bf16 v[66:69], v[154:157], v[212:215], v[66:69]
	v_mfma_f32_16x16x32_bf16 v[94:97], v[150:153], v[190:193], v[94:97]
	v_mfma_f32_16x16x32_bf16 v[90:93], v[166:169], v[190:193], v[90:93]
	v_mfma_f32_16x16x32_bf16 v[86:89], v[150:153], v[198:201], v[86:89]
	v_mfma_f32_16x16x32_bf16 v[82:85], v[166:169], v[198:201], v[82:85]
	v_mfma_f32_16x16x32_bf16 v[78:81], v[150:153], v[208:211], v[78:81]
	v_mfma_f32_16x16x32_bf16 v[74:77], v[166:169], v[208:211], v[74:77]
	v_mfma_f32_16x16x32_bf16 v[70:73], v[150:153], v[216:219], v[70:73]
	v_mfma_f32_16x16x32_bf16 v[66:69], v[166:169], v[216:219], v[66:69]
	v_mfma_f32_16x16x32_bf16 v[30:33], v[170:173], v[186:189], v[30:33]
	v_mfma_f32_16x16x32_bf16 v[26:29], v[178:181], v[186:189], v[26:29]
	v_mfma_f32_16x16x32_bf16 v[22:25], v[170:173], v[194:197], v[22:25]
	v_mfma_f32_16x16x32_bf16 v[18:21], v[178:181], v[194:197], v[18:21]
	v_mfma_f32_16x16x32_bf16 v[14:17], v[170:173], v[202:205], v[14:17]
	v_mfma_f32_16x16x32_bf16 v[10:13], v[178:181], v[202:205], v[10:13]
	v_mfma_f32_16x16x32_bf16 v[6:9], v[170:173], v[212:215], v[6:9]
	v_mfma_f32_16x16x32_bf16 v[2:5], v[178:181], v[212:215], v[2:5]
	v_mfma_f32_16x16x32_bf16 v[30:33], v[174:177], v[190:193], v[30:33]
	v_mfma_f32_16x16x32_bf16 v[26:29], v[182:185], v[190:193], v[26:29]
	v_mfma_f32_16x16x32_bf16 v[22:25], v[174:177], v[198:201], v[22:25]
	v_mfma_f32_16x16x32_bf16 v[18:21], v[182:185], v[198:201], v[18:21]
	v_mfma_f32_16x16x32_bf16 v[14:17], v[174:177], v[208:211], v[14:17]
	v_mfma_f32_16x16x32_bf16 v[10:13], v[182:185], v[208:211], v[10:13]
	v_mfma_f32_16x16x32_bf16 v[6:9], v[174:177], v[216:219], v[6:9]
	v_mfma_f32_16x16x32_bf16 v[2:5], v[182:185], v[216:219], v[2:5]
	s_add_i32 s84, s84, 2
	s_add_u32 s6, s6, 0x100
	s_addc_u32 s7, s7, 0
	s_add_u32 s73, s73, 0x100
	s_addc_u32 s75, s75, 0
	s_cmp_gt_u32 s84, 13
	s_barrier
; #define PG8_STAGE(bufoff, gbase, voff) do { _Pragma("unroll") for (int _i = 0; _i < 2; ++_i) \
;         __builtin_amdgcn_global_load_lds((const unsigned*)((const char*)(gbase) + (voff)[_i]), (PG8_LAS unsigned*)(lds + (bufoff) + ldsw + _i * 8192), 16, 0, 0); } while (0)
; #define PG8_LDA(dst, b, h) do { _Pragma("unroll") for (int m = 0; m < 4; ++m) _Pragma("unroll") for (int k = 0; k < 2; ++k) dst[m][k] = *(const PG8_LAS bf16x8*)(lds + PG8_SA(b, h) + aoff + m * 2048 + k * 1024); } while (0)
; #define PG8_LDB(dst, b, h) do { _Pragma("unroll") for (int n = 0; n < 2; ++n) _Pragma("unroll") for (int k = 0; k < 2; ++k) dst[n][k] = *(const PG8_LAS bf16x8*)(lds + PG8_SB(b, h) + boff + n * 2048 + k * 1024); } while (0)
; #define PG8_MMA(ai, bj, At, Bt) do { __builtin_amdgcn_s_setprio(1); _Pragma("unroll") for (int m = 0; m < 4; ++m) _Pragma("unroll") for (int n = 0; n < 2; ++n) _Pragma("unroll") for (int k = 0; k < 2; ++k) \
;         acc[ai][bj][m][n] = __builtin_amdgcn_mfma_f32_16x16x32_bf16(Bt[n][k], At[m][k], acc[ai][bj][m][n], 0, 0, 0); __builtin_amdgcn_s_setprio(0); } while (0)
; #define PG8_WAIT_V(n) asm volatile("s_waitcnt vmcnt(" #n ")" ::: "memory")
; #define PG8_WAIT_L(n) asm volatile("s_waitcnt lgkmcnt(" #n ")" ::: "memory")
; template <class Epi, class Sched, bool ALIGN_EPI = false, bool SP2 = false>
; __device__ __forceinline__ void gemm_phase(PG8_LAS unsigned char* lds, const Gemm g, const Sched& S, const Epi& E) {
;     ...
;             const bool last = (t == nt - 2);
;             const char* a1 = cA + (size_t)(t + 1) * kstep;
;             const char* a2 = last ? nA : cA + (size_t)(t + 2) * kstep; const char* b2 = last ? nB : cB + (size_t)(t + 2) * kstep;
;             const char* a3 = a2 + kstep; const char* b3 = b2 + kstep;
;             if (last && has_next) S.a_ready(nxt);
;             if constexpr (SP2) {
;             PG8_LDB(B0, 0, 0); PG8_LDB(B1, 0, 1); PG8_SCHED; PG8_LDA(At, 0, 0); PG8_STAGE(PG8_SA(1, 1), a1 + hstep, voffA);
;             PG8_WAIT_V(8); PG8_WAIT_L(0); PG8_BAR; PG8_MMA(0, 0, At, B0); PG8_MMA(0, 1, At, B1); PG8_BAR; PG8_SCHED;
;             PG8_LDA(At, 0, 1); PG8_STAGE(PG8_SB(0, 0), b2, voffB); PG8_STAGE(PG8_SB(0, 1), b2 + hstep, voffB); PG8_STAGE(PG8_SA(0, 0), a2, voffA);
;             PG8_WAIT_V(8); PG8_WAIT_L(0); PG8_BAR; PG8_MMA(1, 0, At, B0); PG8_MMA(1, 1, At, B1); PG8_BAR; PG8_SCHED;
.LBB0_110:
	ds_read_b128 v[146:149], v160
	ds_read_b128 v[150:153], v160 offset:1024
	ds_read_b128 v[154:157], v160 offset:2048
	ds_read_b128 v[166:169], v160 offset:3072
	ds_read_b128 v[170:173], v161
	ds_read_b128 v[174:177], v161 offset:1024
	ds_read_b128 v[178:181], v161 offset:2048
	ds_read_b128 v[182:185], v161 offset:3072
	s_add_u32 s8, s6, 0xfffc0080
	s_addc_u32 s9, s7, -1
	s_cmp_eq_u32 s84, 12
	s_cselect_b32 s83, s1, s9
	s_cselect_b32 s82, s33, s8
	s_cselect_b32 s9, s60, s75
	s_cselect_b32 s8, s61, s73
	v_lshl_add_u64 v[220:221], s[6:7], 0, v[138:139]
	s_add_i32 m0, s81, 0xc000
	ds_read_b128 v[186:189], v162
	ds_read_b128 v[190:193], v162 offset:1024
	ds_read_b128 v[194:197], v162 offset:2048
	ds_read_b128 v[198:201], v162 offset:3072
	ds_read_b128 v[202:205], v162 offset:4096
	ds_read_b128 v[208:211], v162 offset:5120
	ds_read_b128 v[212:215], v162 offset:6144
	ds_read_b128 v[216:219], v162 offset:7168
	global_load_lds_dwordx4 v[220:221], off
	v_lshl_add_u64 v[220:221], s[6:7], 0, v[140:141]
	s_add_i32 m0, s81, 0xe000
	s_nop 0
	global_load_lds_dwordx4 v[220:221], off
	s_waitcnt vmcnt(8)
	s_waitcnt lgkmcnt(0)
	s_barrier
	s_waitcnt lgkmcnt(0)
	v_mfma_f32_16x16x32_bf16 v[126:129], v[146:149], v[186:189], v[126:129]
	v_mfma_f32_16x16x32_bf16 v[122:125], v[154:157], v[186:189], v[122:125]
	v_mfma_f32_16x16x32_bf16 v[118:121], v[146:149], v[194:197], v[118:121]
	v_mfma_f32_16x16x32_bf16 v[114:117], v[154:157], v[194:197], v[114:117]
	v_mfma_f32_16x16x32_bf16 v[110:113], v[146:149], v[202:205], v[110:113]
	v_mfma_f32_16x16x32_bf16 v[106:109], v[154:157], v[202:205], v[106:109]
	v_mfma_f32_16x16x32_bf16 v[102:105], v[146:149], v[212:215], v[102:105]
	v_mfma_f32_16x16x32_bf16 v[98:101], v[154:157], v[212:215], v[98:101]
	v_mfma_f32_16x16x32_bf16 v[126:129], v[150:153], v[190:193], v[126:129]
	v_mfma_f32_16x16x32_bf16 v[122:125], v[166:169], v[190:193], v[122:125]
	v_mfma_f32_16x16x32_bf16 v[118:121], v[150:153], v[198:201], v[118:121]
	v_mfma_f32_16x16x32_bf16 v[114:117], v[166:169], v[198:201], v[114:117]
	v_mfma_f32_16x16x32_bf16 v[110:113], v[150:153], v[208:211], v[110:113]
	v_mfma_f32_16x16x32_bf16 v[106:109], v[166:169], v[208:211], v[106:109]
	v_mfma_f32_16x16x32_bf16 v[102:105], v[150:153], v[216:219], v[102:105]
	v_mfma_f32_16x16x32_bf16 v[98:101], v[166:169], v[216:219], v[98:101]
	v_mfma_f32_16x16x32_bf16 v[62:65], v[170:173], v[186:189], v[62:65]
	v_mfma_f32_16x16x32_bf16 v[58:61], v[178:181], v[186:189], v[58:61]
	v_mfma_f32_16x16x32_bf16 v[54:57], v[170:173], v[194:197], v[54:57]
	v_mfma_f32_16x16x32_bf16 v[50:53], v[178:181], v[194:197], v[50:53]
	v_mfma_f32_16x16x32_bf16 v[46:49], v[170:173], v[202:205], v[46:49]
	v_mfma_f32_16x16x32_bf16 v[42:45], v[178:181], v[202:205], v[42:45]
	v_mfma_f32_16x16x32_bf16 v[38:41], v[170:173], v[212:215], v[38:41]
	v_mfma_f32_16x16x32_bf16 v[34:37], v[178:181], v[212:215], v[34:37]
	v_mfma_f32_16x16x32_bf16 v[62:65], v[174:177], v[190:193], v[62:65]
	v_mfma_f32_16x16x32_bf16 v[58:61], v[182:185], v[190:193], v[58:61]
	v_mfma_f32_16x16x32_bf16 v[54:57], v[174:177], v[198:201], v[54:57]
	v_mfma_f32_16x16x32_bf16 v[50:53], v[182:185], v[198:201], v[50:53]
	v_mfma_f32_16x16x32_bf16 v[46:49], v[174:177], v[208:211], v[46:49]
	v_mfma_f32_16x16x32_bf16 v[42:45], v[182:185], v[208:211], v[42:45]
	v_mfma_f32_16x16x32_bf16 v[38:41], v[174:177], v[216:219], v[38:41]
	v_mfma_f32_16x16x32_bf16 v[34:37], v[182:185], v[216:219], v[34:37]
	s_barrier
	s_add_i32 s85, s30, s87
	s_mov_b32 m0, s85
	ds_read_b128 v[186:189], v162 offset:16384
	ds_read_b128 v[190:193], v162 offset:17408
	ds_read_b128 v[194:197], v162 offset:18432
	ds_read_b128 v[198:201], v162 offset:19456
	ds_read_b128 v[202:205], v162 offset:20480
	ds_read_b128 v[208:211], v162 offset:21504
	ds_read_b128 v[212:215], v162 offset:22528
	ds_read_b128 v[216:219], v162 offset:23552
	global_load_lds_dwordx4 v132, s[8:9]
	s_add_i32 m0, s85, 0x2000
	s_add_u32 vcc_lo, s8, 0x40000
	v_lshl_add_u64 v[222:223], s[8:9], 0, v[136:137]
	s_addc_u32 vcc_hi, s9, 0
	s_add_i32 s85, s31, s87
	global_load_lds_dwordx4 v136, s[8:9]
	s_mov_b32 m0, s85
	v_lshl_add_u64 v[226:227], s[82:83], 0, v[134:135]
	global_load_lds_dwordx4 v132, vcc
	s_add_i32 m0, s85, 0x2000
	s_nop 0
	global_load_lds_dwordx4 v136, vcc
	v_lshl_add_u64 v[224:225], s[82:83], 0, v[130:131]
	s_mov_b32 m0, s81
	s_nop 0
	global_load_lds_dwordx4 v130, s[82:83]
	s_mov_b32 m0, s88
	s_nop 0
	global_load_lds_dwordx4 v134, s[82:83]
	s_waitcnt vmcnt(8)
	s_waitcnt lgkmcnt(0)
	s_barrier
	s_waitcnt lgkmcnt(0)
	v_mfma_f32_16x16x32_bf16 v[94:97], v[146:149], v[186:189], v[94:97]
	v_mfma_f32_16x16x32_bf16 v[90:93], v[154:157], v[186:189], v[90:93]
	v_mfma_f32_16x16x32_bf16 v[86:89], v[146:149], v[194:197], v[86:89]
	v_mfma_f32_16x16x32_bf16 v[82:85], v[154:157], v[194:197], v[82:85]
	v_mfma_f32_16x16x32_bf16 v[78:81], v[146:149], v[202:205], v[78:81]
	v_mfma_f32_16x16x32_bf16 v[74:77], v[154:157], v[202:205], v[74:77]
	v_mfma_f32_16x16x32_bf16 v[70:73], v[146:149], v[212:215], v[70:73]
	v_mfma_f32_16x16x32_bf16 v[66:69], v[154:157], v[212:215], v[66:69]
	v_mfma_f32_16x16x32_bf16 v[94:97], v[150:153], v[190:193], v[94:97]
	v_mfma_f32_16x16x32_bf16 v[90:93], v[166:169], v[190:193], v[90:93]
	v_mfma_f32_16x16x32_bf16 v[86:89], v[150:153], v[198:201], v[86:89]
	v_mfma_f32_16x16x32_bf16 v[82:85], v[166:169], v[198:201], v[82:85]
	v_mfma_f32_16x16x32_bf16 v[78:81], v[150:153], v[208:211], v[78:81]
	v_mfma_f32_16x16x32_bf16 v[74:77], v[166:169], v[208:211], v[74:77]
	v_mfma_f32_16x16x32_bf16 v[70:73], v[150:153], v[216:219], v[70:73]
	v_mfma_f32_16x16x32_bf16 v[66:69], v[166:169], v[216:219], v[66:69]
	v_mfma_f32_16x16x32_bf16 v[30:33], v[170:173], v[186:189], v[30:33]
	v_mfma_f32_16x16x32_bf16 v[26:29], v[178:181], v[186:189], v[26:29]
	v_mfma_f32_16x16x32_bf16 v[22:25], v[170:173], v[194:197], v[22:25]
	v_mfma_f32_16x16x32_bf16 v[18:21], v[178:181], v[194:197], v[18:21]
	v_mfma_f32_16x16x32_bf16 v[14:17], v[170:173], v[202:205], v[14:17]
	v_mfma_f32_16x16x32_bf16 v[10:13], v[178:181], v[202:205], v[10:13]
	v_mfma_f32_16x16x32_bf16 v[6:9], v[170:173], v[212:215], v[6:9]
	v_mfma_f32_16x16x32_bf16 v[2:5], v[178:181], v[212:215], v[2:5]
	v_mfma_f32_16x16x32_bf16 v[30:33], v[174:177], v[190:193], v[30:33]
	v_mfma_f32_16x16x32_bf16 v[26:29], v[182:185], v[190:193], v[26:29]
	v_mfma_f32_16x16x32_bf16 v[22:25], v[174:177], v[198:201], v[22:25]
	v_mfma_f32_16x16x32_bf16 v[18:21], v[182:185], v[198:201], v[18:21]
	v_mfma_f32_16x16x32_bf16 v[14:17], v[174:177], v[208:211], v[14:17]
	v_mfma_f32_16x16x32_bf16 v[10:13], v[182:185], v[208:211], v[10:13]
	v_mfma_f32_16x16x32_bf16 v[6:9], v[174:177], v[216:219], v[6:9]
	v_mfma_f32_16x16x32_bf16 v[2:5], v[182:185], v[216:219], v[2:5]
	s_barrier
; #define PG8_STAGE(bufoff, gbase, voff) do { _Pragma("unroll") for (int _i = 0; _i < 2; ++_i) \
;         __builtin_amdgcn_global_load_lds((const unsigned*)((const char*)(gbase) + (voff)[_i]), (PG8_LAS unsigned*)(lds + (bufoff) + ldsw + _i * 8192), 16, 0, 0); } while (0)
; #define PG8_LDA(dst, b, h) do { _Pragma("unroll") for (int m = 0; m < 4; ++m) _Pragma("unroll") for (int k = 0; k < 2; ++k) dst[m][k] = *(const PG8_LAS bf16x8*)(lds + PG8_SA(b, h) + aoff + m * 2048 + k * 1024); } while (0)
; #define PG8_LDB(dst, b, h) do { _Pragma("unroll") for (int n = 0; n < 2; ++n) _Pragma("unroll") for (int k = 0; k < 2; ++k) dst[n][k] = *(const PG8_LAS bf16x8*)(lds + PG8_SB(b, h) + boff + n * 2048 + k * 1024); } while (0)
; #define PG8_MMA(ai, bj, At, Bt) do { __builtin_amdgcn_s_setprio(1); _Pragma("unroll") for (int m = 0; m < 4; ++m) _Pragma("unroll") for (int n = 0; n < 2; ++n) _Pragma("unroll") for (int k = 0; k < 2; ++k) \
;         acc[ai][bj][m][n] = __builtin_amdgcn_mfma_f32_16x16x32_bf16(Bt[n][k], At[m][k], acc[ai][bj][m][n], 0, 0, 0); __builtin_amdgcn_s_setprio(0); } while (0)
; #define PG8_WAIT_V(n) asm volatile("s_waitcnt vmcnt(" #n ")" ::: "memory")
; #define PG8_WAIT_L(n) asm volatile("s_waitcnt lgkmcnt(" #n ")" ::: "memory")
; #define PG8_BAR __builtin_amdgcn_s_barrier()
; #define PG8_SCHED __builtin_amdgcn_sched_barrier(0)
; template <class Epi, class Sched, bool ALIGN_EPI = false, bool SP2 = false>
; __device__ __forceinline__ void gemm_phase(PG8_LAS unsigned char* lds, const Gemm g, const Sched& S, const Epi& E) {
;     ...
;             PG8_LDB(B0, 1, 0); PG8_LDB(B1, 1, 1); PG8_SCHED; PG8_LDA(At, 1, 0); PG8_STAGE(PG8_SA(0, 1), a2 + hstep, voffA);
;             PG8_WAIT_V(8); PG8_WAIT_L(0); PG8_BAR; PG8_MMA(0, 0, At, B0); PG8_MMA(0, 1, At, B1); PG8_BAR; PG8_SCHED;
;             PG8_LDA(At, 1, 1); PG8_STAGE(PG8_SB(1, 0), b3, voffB); PG8_STAGE(PG8_SB(1, 1), b3 + hstep, voffB); PG8_STAGE(PG8_SA(1, 0), a3, voffA);
;             PG8_WAIT_V(8); PG8_WAIT_L(0); PG8_BAR; PG8_MMA(1, 0, At, B0); PG8_MMA(1, 1, At, B1); PG8_BAR; PG8_SCHED;
	s_add_i32 s85, 0, 0x18000
	v_add_u32_e32 v165, s85, v158
	s_add_i32 vcc_lo, 0, 0x1c000
	ds_read_b128 v[146:149], v165
	ds_read_b128 v[150:153], v165 offset:1024
	ds_read_b128 v[154:157], v165 offset:2048
	ds_read_b128 v[166:169], v165 offset:3072
	v_add_u32_e32 v165, vcc_lo, v158
	ds_read_b128 v[170:173], v165
	ds_read_b128 v[174:177], v165 offset:1024
	ds_read_b128 v[178:181], v165 offset:2048
	ds_read_b128 v[182:185], v165 offset:3072
	s_add_u32 s82, s82, 0x40000
	s_addc_u32 s83, s83, 0
	s_mov_b32 m0, s89
	ds_read_b128 v[186:189], v162 offset:32768
	ds_read_b128 v[190:193], v162 offset:33792
	ds_read_b128 v[194:197], v162 offset:34816
	ds_read_b128 v[198:201], v162 offset:35840
	ds_read_b128 v[202:205], v162 offset:36864
	ds_read_b128 v[208:211], v162 offset:37888
	ds_read_b128 v[212:215], v162 offset:38912
	ds_read_b128 v[216:219], v162 offset:39936
	global_load_lds_dwordx4 v130, s[82:83]
	s_mov_b32 m0, s90
	s_nop 0
	global_load_lds_dwordx4 v134, s[82:83]
	s_waitcnt vmcnt(8)
	s_waitcnt lgkmcnt(0)
	s_barrier
	s_waitcnt lgkmcnt(0)
	v_mfma_f32_16x16x32_bf16 v[126:129], v[146:149], v[186:189], v[126:129]
	v_mfma_f32_16x16x32_bf16 v[122:125], v[154:157], v[186:189], v[122:125]
	v_mfma_f32_16x16x32_bf16 v[118:121], v[146:149], v[194:197], v[118:121]
	v_mfma_f32_16x16x32_bf16 v[114:117], v[154:157], v[194:197], v[114:117]
	v_mfma_f32_16x16x32_bf16 v[110:113], v[146:149], v[202:205], v[110:113]
	v_mfma_f32_16x16x32_bf16 v[106:109], v[154:157], v[202:205], v[106:109]
	v_mfma_f32_16x16x32_bf16 v[102:105], v[146:149], v[212:215], v[102:105]
	v_mfma_f32_16x16x32_bf16 v[98:101], v[154:157], v[212:215], v[98:101]
	v_mfma_f32_16x16x32_bf16 v[126:129], v[150:153], v[190:193], v[126:129]
	v_mfma_f32_16x16x32_bf16 v[122:125], v[166:169], v[190:193], v[122:125]
	v_mfma_f32_16x16x32_bf16 v[118:121], v[150:153], v[198:201], v[118:121]
	v_mfma_f32_16x16x32_bf16 v[114:117], v[166:169], v[198:201], v[114:117]
	v_mfma_f32_16x16x32_bf16 v[110:113], v[150:153], v[208:211], v[110:113]
	v_mfma_f32_16x16x32_bf16 v[106:109], v[166:169], v[208:211], v[106:109]
	v_mfma_f32_16x16x32_bf16 v[102:105], v[150:153], v[216:219], v[102:105]
	v_mfma_f32_16x16x32_bf16 v[98:101], v[166:169], v[216:219], v[98:101]
	v_mfma_f32_16x16x32_bf16 v[62:65], v[170:173], v[186:189], v[62:65]
	v_mfma_f32_16x16x32_bf16 v[58:61], v[178:181], v[186:189], v[58:61]
	v_mfma_f32_16x16x32_bf16 v[54:57], v[170:173], v[194:197], v[54:57]
	v_mfma_f32_16x16x32_bf16 v[50:53], v[178:181], v[194:197], v[50:53]
	v_mfma_f32_16x16x32_bf16 v[46:49], v[170:173], v[202:205], v[46:49]
	v_mfma_f32_16x16x32_bf16 v[42:45], v[178:181], v[202:205], v[42:45]
	v_mfma_f32_16x16x32_bf16 v[38:41], v[170:173], v[212:215], v[38:41]
	v_mfma_f32_16x16x32_bf16 v[34:37], v[178:181], v[212:215], v[34:37]
	v_mfma_f32_16x16x32_bf16 v[62:65], v[174:177], v[190:193], v[62:65]
	v_mfma_f32_16x16x32_bf16 v[58:61], v[182:185], v[190:193], v[58:61]
	v_mfma_f32_16x16x32_bf16 v[54:57], v[174:177], v[198:201], v[54:57]
	v_mfma_f32_16x16x32_bf16 v[50:53], v[182:185], v[198:201], v[50:53]
	v_mfma_f32_16x16x32_bf16 v[46:49], v[174:177], v[208:211], v[46:49]
	v_mfma_f32_16x16x32_bf16 v[42:45], v[182:185], v[208:211], v[42:45]
	v_mfma_f32_16x16x32_bf16 v[38:41], v[174:177], v[216:219], v[38:41]
	v_mfma_f32_16x16x32_bf16 v[34:37], v[182:185], v[216:219], v[34:37]
	s_barrier
	s_add_i32 s82, s85, s87
	s_mov_b32 m0, s82
	ds_read_b128 v[186:189], v162 offset:49152
	ds_read_b128 v[190:193], v162 offset:50176
	ds_read_b128 v[194:197], v162 offset:51200
	ds_read_b128 v[198:201], v162 offset:52224
	ds_read_b128 v[202:205], v162 offset:53248
	ds_read_b128 v[208:211], v162 offset:54272
	ds_read_b128 v[212:215], v162 offset:55296
	ds_read_b128 v[216:219], v162 offset:56320
	s_add_u32 s98, s8, s26
	s_addc_u32 s99, s9, s27
	global_load_lds_dwordx4 v132, s[98:99]
	s_add_i32 m0, s82, 0x2000
	s_add_u32 s8, s8, 0x40080
	v_lshl_add_u64 v[220:221], v[222:223], 0, s[26:27]
	s_addc_u32 s9, s9, 0
	s_add_i32 s82, vcc_lo, s87
	global_load_lds_dwordx4 v[220:221], off
	s_mov_b32 m0, s82
	s_nop 0
	global_load_lds_dwordx4 v132, s[8:9]
	s_add_i32 m0, s82, 0x2000
	s_nop 0
	global_load_lds_dwordx4 v136, s[8:9]
	v_lshl_add_u64 v[220:221], v[224:225], 0, s[26:27]
	s_mov_b32 m0, s92
	s_nop 0
	global_load_lds_dwordx4 v[220:221], off
	v_lshl_add_u64 v[220:221], v[226:227], 0, s[26:27]
	s_mov_b32 m0, s93
	s_nop 0
	global_load_lds_dwordx4 v[220:221], off
	s_waitcnt vmcnt(8)
	s_waitcnt lgkmcnt(0)
	s_barrier
	s_waitcnt lgkmcnt(0)
	v_mfma_f32_16x16x32_bf16 v[94:97], v[146:149], v[186:189], v[94:97]
	v_mfma_f32_16x16x32_bf16 v[90:93], v[154:157], v[186:189], v[90:93]
	v_mfma_f32_16x16x32_bf16 v[86:89], v[146:149], v[194:197], v[86:89]
	v_mfma_f32_16x16x32_bf16 v[82:85], v[154:157], v[194:197], v[82:85]
	v_mfma_f32_16x16x32_bf16 v[78:81], v[146:149], v[202:205], v[78:81]
	v_mfma_f32_16x16x32_bf16 v[74:77], v[154:157], v[202:205], v[74:77]
	v_mfma_f32_16x16x32_bf16 v[70:73], v[146:149], v[212:215], v[70:73]
	v_mfma_f32_16x16x32_bf16 v[66:69], v[154:157], v[212:215], v[66:69]
	v_mfma_f32_16x16x32_bf16 v[94:97], v[150:153], v[190:193], v[94:97]
	v_mfma_f32_16x16x32_bf16 v[90:93], v[166:169], v[190:193], v[90:93]
	v_mfma_f32_16x16x32_bf16 v[86:89], v[150:153], v[198:201], v[86:89]
	v_mfma_f32_16x16x32_bf16 v[82:85], v[166:169], v[198:201], v[82:85]
	v_mfma_f32_16x16x32_bf16 v[78:81], v[150:153], v[208:211], v[78:81]
	v_mfma_f32_16x16x32_bf16 v[74:77], v[166:169], v[208:211], v[74:77]
	v_mfma_f32_16x16x32_bf16 v[70:73], v[150:153], v[216:219], v[70:73]
	v_mfma_f32_16x16x32_bf16 v[66:69], v[166:169], v[216:219], v[66:69]
	v_mfma_f32_16x16x32_bf16 v[30:33], v[170:173], v[186:189], v[30:33]
	v_mfma_f32_16x16x32_bf16 v[26:29], v[178:181], v[186:189], v[26:29]
	v_mfma_f32_16x16x32_bf16 v[22:25], v[170:173], v[194:197], v[22:25]
	v_mfma_f32_16x16x32_bf16 v[18:21], v[178:181], v[194:197], v[18:21]
	v_mfma_f32_16x16x32_bf16 v[14:17], v[170:173], v[202:205], v[14:17]
	v_mfma_f32_16x16x32_bf16 v[10:13], v[178:181], v[202:205], v[10:13]
	v_mfma_f32_16x16x32_bf16 v[6:9], v[170:173], v[212:215], v[6:9]
	v_mfma_f32_16x16x32_bf16 v[2:5], v[178:181], v[212:215], v[2:5]
	v_mfma_f32_16x16x32_bf16 v[30:33], v[174:177], v[190:193], v[30:33]
	v_mfma_f32_16x16x32_bf16 v[26:29], v[182:185], v[190:193], v[26:29]
	v_mfma_f32_16x16x32_bf16 v[22:25], v[174:177], v[198:201], v[22:25]
	v_mfma_f32_16x16x32_bf16 v[18:21], v[182:185], v[198:201], v[18:21]
	v_mfma_f32_16x16x32_bf16 v[14:17], v[174:177], v[208:211], v[14:17]
	v_mfma_f32_16x16x32_bf16 v[10:13], v[182:185], v[208:211], v[10:13]
	v_mfma_f32_16x16x32_bf16 v[6:9], v[174:177], v[216:219], v[6:9]
	v_mfma_f32_16x16x32_bf16 v[2:5], v[182:185], v[216:219], v[2:5]
	s_add_i32 s84, s84, 2
	s_add_u32 s6, s6, 0x100
	s_addc_u32 s7, s7, 0
	s_add_u32 s73, s73, 0x100
	s_addc_u32 s75, s75, 0
	s_cmp_gt_u32 s84, 13
	s_barrier
	s_cbranch_scc0 .LBB0_110
	s_mov_b32 s100, 0xbfb8aa3b
	s_mov_b32 s98, 1.0
	s_and_b64 vcc, exec, s[68:69]
	s_cbranch_vccz .LBB0_113
	s_barrier

; #define PG8_STAGE(bufoff, gbase, voff) do { _Pragma("unroll") for (int _i = 0; _i < 2; ++_i) \
;         __builtin_amdgcn_global_load_lds((const unsigned*)((const char*)(gbase) + (voff)[_i]), (PG8_LAS unsigned*)(lds + (bufoff) + ldsw + _i * 8192), 16, 0, 0); } while (0)
; #define PG8_LDA(dst, b, h) do { _Pragma("unroll") for (int m = 0; m < 4; ++m) _Pragma("unroll") for (int k = 0; k < 2; ++k) dst[m][k] = *(const PG8_LAS bf16x8*)(lds + PG8_SA(b, h) + aoff + m * 2048 + k * 1024); } while (0)
; #define PG8_LDB(dst, b, h) do { _Pragma("unroll") for (int n = 0; n < 2; ++n) _Pragma("unroll") for (int k = 0; k < 2; ++k) dst[n][k] = *(const PG8_LAS bf16x8*)(lds + PG8_SB(b, h) + boff + n * 2048 + k * 1024); } while (0)
; #define PG8_WAIT_V(n) asm volatile("s_waitcnt vmcnt(" #n ")" ::: "memory")
; #define PG8_WAIT_L(n) asm volatile("s_waitcnt lgkmcnt(" #n ")" ::: "memory")
; #define PG8_BAR __builtin_amdgcn_s_barrier()
; #define PG8_SCHED __builtin_amdgcn_sched_barrier(0)
; template <class Epi, class Sched, bool ALIGN_EPI = false, bool SP2 = false>
; __device__ __forceinline__ void gemm_phase(PG8_LAS unsigned char* lds, const Gemm g, const Sched& S, const Epi& E) {
;     ...
;         const bool has_next = S.next(ui + 1, nxt);
;         const char* nA = has_next ? (const char*)g.A + (size_t)nxt.pm * tstep : cA; const char* nB = has_next ? (const char*)g.Bt + (size_t)nxt.pn * tstep : cB;
;         for (int t = 0; t < nt; t += 2) {
;             const bool last = (t == nt - 2);
;             const char* a1 = cA + (size_t)(t + 1) * kstep;
;             const char* a2 = last ? nA : cA + (size_t)(t + 2) * kstep; const char* b2 = last ? nB : cB + (size_t)(t + 2) * kstep;
;             const char* a3 = a2 + kstep; const char* b3 = b2 + kstep;
;             if (last && has_next) S.a_ready(nxt);
;             if constexpr (SP2) {
;             PG8_LDB(B0, 0, 0); PG8_LDB(B1, 0, 1); PG8_SCHED; PG8_LDA(At, 0, 0); PG8_STAGE(PG8_SA(1, 1), a1 + hstep, voffA);
;             PG8_WAIT_V(8); PG8_WAIT_L(0); PG8_BAR; PG8_MMA(0, 0, At, B0); PG8_MMA(0, 1, At, B1); PG8_BAR; PG8_SCHED;
;             PG8_LDA(At, 0, 1); PG8_STAGE(PG8_SB(0, 0), b2, voffB); PG8_STAGE(PG8_SB(0, 1), b2 + hstep, voffB); PG8_STAGE(PG8_SA(0, 0), a2, voffA);
;             PG8_WAIT_V(8); PG8_WAIT_L(0); PG8_BAR; PG8_MMA(1, 0, At, B0); PG8_MMA(1, 1, At, B1); PG8_BAR; PG8_SCHED;
.LBB0_645:
	s_ashr_i32 s21, s20, 31
	s_lshl_b64 s[22:23], s[20:21], 19
	s_add_u32 s22, s0, s22
	s_addc_u32 s23, s1, s23
	s_and_b64 s[24:25], s[6:7], exec
	s_cselect_b32 s21, s23, s45
	s_cselect_b32 s27, s22, s44
	s_ashr_i32 s19, s18, 31
	s_lshl_b64 s[24:25], s[18:19], 19
	s_add_u32 s24, s64, s24
	s_addc_u32 s25, s65, s25
	s_and_b64 s[48:49], s[6:7], exec
	s_cselect_b32 s19, s25, s47
	s_cselect_b32 s33, s24, s46
	s_add_u32 s44, s44, 0x40080
	s_addc_u32 s45, s45, 0
	s_add_u32 s71, s46, 0x100
	s_addc_u32 s72, s47, 0
	s_mov_b32 s73, -2
	s_waitcnt lgkmcnt(0)
	ds_read_b128 v[148:151], v152
	ds_read_b128 v[156:159], v152 offset:1024
	ds_read_b128 v[160:163], v152 offset:2048
	ds_read_b128 v[164:167], v152 offset:3072
	ds_read_b128 v[168:171], v153
	ds_read_b128 v[172:175], v153 offset:1024
	ds_read_b128 v[176:179], v153 offset:2048
	ds_read_b128 v[180:183], v153 offset:3072
	s_add_u32 s46, s44, 0xfffc0080
	s_addc_u32 s47, s45, -1
	s_cmp_eq_u32 s73, 12
	s_cselect_b32 s49, s21, s47
	s_cselect_b32 s48, s27, s46
	s_cselect_b32 s47, s19, s72
	s_cselect_b32 s46, s33, s71
	v_lshl_add_u64 v[204:205], s[44:45], 0, v[140:141]
	s_add_i32 m0, s31, 0xc000
	ds_read_b128 v[184:187], v154
	ds_read_b128 v[188:191], v154 offset:1024
	ds_read_b128 v[192:195], v154 offset:2048
	ds_read_b128 v[196:199], v154 offset:3072
	ds_read_b128 v[200:203], v154 offset:4096
	ds_read_b128 v[208:211], v154 offset:5120
	ds_read_b128 v[212:215], v154 offset:6144
	ds_read_b128 v[216:219], v154 offset:7168
	global_load_lds_dwordx4 v[204:205], off
	v_lshl_add_u64 v[204:205], s[44:45], 0, v[142:143]
	s_add_i32 m0, s31, 0xe000
	s_nop 0
	global_load_lds_dwordx4 v[204:205], off
	s_waitcnt vmcnt(8)
	s_waitcnt lgkmcnt(0)
	s_barrier
	s_waitcnt lgkmcnt(0)
	v_mfma_f32_16x16x32_bf16 v[126:129], v[148:151], v[184:187], 0
	v_mfma_f32_16x16x32_bf16 v[122:125], v[160:163], v[184:187], 0
	v_mfma_f32_16x16x32_bf16 v[110:113], v[148:151], v[192:195], 0
	v_mfma_f32_16x16x32_bf16 v[106:109], v[160:163], v[192:195], 0
	v_mfma_f32_16x16x32_bf16 v[94:97], v[148:151], v[200:203], 0
	v_mfma_f32_16x16x32_bf16 v[90:93], v[160:163], v[200:203], 0
	v_mfma_f32_16x16x32_bf16 v[78:81], v[148:151], v[212:215], 0
	v_mfma_f32_16x16x32_bf16 v[74:77], v[160:163], v[212:215], 0
	v_mfma_f32_16x16x32_bf16 v[126:129], v[156:159], v[188:191], v[126:129]
	v_mfma_f32_16x16x32_bf16 v[122:125], v[164:167], v[188:191], v[122:125]
	v_mfma_f32_16x16x32_bf16 v[110:113], v[156:159], v[196:199], v[110:113]
	v_mfma_f32_16x16x32_bf16 v[106:109], v[164:167], v[196:199], v[106:109]
	v_mfma_f32_16x16x32_bf16 v[94:97], v[156:159], v[208:211], v[94:97]
	v_mfma_f32_16x16x32_bf16 v[90:93], v[164:167], v[208:211], v[90:93]
	v_mfma_f32_16x16x32_bf16 v[78:81], v[156:159], v[216:219], v[78:81]
	v_mfma_f32_16x16x32_bf16 v[74:77], v[164:167], v[216:219], v[74:77]
	v_mfma_f32_16x16x32_bf16 v[118:121], v[168:171], v[184:187], 0
	v_mfma_f32_16x16x32_bf16 v[114:117], v[176:179], v[184:187], 0
	v_mfma_f32_16x16x32_bf16 v[102:105], v[168:171], v[192:195], 0
	v_mfma_f32_16x16x32_bf16 v[98:101], v[176:179], v[192:195], 0
	v_mfma_f32_16x16x32_bf16 v[86:89], v[168:171], v[200:203], 0
	v_mfma_f32_16x16x32_bf16 v[82:85], v[176:179], v[200:203], 0
	v_mfma_f32_16x16x32_bf16 v[70:73], v[168:171], v[212:215], 0
	v_mfma_f32_16x16x32_bf16 v[66:69], v[176:179], v[212:215], 0
	v_mfma_f32_16x16x32_bf16 v[118:121], v[172:175], v[188:191], v[118:121]
	v_mfma_f32_16x16x32_bf16 v[114:117], v[180:183], v[188:191], v[114:117]
	v_mfma_f32_16x16x32_bf16 v[102:105], v[172:175], v[196:199], v[102:105]
	v_mfma_f32_16x16x32_bf16 v[98:101], v[180:183], v[196:199], v[98:101]
	v_mfma_f32_16x16x32_bf16 v[86:89], v[172:175], v[208:211], v[86:89]
	v_mfma_f32_16x16x32_bf16 v[82:85], v[180:183], v[208:211], v[82:85]
	v_mfma_f32_16x16x32_bf16 v[70:73], v[172:175], v[216:219], v[70:73]
	v_mfma_f32_16x16x32_bf16 v[66:69], v[180:183], v[216:219], v[66:69]
	s_barrier
	s_add_i32 s74, s68, s30
	s_mov_b32 m0, s74
	ds_read_b128 v[184:187], v154 offset:16384
	ds_read_b128 v[188:191], v154 offset:17408
	ds_read_b128 v[192:195], v154 offset:18432
	ds_read_b128 v[196:199], v154 offset:19456
	ds_read_b128 v[200:203], v154 offset:20480
	ds_read_b128 v[208:211], v154 offset:21504
	ds_read_b128 v[212:215], v154 offset:22528
	ds_read_b128 v[216:219], v154 offset:23552
	global_load_lds_dwordx4 v132, s[46:47]
	s_add_i32 m0, s74, 0x2000
	s_add_u32 s74, s46, 0x40000
	v_lshl_add_u64 v[220:221], s[46:47], 0, v[136:137]
	s_addc_u32 s75, s47, 0
	s_add_i32 s76, s69, s30
	global_load_lds_dwordx4 v136, s[46:47]
	s_mov_b32 m0, s76
	v_lshl_add_u64 v[224:225], s[48:49], 0, v[134:135]
	global_load_lds_dwordx4 v132, s[74:75]
	s_add_i32 m0, s76, 0x2000
	s_nop 0
	global_load_lds_dwordx4 v136, s[74:75]
	v_lshl_add_u64 v[222:223], s[48:49], 0, v[130:131]
	s_mov_b32 m0, s31
	s_nop 0
	global_load_lds_dwordx4 v130, s[48:49]
	s_mov_b32 m0, s50
	s_nop 0
	global_load_lds_dwordx4 v134, s[48:49]
	s_waitcnt vmcnt(8)
	s_waitcnt lgkmcnt(0)
	s_barrier
; #define PG8_STAGE(bufoff, gbase, voff) do { _Pragma("unroll") for (int _i = 0; _i < 2; ++_i) \
;         __builtin_amdgcn_global_load_lds((const unsigned*)((const char*)(gbase) + (voff)[_i]), (PG8_LAS unsigned*)(lds + (bufoff) + ldsw + _i * 8192), 16, 0, 0); } while (0)
; #define PG8_LDA(dst, b, h) do { _Pragma("unroll") for (int m = 0; m < 4; ++m) _Pragma("unroll") for (int k = 0; k < 2; ++k) dst[m][k] = *(const PG8_LAS bf16x8*)(lds + PG8_SA(b, h) + aoff + m * 2048 + k * 1024); } while (0)
; #define PG8_LDB(dst, b, h) do { _Pragma("unroll") for (int n = 0; n < 2; ++n) _Pragma("unroll") for (int k = 0; k < 2; ++k) dst[n][k] = *(const PG8_LAS bf16x8*)(lds + PG8_SB(b, h) + boff + n * 2048 + k * 1024); } while (0)
; #define PG8_MMA(ai, bj, At, Bt) do { __builtin_amdgcn_s_setprio(1); _Pragma("unroll") for (int m = 0; m < 4; ++m) _Pragma("unroll") for (int n = 0; n < 2; ++n) _Pragma("unroll") for (int k = 0; k < 2; ++k) \
;         acc[ai][bj][m][n] = __builtin_amdgcn_mfma_f32_16x16x32_bf16(Bt[n][k], At[m][k], acc[ai][bj][m][n], 0, 0, 0); __builtin_amdgcn_s_setprio(0); } while (0)
; #define PG8_WAIT_V(n) asm volatile("s_waitcnt vmcnt(" #n ")" ::: "memory")
; #define PG8_WAIT_L(n) asm volatile("s_waitcnt lgkmcnt(" #n ")" ::: "memory")
; #define PG8_BAR __builtin_amdgcn_s_barrier()
; #define PG8_SCHED __builtin_amdgcn_sched_barrier(0)
; template <class Epi, class Sched, bool ALIGN_EPI = false, bool SP2 = false>
; __device__ __forceinline__ void gemm_phase(PG8_LAS unsigned char* lds, const Gemm g, const Sched& S, const Epi& E) {
;     ...
;             PG8_WAIT_V(8); PG8_WAIT_L(0); PG8_BAR; PG8_MMA(0, 0, At, B0); PG8_MMA(0, 1, At, B1); PG8_BAR; PG8_SCHED;
;             PG8_LDA(At, 0, 1); PG8_STAGE(PG8_SB(0, 0), b2, voffB); PG8_STAGE(PG8_SB(0, 1), b2 + hstep, voffB); PG8_STAGE(PG8_SA(0, 0), a2, voffA);
;             PG8_WAIT_V(8); PG8_WAIT_L(0); PG8_BAR; PG8_MMA(1, 0, At, B0); PG8_MMA(1, 1, At, B1); PG8_BAR; PG8_SCHED;
;             PG8_LDB(B0, 1, 0); PG8_LDB(B1, 1, 1); PG8_SCHED; PG8_LDA(At, 1, 0); PG8_STAGE(PG8_SA(0, 1), a2 + hstep, voffA);
;             PG8_WAIT_V(8); PG8_WAIT_L(0); PG8_BAR; PG8_MMA(0, 0, At, B0); PG8_MMA(0, 1, At, B1); PG8_BAR; PG8_SCHED;
	s_waitcnt lgkmcnt(0)
	v_mfma_f32_16x16x32_bf16 v[62:65], v[148:151], v[184:187], 0
	v_mfma_f32_16x16x32_bf16 v[58:61], v[160:163], v[184:187], 0
	v_mfma_f32_16x16x32_bf16 v[46:49], v[148:151], v[192:195], 0
	v_mfma_f32_16x16x32_bf16 v[42:45], v[160:163], v[192:195], 0
	v_mfma_f32_16x16x32_bf16 v[30:33], v[148:151], v[200:203], 0
	v_mfma_f32_16x16x32_bf16 v[26:29], v[160:163], v[200:203], 0
	v_mfma_f32_16x16x32_bf16 v[14:17], v[148:151], v[212:215], 0
	v_mfma_f32_16x16x32_bf16 v[10:13], v[160:163], v[212:215], 0
	v_mfma_f32_16x16x32_bf16 v[62:65], v[156:159], v[188:191], v[62:65]
	v_mfma_f32_16x16x32_bf16 v[58:61], v[164:167], v[188:191], v[58:61]
	v_mfma_f32_16x16x32_bf16 v[46:49], v[156:159], v[196:199], v[46:49]
	v_mfma_f32_16x16x32_bf16 v[42:45], v[164:167], v[196:199], v[42:45]
	v_mfma_f32_16x16x32_bf16 v[30:33], v[156:159], v[208:211], v[30:33]
	v_mfma_f32_16x16x32_bf16 v[26:29], v[164:167], v[208:211], v[26:29]
	v_mfma_f32_16x16x32_bf16 v[14:17], v[156:159], v[216:219], v[14:17]
	v_mfma_f32_16x16x32_bf16 v[10:13], v[164:167], v[216:219], v[10:13]
	v_mfma_f32_16x16x32_bf16 v[54:57], v[168:171], v[184:187], 0
	v_mfma_f32_16x16x32_bf16 v[50:53], v[176:179], v[184:187], 0
	v_mfma_f32_16x16x32_bf16 v[38:41], v[168:171], v[192:195], 0
	v_mfma_f32_16x16x32_bf16 v[34:37], v[176:179], v[192:195], 0
	v_mfma_f32_16x16x32_bf16 v[22:25], v[168:171], v[200:203], 0
	v_mfma_f32_16x16x32_bf16 v[18:21], v[176:179], v[200:203], 0
	v_mfma_f32_16x16x32_bf16 v[6:9], v[168:171], v[212:215], 0
	v_mfma_f32_16x16x32_bf16 v[2:5], v[176:179], v[212:215], 0
	v_mfma_f32_16x16x32_bf16 v[54:57], v[172:175], v[188:191], v[54:57]
	v_mfma_f32_16x16x32_bf16 v[50:53], v[180:183], v[188:191], v[50:53]
	v_mfma_f32_16x16x32_bf16 v[38:41], v[172:175], v[196:199], v[38:41]
	v_mfma_f32_16x16x32_bf16 v[34:37], v[180:183], v[196:199], v[34:37]
	v_mfma_f32_16x16x32_bf16 v[22:25], v[172:175], v[208:211], v[22:25]
	v_mfma_f32_16x16x32_bf16 v[18:21], v[180:183], v[208:211], v[18:21]
	v_mfma_f32_16x16x32_bf16 v[6:9], v[172:175], v[216:219], v[6:9]
	v_mfma_f32_16x16x32_bf16 v[2:5], v[180:183], v[216:219], v[2:5]
	s_barrier
	s_add_i32 s74, 0, 0x18000
	s_add_i32 s75, 0, 0x1c000
	v_add_u32_e32 v164, s74, v139
	v_add_u32_e32 v180, s75, v139
	ds_read_b128 v[148:151], v164
	ds_read_b128 v[156:159], v164 offset:1024
	ds_read_b128 v[160:163], v164 offset:2048
	ds_read_b128 v[164:167], v164 offset:3072
	ds_read_b128 v[168:171], v180
	ds_read_b128 v[172:175], v180 offset:1024
	ds_read_b128 v[176:179], v180 offset:2048
	ds_read_b128 v[180:183], v180 offset:3072
	s_add_u32 s48, s48, 0x40000
	s_addc_u32 s49, s49, 0
	s_mov_b32 m0, s51
	ds_read_b128 v[184:187], v154 offset:32768
	ds_read_b128 v[188:191], v154 offset:33792
	ds_read_b128 v[192:195], v154 offset:34816
	ds_read_b128 v[196:199], v154 offset:35840
	ds_read_b128 v[200:203], v154 offset:36864
	ds_read_b128 v[208:211], v154 offset:37888
	ds_read_b128 v[212:215], v154 offset:38912
	ds_read_b128 v[216:219], v154 offset:39936
	global_load_lds_dwordx4 v130, s[48:49]
	s_mov_b32 m0, s60
	s_nop 0
	global_load_lds_dwordx4 v134, s[48:49]
	s_waitcnt vmcnt(8)
	s_waitcnt lgkmcnt(0)
	s_barrier
	s_waitcnt lgkmcnt(0)
	v_mfma_f32_16x16x32_bf16 v[126:129], v[148:151], v[184:187], v[126:129]
	v_mfma_f32_16x16x32_bf16 v[122:125], v[160:163], v[184:187], v[122:125]
	v_mfma_f32_16x16x32_bf16 v[110:113], v[148:151], v[192:195], v[110:113]
	v_mfma_f32_16x16x32_bf16 v[106:109], v[160:163], v[192:195], v[106:109]
	v_mfma_f32_16x16x32_bf16 v[94:97], v[148:151], v[200:203], v[94:97]
	v_mfma_f32_16x16x32_bf16 v[90:93], v[160:163], v[200:203], v[90:93]
	v_mfma_f32_16x16x32_bf16 v[78:81], v[148:151], v[212:215], v[78:81]
	v_mfma_f32_16x16x32_bf16 v[74:77], v[160:163], v[212:215], v[74:77]
	v_mfma_f32_16x16x32_bf16 v[126:129], v[156:159], v[188:191], v[126:129]
	v_mfma_f32_16x16x32_bf16 v[122:125], v[164:167], v[188:191], v[122:125]
	v_mfma_f32_16x16x32_bf16 v[110:113], v[156:159], v[196:199], v[110:113]
	v_mfma_f32_16x16x32_bf16 v[106:109], v[164:167], v[196:199], v[106:109]
	v_mfma_f32_16x16x32_bf16 v[94:97], v[156:159], v[208:211], v[94:97]
	v_mfma_f32_16x16x32_bf16 v[90:93], v[164:167], v[208:211], v[90:93]
	v_mfma_f32_16x16x32_bf16 v[78:81], v[156:159], v[216:219], v[78:81]
	v_mfma_f32_16x16x32_bf16 v[74:77], v[164:167], v[216:219], v[74:77]
	v_mfma_f32_16x16x32_bf16 v[118:121], v[168:171], v[184:187], v[118:121]
	v_mfma_f32_16x16x32_bf16 v[114:117], v[176:179], v[184:187], v[114:117]
	v_mfma_f32_16x16x32_bf16 v[102:105], v[168:171], v[192:195], v[102:105]
	v_mfma_f32_16x16x32_bf16 v[98:101], v[176:179], v[192:195], v[98:101]
	v_mfma_f32_16x16x32_bf16 v[86:89], v[168:171], v[200:203], v[86:89]
	v_mfma_f32_16x16x32_bf16 v[82:85], v[176:179], v[200:203], v[82:85]
	v_mfma_f32_16x16x32_bf16 v[70:73], v[168:171], v[212:215], v[70:73]
	v_mfma_f32_16x16x32_bf16 v[66:69], v[176:179], v[212:215], v[66:69]
	v_mfma_f32_16x16x32_bf16 v[118:121], v[172:175], v[188:191], v[118:121]
	v_mfma_f32_16x16x32_bf16 v[114:117], v[180:183], v[188:191], v[114:117]
	v_mfma_f32_16x16x32_bf16 v[102:105], v[172:175], v[196:199], v[102:105]
	v_mfma_f32_16x16x32_bf16 v[98:101], v[180:183], v[196:199], v[98:101]
	v_mfma_f32_16x16x32_bf16 v[86:89], v[172:175], v[208:211], v[86:89]
	v_mfma_f32_16x16x32_bf16 v[82:85], v[180:183], v[208:211], v[82:85]
	v_mfma_f32_16x16x32_bf16 v[70:73], v[172:175], v[216:219], v[70:73]
	v_mfma_f32_16x16x32_bf16 v[66:69], v[180:183], v[216:219], v[66:69]
	s_barrier
; #define PG8_STAGE(bufoff, gbase, voff) do { _Pragma("unroll") for (int _i = 0; _i < 2; ++_i) \
;         __builtin_amdgcn_global_load_lds((const unsigned*)((const char*)(gbase) + (voff)[_i]), (PG8_LAS unsigned*)(lds + (bufoff) + ldsw + _i * 8192), 16, 0, 0); } while (0)
; #define PG8_LDA(dst, b, h) do { _Pragma("unroll") for (int m = 0; m < 4; ++m) _Pragma("unroll") for (int k = 0; k < 2; ++k) dst[m][k] = *(const PG8_LAS bf16x8*)(lds + PG8_SA(b, h) + aoff + m * 2048 + k * 1024); } while (0)
; #define PG8_LDB(dst, b, h) do { _Pragma("unroll") for (int n = 0; n < 2; ++n) _Pragma("unroll") for (int k = 0; k < 2; ++k) dst[n][k] = *(const PG8_LAS bf16x8*)(lds + PG8_SB(b, h) + boff + n * 2048 + k * 1024); } while (0)
; #define PG8_MMA(ai, bj, At, Bt) do { __builtin_amdgcn_s_setprio(1); _Pragma("unroll") for (int m = 0; m < 4; ++m) _Pragma("unroll") for (int n = 0; n < 2; ++n) _Pragma("unroll") for (int k = 0; k < 2; ++k) \
;         acc[ai][bj][m][n] = __builtin_amdgcn_mfma_f32_16x16x32_bf16(Bt[n][k], At[m][k], acc[ai][bj][m][n], 0, 0, 0); __builtin_amdgcn_s_setprio(0); } while (0)
; #define PG8_WAIT_V(n) asm volatile("s_waitcnt vmcnt(" #n ")" ::: "memory")
; #define PG8_WAIT_L(n) asm volatile("s_waitcnt lgkmcnt(" #n ")" ::: "memory")
; #define PG8_BAR __builtin_amdgcn_s_barrier()
; #define PG8_SCHED __builtin_amdgcn_sched_barrier(0)
; template <class Epi, class Sched, bool ALIGN_EPI = false, bool SP2 = false>
; __device__ __forceinline__ void gemm_phase(PG8_LAS unsigned char* lds, const Gemm g, const Sched& S, const Epi& E) {
;     ...
;             PG8_LDB(B0, 0, 0); PG8_LDB(B1, 0, 1); PG8_SCHED; PG8_LDA(At, 0, 0); PG8_STAGE(PG8_SA(1, 1), a1 + hstep, voffA);
;     ...
;             PG8_LDB(B0, 1, 0); PG8_LDB(B1, 1, 1); PG8_SCHED; PG8_LDA(At, 1, 0); PG8_STAGE(PG8_SA(0, 1), a2 + hstep, voffA);
;             PG8_WAIT_V(8); PG8_WAIT_L(0); PG8_BAR; PG8_MMA(0, 0, At, B0); PG8_MMA(0, 1, At, B1); PG8_BAR; PG8_SCHED;
;             PG8_LDA(At, 1, 1); PG8_STAGE(PG8_SB(1, 0), b3, voffB); PG8_STAGE(PG8_SB(1, 1), b3 + hstep, voffB); PG8_STAGE(PG8_SA(1, 0), a3, voffA);
;             PG8_WAIT_V(8); PG8_WAIT_L(0); PG8_BAR; PG8_MMA(1, 0, At, B0); PG8_MMA(1, 1, At, B1); PG8_BAR; PG8_SCHED;
	s_add_i32 s48, s74, s30
	s_mov_b32 m0, s48
	ds_read_b128 v[184:187], v154 offset:49152
	ds_read_b128 v[188:191], v154 offset:50176
	ds_read_b128 v[192:195], v154 offset:51200
	ds_read_b128 v[196:199], v154 offset:52224
	ds_read_b128 v[200:203], v154 offset:53248
	ds_read_b128 v[208:211], v154 offset:54272
	ds_read_b128 v[212:215], v154 offset:55296
	ds_read_b128 v[216:219], v154 offset:56320
	s_add_u32 s98, s46, s14
	s_addc_u32 s99, s47, s15
	global_load_lds_dwordx4 v132, s[98:99]
	s_add_i32 m0, s48, 0x2000
	s_add_u32 s46, s46, 0x40080
	v_lshl_add_u64 v[204:205], v[220:221], 0, s[14:15]
	s_addc_u32 s47, s47, 0
	s_add_i32 s48, s75, s30
	global_load_lds_dwordx4 v[204:205], off
	s_mov_b32 m0, s48
	s_nop 0
	global_load_lds_dwordx4 v132, s[46:47]
	s_add_i32 m0, s48, 0x2000
	s_nop 0
	global_load_lds_dwordx4 v136, s[46:47]
	v_lshl_add_u64 v[204:205], v[222:223], 0, s[14:15]
	s_mov_b32 m0, s62
	s_nop 0
	global_load_lds_dwordx4 v[204:205], off
	v_lshl_add_u64 v[204:205], v[224:225], 0, s[14:15]
	s_mov_b32 m0, s63
	s_nop 0
	global_load_lds_dwordx4 v[204:205], off
	s_waitcnt vmcnt(8)
	s_waitcnt lgkmcnt(0)
	s_barrier
	s_waitcnt lgkmcnt(0)
	v_mfma_f32_16x16x32_bf16 v[62:65], v[148:151], v[184:187], v[62:65]
	v_mfma_f32_16x16x32_bf16 v[58:61], v[160:163], v[184:187], v[58:61]
	v_mfma_f32_16x16x32_bf16 v[46:49], v[148:151], v[192:195], v[46:49]
	v_mfma_f32_16x16x32_bf16 v[42:45], v[160:163], v[192:195], v[42:45]
	v_mfma_f32_16x16x32_bf16 v[30:33], v[148:151], v[200:203], v[30:33]
	v_mfma_f32_16x16x32_bf16 v[26:29], v[160:163], v[200:203], v[26:29]
	v_mfma_f32_16x16x32_bf16 v[14:17], v[148:151], v[212:215], v[14:17]
	v_mfma_f32_16x16x32_bf16 v[10:13], v[160:163], v[212:215], v[10:13]
	v_mfma_f32_16x16x32_bf16 v[62:65], v[156:159], v[188:191], v[62:65]
	v_mfma_f32_16x16x32_bf16 v[58:61], v[164:167], v[188:191], v[58:61]
	v_mfma_f32_16x16x32_bf16 v[46:49], v[156:159], v[196:199], v[46:49]
	v_mfma_f32_16x16x32_bf16 v[42:45], v[164:167], v[196:199], v[42:45]
	v_mfma_f32_16x16x32_bf16 v[30:33], v[156:159], v[208:211], v[30:33]
	v_mfma_f32_16x16x32_bf16 v[26:29], v[164:167], v[208:211], v[26:29]
	v_mfma_f32_16x16x32_bf16 v[14:17], v[156:159], v[216:219], v[14:17]
	v_mfma_f32_16x16x32_bf16 v[10:13], v[164:167], v[216:219], v[10:13]
	v_mfma_f32_16x16x32_bf16 v[54:57], v[168:171], v[184:187], v[54:57]
	v_mfma_f32_16x16x32_bf16 v[50:53], v[176:179], v[184:187], v[50:53]
	v_mfma_f32_16x16x32_bf16 v[38:41], v[168:171], v[192:195], v[38:41]
	v_mfma_f32_16x16x32_bf16 v[34:37], v[176:179], v[192:195], v[34:37]
	v_mfma_f32_16x16x32_bf16 v[22:25], v[168:171], v[200:203], v[22:25]
	v_mfma_f32_16x16x32_bf16 v[18:21], v[176:179], v[200:203], v[18:21]
	v_mfma_f32_16x16x32_bf16 v[6:9], v[168:171], v[212:215], v[6:9]
	v_mfma_f32_16x16x32_bf16 v[2:5], v[176:179], v[212:215], v[2:5]
	v_mfma_f32_16x16x32_bf16 v[54:57], v[172:175], v[188:191], v[54:57]
	v_mfma_f32_16x16x32_bf16 v[50:53], v[180:183], v[188:191], v[50:53]
	v_mfma_f32_16x16x32_bf16 v[38:41], v[172:175], v[196:199], v[38:41]
	v_mfma_f32_16x16x32_bf16 v[34:37], v[180:183], v[196:199], v[34:37]
	v_mfma_f32_16x16x32_bf16 v[22:25], v[172:175], v[208:211], v[22:25]
	v_mfma_f32_16x16x32_bf16 v[18:21], v[180:183], v[208:211], v[18:21]
	v_mfma_f32_16x16x32_bf16 v[6:9], v[172:175], v[216:219], v[6:9]
	v_mfma_f32_16x16x32_bf16 v[2:5], v[180:183], v[216:219], v[2:5]
	s_add_i32 s73, s73, 2
	s_add_u32 s44, s44, 0x100
	s_addc_u32 s45, s45, 0
	s_add_u32 s71, s71, 0x100
	s_addc_u32 s72, s72, 0
	s_cmp_gt_u32 s73, 13
	s_barrier
.LBB0_646:
	ds_read_b128 v[148:151], v152
	ds_read_b128 v[156:159], v152 offset:1024
	ds_read_b128 v[160:163], v152 offset:2048
	ds_read_b128 v[164:167], v152 offset:3072
	ds_read_b128 v[168:171], v153
	ds_read_b128 v[172:175], v153 offset:1024
	ds_read_b128 v[176:179], v153 offset:2048
	ds_read_b128 v[180:183], v153 offset:3072
	s_add_u32 s46, s44, 0xfffc0080
	s_addc_u32 s47, s45, -1
	s_cmp_eq_u32 s73, 12
	s_cselect_b32 s49, s21, s47
	s_cselect_b32 s48, s27, s46
	s_cselect_b32 s47, s19, s72
	s_cselect_b32 s46, s33, s71
	v_lshl_add_u64 v[204:205], s[44:45], 0, v[140:141]
	s_add_i32 m0, s31, 0xc000
	ds_read_b128 v[184:187], v154
	ds_read_b128 v[188:191], v154 offset:1024
	ds_read_b128 v[192:195], v154 offset:2048
	ds_read_b128 v[196:199], v154 offset:3072
	ds_read_b128 v[200:203], v154 offset:4096
	ds_read_b128 v[208:211], v154 offset:5120
	ds_read_b128 v[212:215], v154 offset:6144
	ds_read_b128 v[216:219], v154 offset:7168
	global_load_lds_dwordx4 v[204:205], off
	v_lshl_add_u64 v[204:205], s[44:45], 0, v[142:143]
	s_add_i32 m0, s31, 0xe000
	s_nop 0
	global_load_lds_dwordx4 v[204:205], off
	s_waitcnt vmcnt(8)
	s_waitcnt lgkmcnt(0)
	s_barrier
; #define PG8_STAGE(bufoff, gbase, voff) do { _Pragma("unroll") for (int _i = 0; _i < 2; ++_i) \
;         __builtin_amdgcn_global_load_lds((const unsigned*)((const char*)(gbase) + (voff)[_i]), (PG8_LAS unsigned*)(lds + (bufoff) + ldsw + _i * 8192), 16, 0, 0); } while (0)
; #define PG8_LDA(dst, b, h) do { _Pragma("unroll") for (int m = 0; m < 4; ++m) _Pragma("unroll") for (int k = 0; k < 2; ++k) dst[m][k] = *(const PG8_LAS bf16x8*)(lds + PG8_SA(b, h) + aoff + m * 2048 + k * 1024); } while (0)
; #define PG8_MMA(ai, bj, At, Bt) do { __builtin_amdgcn_s_setprio(1); _Pragma("unroll") for (int m = 0; m < 4; ++m) _Pragma("unroll") for (int n = 0; n < 2; ++n) _Pragma("unroll") for (int k = 0; k < 2; ++k) \
;         acc[ai][bj][m][n] = __builtin_amdgcn_mfma_f32_16x16x32_bf16(Bt[n][k], At[m][k], acc[ai][bj][m][n], 0, 0, 0); __builtin_amdgcn_s_setprio(0); } while (0)
; #define PG8_WAIT_V(n) asm volatile("s_waitcnt vmcnt(" #n ")" ::: "memory")
; #define PG8_WAIT_L(n) asm volatile("s_waitcnt lgkmcnt(" #n ")" ::: "memory")
; #define PG8_BAR __builtin_amdgcn_s_barrier()
; #define PG8_SCHED __builtin_amdgcn_sched_barrier(0)
; template <class Epi, class Sched, bool ALIGN_EPI = false, bool SP2 = false>
; __device__ __forceinline__ void gemm_phase(PG8_LAS unsigned char* lds, const Gemm g, const Sched& S, const Epi& E) {
;     ...
;             PG8_WAIT_V(8); PG8_WAIT_L(0); PG8_BAR; PG8_MMA(0, 0, At, B0); PG8_MMA(0, 1, At, B1); PG8_BAR; PG8_SCHED;
;             PG8_LDA(At, 0, 1); PG8_STAGE(PG8_SB(0, 0), b2, voffB); PG8_STAGE(PG8_SB(0, 1), b2 + hstep, voffB); PG8_STAGE(PG8_SA(0, 0), a2, voffA);
;             PG8_WAIT_V(8); PG8_WAIT_L(0); PG8_BAR; PG8_MMA(1, 0, At, B0); PG8_MMA(1, 1, At, B1); PG8_BAR; PG8_SCHED;
	s_waitcnt lgkmcnt(0)
	v_mfma_f32_16x16x32_bf16 v[126:129], v[148:151], v[184:187], v[126:129]
	v_mfma_f32_16x16x32_bf16 v[122:125], v[160:163], v[184:187], v[122:125]
	v_mfma_f32_16x16x32_bf16 v[110:113], v[148:151], v[192:195], v[110:113]
	v_mfma_f32_16x16x32_bf16 v[106:109], v[160:163], v[192:195], v[106:109]
	v_mfma_f32_16x16x32_bf16 v[94:97], v[148:151], v[200:203], v[94:97]
	v_mfma_f32_16x16x32_bf16 v[90:93], v[160:163], v[200:203], v[90:93]
	v_mfma_f32_16x16x32_bf16 v[78:81], v[148:151], v[212:215], v[78:81]
	v_mfma_f32_16x16x32_bf16 v[74:77], v[160:163], v[212:215], v[74:77]
	v_mfma_f32_16x16x32_bf16 v[126:129], v[156:159], v[188:191], v[126:129]
	v_mfma_f32_16x16x32_bf16 v[122:125], v[164:167], v[188:191], v[122:125]
	v_mfma_f32_16x16x32_bf16 v[110:113], v[156:159], v[196:199], v[110:113]
	v_mfma_f32_16x16x32_bf16 v[106:109], v[164:167], v[196:199], v[106:109]
	v_mfma_f32_16x16x32_bf16 v[94:97], v[156:159], v[208:211], v[94:97]
	v_mfma_f32_16x16x32_bf16 v[90:93], v[164:167], v[208:211], v[90:93]
	v_mfma_f32_16x16x32_bf16 v[78:81], v[156:159], v[216:219], v[78:81]
	v_mfma_f32_16x16x32_bf16 v[74:77], v[164:167], v[216:219], v[74:77]
	v_mfma_f32_16x16x32_bf16 v[118:121], v[168:171], v[184:187], v[118:121]
	v_mfma_f32_16x16x32_bf16 v[114:117], v[176:179], v[184:187], v[114:117]
	v_mfma_f32_16x16x32_bf16 v[102:105], v[168:171], v[192:195], v[102:105]
	v_mfma_f32_16x16x32_bf16 v[98:101], v[176:179], v[192:195], v[98:101]
	v_mfma_f32_16x16x32_bf16 v[86:89], v[168:171], v[200:203], v[86:89]
	v_mfma_f32_16x16x32_bf16 v[82:85], v[176:179], v[200:203], v[82:85]
	v_mfma_f32_16x16x32_bf16 v[70:73], v[168:171], v[212:215], v[70:73]
	v_mfma_f32_16x16x32_bf16 v[66:69], v[176:179], v[212:215], v[66:69]
	v_mfma_f32_16x16x32_bf16 v[118:121], v[172:175], v[188:191], v[118:121]
	v_mfma_f32_16x16x32_bf16 v[114:117], v[180:183], v[188:191], v[114:117]
	v_mfma_f32_16x16x32_bf16 v[102:105], v[172:175], v[196:199], v[102:105]
	v_mfma_f32_16x16x32_bf16 v[98:101], v[180:183], v[196:199], v[98:101]
	v_mfma_f32_16x16x32_bf16 v[86:89], v[172:175], v[208:211], v[86:89]
	v_mfma_f32_16x16x32_bf16 v[82:85], v[180:183], v[208:211], v[82:85]
	v_mfma_f32_16x16x32_bf16 v[70:73], v[172:175], v[216:219], v[70:73]
	v_mfma_f32_16x16x32_bf16 v[66:69], v[180:183], v[216:219], v[66:69]
	s_barrier
	s_add_i32 s74, s68, s30
	s_mov_b32 m0, s74
	ds_read_b128 v[184:187], v154 offset:16384
	ds_read_b128 v[188:191], v154 offset:17408
	ds_read_b128 v[192:195], v154 offset:18432
	ds_read_b128 v[196:199], v154 offset:19456
	ds_read_b128 v[200:203], v154 offset:20480
	ds_read_b128 v[208:211], v154 offset:21504
	ds_read_b128 v[212:215], v154 offset:22528
	ds_read_b128 v[216:219], v154 offset:23552
	global_load_lds_dwordx4 v132, s[46:47]
	s_add_i32 m0, s74, 0x2000
	s_add_u32 s74, s46, 0x40000
	v_lshl_add_u64 v[220:221], s[46:47], 0, v[136:137]
	s_addc_u32 s75, s47, 0
	s_add_i32 s76, s69, s30
	global_load_lds_dwordx4 v136, s[46:47]
	s_mov_b32 m0, s76
	v_lshl_add_u64 v[224:225], s[48:49], 0, v[134:135]
	global_load_lds_dwordx4 v132, s[74:75]
	s_add_i32 m0, s76, 0x2000
	s_nop 0
	global_load_lds_dwordx4 v136, s[74:75]
	v_lshl_add_u64 v[222:223], s[48:49], 0, v[130:131]
	s_mov_b32 m0, s31
	s_nop 0
	global_load_lds_dwordx4 v130, s[48:49]
	s_mov_b32 m0, s50
	s_nop 0
	global_load_lds_dwordx4 v134, s[48:49]
	s_waitcnt vmcnt(8)
	s_waitcnt lgkmcnt(0)
	s_barrier
	s_waitcnt lgkmcnt(0)
	v_mfma_f32_16x16x32_bf16 v[62:65], v[148:151], v[184:187], v[62:65]
	v_mfma_f32_16x16x32_bf16 v[58:61], v[160:163], v[184:187], v[58:61]
	v_mfma_f32_16x16x32_bf16 v[46:49], v[148:151], v[192:195], v[46:49]
	v_mfma_f32_16x16x32_bf16 v[42:45], v[160:163], v[192:195], v[42:45]
	v_mfma_f32_16x16x32_bf16 v[30:33], v[148:151], v[200:203], v[30:33]
	v_mfma_f32_16x16x32_bf16 v[26:29], v[160:163], v[200:203], v[26:29]
	v_mfma_f32_16x16x32_bf16 v[14:17], v[148:151], v[212:215], v[14:17]
	v_mfma_f32_16x16x32_bf16 v[10:13], v[160:163], v[212:215], v[10:13]
	v_mfma_f32_16x16x32_bf16 v[62:65], v[156:159], v[188:191], v[62:65]
	v_mfma_f32_16x16x32_bf16 v[58:61], v[164:167], v[188:191], v[58:61]
	v_mfma_f32_16x16x32_bf16 v[46:49], v[156:159], v[196:199], v[46:49]
	v_mfma_f32_16x16x32_bf16 v[42:45], v[164:167], v[196:199], v[42:45]
	v_mfma_f32_16x16x32_bf16 v[30:33], v[156:159], v[208:211], v[30:33]
	v_mfma_f32_16x16x32_bf16 v[26:29], v[164:167], v[208:211], v[26:29]
	v_mfma_f32_16x16x32_bf16 v[14:17], v[156:159], v[216:219], v[14:17]
	v_mfma_f32_16x16x32_bf16 v[10:13], v[164:167], v[216:219], v[10:13]
	v_mfma_f32_16x16x32_bf16 v[54:57], v[168:171], v[184:187], v[54:57]
	v_mfma_f32_16x16x32_bf16 v[50:53], v[176:179], v[184:187], v[50:53]
	v_mfma_f32_16x16x32_bf16 v[38:41], v[168:171], v[192:195], v[38:41]
	v_mfma_f32_16x16x32_bf16 v[34:37], v[176:179], v[192:195], v[34:37]
	v_mfma_f32_16x16x32_bf16 v[22:25], v[168:171], v[200:203], v[22:25]
	v_mfma_f32_16x16x32_bf16 v[18:21], v[176:179], v[200:203], v[18:21]
	v_mfma_f32_16x16x32_bf16 v[6:9], v[168:171], v[212:215], v[6:9]
	v_mfma_f32_16x16x32_bf16 v[2:5], v[176:179], v[212:215], v[2:5]
	v_mfma_f32_16x16x32_bf16 v[54:57], v[172:175], v[188:191], v[54:57]
	v_mfma_f32_16x16x32_bf16 v[50:53], v[180:183], v[188:191], v[50:53]
	v_mfma_f32_16x16x32_bf16 v[38:41], v[172:175], v[196:199], v[38:41]
	v_mfma_f32_16x16x32_bf16 v[34:37], v[180:183], v[196:199], v[34:37]
	v_mfma_f32_16x16x32_bf16 v[22:25], v[172:175], v[208:211], v[22:25]
	v_mfma_f32_16x16x32_bf16 v[18:21], v[180:183], v[208:211], v[18:21]
	v_mfma_f32_16x16x32_bf16 v[6:9], v[172:175], v[216:219], v[6:9]
	v_mfma_f32_16x16x32_bf16 v[2:5], v[180:183], v[216:219], v[2:5]
	s_barrier
; #define PG8_STAGE(bufoff, gbase, voff) do { _Pragma("unroll") for (int _i = 0; _i < 2; ++_i) \
;         __builtin_amdgcn_global_load_lds((const unsigned*)((const char*)(gbase) + (voff)[_i]), (PG8_LAS unsigned*)(lds + (bufoff) + ldsw + _i * 8192), 16, 0, 0); } while (0)
; #define PG8_LDA(dst, b, h) do { _Pragma("unroll") for (int m = 0; m < 4; ++m) _Pragma("unroll") for (int k = 0; k < 2; ++k) dst[m][k] = *(const PG8_LAS bf16x8*)(lds + PG8_SA(b, h) + aoff + m * 2048 + k * 1024); } while (0)
; #define PG8_LDB(dst, b, h) do { _Pragma("unroll") for (int n = 0; n < 2; ++n) _Pragma("unroll") for (int k = 0; k < 2; ++k) dst[n][k] = *(const PG8_LAS bf16x8*)(lds + PG8_SB(b, h) + boff + n * 2048 + k * 1024); } while (0)
; #define PG8_MMA(ai, bj, At, Bt) do { __builtin_amdgcn_s_setprio(1); _Pragma("unroll") for (int m = 0; m < 4; ++m) _Pragma("unroll") for (int n = 0; n < 2; ++n) _Pragma("unroll") for (int k = 0; k < 2; ++k) \
;         acc[ai][bj][m][n] = __builtin_amdgcn_mfma_f32_16x16x32_bf16(Bt[n][k], At[m][k], acc[ai][bj][m][n], 0, 0, 0); __builtin_amdgcn_s_setprio(0); } while (0)
; #define PG8_WAIT_V(n) asm volatile("s_waitcnt vmcnt(" #n ")" ::: "memory")
; #define PG8_WAIT_L(n) asm volatile("s_waitcnt lgkmcnt(" #n ")" ::: "memory")
; #define PG8_BAR __builtin_amdgcn_s_barrier()
; #define PG8_SCHED __builtin_amdgcn_sched_barrier(0)
; template <class Epi, class Sched, bool ALIGN_EPI = false, bool SP2 = false>
; __device__ __forceinline__ void gemm_phase(PG8_LAS unsigned char* lds, const Gemm g, const Sched& S, const Epi& E) {
;     ...
;             PG8_LDB(B0, 1, 0); PG8_LDB(B1, 1, 1); PG8_SCHED; PG8_LDA(At, 1, 0); PG8_STAGE(PG8_SA(0, 1), a2 + hstep, voffA);
;             PG8_WAIT_V(8); PG8_WAIT_L(0); PG8_BAR; PG8_MMA(0, 0, At, B0); PG8_MMA(0, 1, At, B1); PG8_BAR; PG8_SCHED;
;             PG8_LDA(At, 1, 1); PG8_STAGE(PG8_SB(1, 0), b3, voffB); PG8_STAGE(PG8_SB(1, 1), b3 + hstep, voffB); PG8_STAGE(PG8_SA(1, 0), a3, voffA);
;             PG8_WAIT_V(8); PG8_WAIT_L(0); PG8_BAR; PG8_MMA(1, 0, At, B0); PG8_MMA(1, 1, At, B1); PG8_BAR; PG8_SCHED;
	s_add_i32 s74, 0, 0x18000
	s_add_i32 s75, 0, 0x1c000
	v_add_u32_e32 v164, s74, v139
	v_add_u32_e32 v180, s75, v139
	ds_read_b128 v[148:151], v164
	ds_read_b128 v[156:159], v164 offset:1024
	ds_read_b128 v[160:163], v164 offset:2048
	ds_read_b128 v[164:167], v164 offset:3072
	ds_read_b128 v[168:171], v180
	ds_read_b128 v[172:175], v180 offset:1024
	ds_read_b128 v[176:179], v180 offset:2048
	ds_read_b128 v[180:183], v180 offset:3072
	s_add_u32 s48, s48, 0x40000
	s_addc_u32 s49, s49, 0
	s_mov_b32 m0, s51
	ds_read_b128 v[184:187], v154 offset:32768
	ds_read_b128 v[188:191], v154 offset:33792
	ds_read_b128 v[192:195], v154 offset:34816
	ds_read_b128 v[196:199], v154 offset:35840
	ds_read_b128 v[200:203], v154 offset:36864
	ds_read_b128 v[208:211], v154 offset:37888
	ds_read_b128 v[212:215], v154 offset:38912
	ds_read_b128 v[216:219], v154 offset:39936
	global_load_lds_dwordx4 v130, s[48:49]
	s_mov_b32 m0, s60
	s_nop 0
	global_load_lds_dwordx4 v134, s[48:49]
	s_waitcnt vmcnt(8)
	s_waitcnt lgkmcnt(0)
	s_barrier
	s_waitcnt lgkmcnt(0)
	v_mfma_f32_16x16x32_bf16 v[126:129], v[148:151], v[184:187], v[126:129]
	v_mfma_f32_16x16x32_bf16 v[122:125], v[160:163], v[184:187], v[122:125]
	v_mfma_f32_16x16x32_bf16 v[110:113], v[148:151], v[192:195], v[110:113]
	v_mfma_f32_16x16x32_bf16 v[106:109], v[160:163], v[192:195], v[106:109]
	v_mfma_f32_16x16x32_bf16 v[94:97], v[148:151], v[200:203], v[94:97]
	v_mfma_f32_16x16x32_bf16 v[90:93], v[160:163], v[200:203], v[90:93]
	v_mfma_f32_16x16x32_bf16 v[78:81], v[148:151], v[212:215], v[78:81]
	v_mfma_f32_16x16x32_bf16 v[74:77], v[160:163], v[212:215], v[74:77]
	v_mfma_f32_16x16x32_bf16 v[126:129], v[156:159], v[188:191], v[126:129]
	v_mfma_f32_16x16x32_bf16 v[122:125], v[164:167], v[188:191], v[122:125]
	v_mfma_f32_16x16x32_bf16 v[110:113], v[156:159], v[196:199], v[110:113]
	v_mfma_f32_16x16x32_bf16 v[106:109], v[164:167], v[196:199], v[106:109]
	v_mfma_f32_16x16x32_bf16 v[94:97], v[156:159], v[208:211], v[94:97]
	v_mfma_f32_16x16x32_bf16 v[90:93], v[164:167], v[208:211], v[90:93]
	v_mfma_f32_16x16x32_bf16 v[78:81], v[156:159], v[216:219], v[78:81]
	v_mfma_f32_16x16x32_bf16 v[74:77], v[164:167], v[216:219], v[74:77]
	v_mfma_f32_16x16x32_bf16 v[118:121], v[168:171], v[184:187], v[118:121]
	v_mfma_f32_16x16x32_bf16 v[114:117], v[176:179], v[184:187], v[114:117]
	v_mfma_f32_16x16x32_bf16 v[102:105], v[168:171], v[192:195], v[102:105]
	v_mfma_f32_16x16x32_bf16 v[98:101], v[176:179], v[192:195], v[98:101]
	v_mfma_f32_16x16x32_bf16 v[86:89], v[168:171], v[200:203], v[86:89]
	v_mfma_f32_16x16x32_bf16 v[82:85], v[176:179], v[200:203], v[82:85]
	v_mfma_f32_16x16x32_bf16 v[70:73], v[168:171], v[212:215], v[70:73]
	v_mfma_f32_16x16x32_bf16 v[66:69], v[176:179], v[212:215], v[66:69]
	v_mfma_f32_16x16x32_bf16 v[118:121], v[172:175], v[188:191], v[118:121]
	v_mfma_f32_16x16x32_bf16 v[114:117], v[180:183], v[188:191], v[114:117]
	v_mfma_f32_16x16x32_bf16 v[102:105], v[172:175], v[196:199], v[102:105]
	v_mfma_f32_16x16x32_bf16 v[98:101], v[180:183], v[196:199], v[98:101]
	v_mfma_f32_16x16x32_bf16 v[86:89], v[172:175], v[208:211], v[86:89]
	v_mfma_f32_16x16x32_bf16 v[82:85], v[180:183], v[208:211], v[82:85]
	v_mfma_f32_16x16x32_bf16 v[70:73], v[172:175], v[216:219], v[70:73]
	v_mfma_f32_16x16x32_bf16 v[66:69], v[180:183], v[216:219], v[66:69]
	s_barrier
	s_add_i32 s48, s74, s30
	s_mov_b32 m0, s48
	ds_read_b128 v[184:187], v154 offset:49152
	ds_read_b128 v[188:191], v154 offset:50176
	ds_read_b128 v[192:195], v154 offset:51200
	ds_read_b128 v[196:199], v154 offset:52224
	ds_read_b128 v[200:203], v154 offset:53248
	ds_read_b128 v[208:211], v154 offset:54272
	ds_read_b128 v[212:215], v154 offset:55296
	ds_read_b128 v[216:219], v154 offset:56320
	s_add_u32 s98, s46, s14
	s_addc_u32 s99, s47, s15
	global_load_lds_dwordx4 v132, s[98:99]
	s_add_i32 m0, s48, 0x2000
	s_add_u32 s46, s46, 0x40080
	v_lshl_add_u64 v[204:205], v[220:221], 0, s[14:15]
	s_addc_u32 s47, s47, 0
	s_add_i32 s48, s75, s30
	global_load_lds_dwordx4 v[204:205], off
	s_mov_b32 m0, s48
	s_nop 0
	global_load_lds_dwordx4 v132, s[46:47]
	s_add_i32 m0, s48, 0x2000
	s_nop 0
	global_load_lds_dwordx4 v136, s[46:47]
	v_lshl_add_u64 v[204:205], v[222:223], 0, s[14:15]
	s_mov_b32 m0, s62
	s_nop 0
	global_load_lds_dwordx4 v[204:205], off
	v_lshl_add_u64 v[204:205], v[224:225], 0, s[14:15]
	s_mov_b32 m0, s63
	s_nop 0
	global_load_lds_dwordx4 v[204:205], off
	s_waitcnt vmcnt(8)
	s_waitcnt lgkmcnt(0)
	s_barrier
	s_waitcnt lgkmcnt(0)
	v_mfma_f32_16x16x32_bf16 v[62:65], v[148:151], v[184:187], v[62:65]
	v_mfma_f32_16x16x32_bf16 v[58:61], v[160:163], v[184:187], v[58:61]
	v_mfma_f32_16x16x32_bf16 v[46:49], v[148:151], v[192:195], v[46:49]
	v_mfma_f32_16x16x32_bf16 v[42:45], v[160:163], v[192:195], v[42:45]
	v_mfma_f32_16x16x32_bf16 v[30:33], v[148:151], v[200:203], v[30:33]
	v_mfma_f32_16x16x32_bf16 v[26:29], v[160:163], v[200:203], v[26:29]
	v_mfma_f32_16x16x32_bf16 v[14:17], v[148:151], v[212:215], v[14:17]
	v_mfma_f32_16x16x32_bf16 v[10:13], v[160:163], v[212:215], v[10:13]
	v_mfma_f32_16x16x32_bf16 v[62:65], v[156:159], v[188:191], v[62:65]
	v_mfma_f32_16x16x32_bf16 v[58:61], v[164:167], v[188:191], v[58:61]
	v_mfma_f32_16x16x32_bf16 v[46:49], v[156:159], v[196:199], v[46:49]
	v_mfma_f32_16x16x32_bf16 v[42:45], v[164:167], v[196:199], v[42:45]
	v_mfma_f32_16x16x32_bf16 v[30:33], v[156:159], v[208:211], v[30:33]
	v_mfma_f32_16x16x32_bf16 v[26:29], v[164:167], v[208:211], v[26:29]
	v_mfma_f32_16x16x32_bf16 v[14:17], v[156:159], v[216:219], v[14:17]
	v_mfma_f32_16x16x32_bf16 v[10:13], v[164:167], v[216:219], v[10:13]
	v_mfma_f32_16x16x32_bf16 v[54:57], v[168:171], v[184:187], v[54:57]
	v_mfma_f32_16x16x32_bf16 v[50:53], v[176:179], v[184:187], v[50:53]
	v_mfma_f32_16x16x32_bf16 v[38:41], v[168:171], v[192:195], v[38:41]
	v_mfma_f32_16x16x32_bf16 v[34:37], v[176:179], v[192:195], v[34:37]
	v_mfma_f32_16x16x32_bf16 v[22:25], v[168:171], v[200:203], v[22:25]
	v_mfma_f32_16x16x32_bf16 v[18:21], v[176:179], v[200:203], v[18:21]
	v_mfma_f32_16x16x32_bf16 v[6:9], v[168:171], v[212:215], v[6:9]
	v_mfma_f32_16x16x32_bf16 v[2:5], v[176:179], v[212:215], v[2:5]
	v_mfma_f32_16x16x32_bf16 v[54:57], v[172:175], v[188:191], v[54:57]
	v_mfma_f32_16x16x32_bf16 v[50:53], v[180:183], v[188:191], v[50:53]
	v_mfma_f32_16x16x32_bf16 v[38:41], v[172:175], v[196:199], v[38:41]
	v_mfma_f32_16x16x32_bf16 v[34:37], v[180:183], v[196:199], v[34:37]
	v_mfma_f32_16x16x32_bf16 v[22:25], v[172:175], v[208:211], v[22:25]
	v_mfma_f32_16x16x32_bf16 v[18:21], v[180:183], v[208:211], v[18:21]
	v_mfma_f32_16x16x32_bf16 v[6:9], v[172:175], v[216:219], v[6:9]
	v_mfma_f32_16x16x32_bf16 v[2:5], v[180:183], v[216:219], v[2:5]
	s_add_i32 s73, s73, 2
	s_add_u32 s44, s44, 0x100
	s_addc_u32 s45, s45, 0
	s_add_u32 s71, s71, 0x100
	s_addc_u32 s72, s72, 0
	s_cmp_gt_u32 s73, 13
	s_barrier
	s_cbranch_scc0 .LBB0_646
	s_and_b64 vcc, exec, s[16:17]
	s_cbranch_vccz .LBB0_649
	s_barrier

; #define PG8_STAGE(bufoff, gbase, voff) do { _Pragma("unroll") for (int _i = 0; _i < 2; ++_i) \
;         __builtin_amdgcn_global_load_lds((const unsigned*)((const char*)(gbase) + (voff)[_i]), (PG8_LAS unsigned*)(lds + (bufoff) + ldsw + _i * 8192), 16, 0, 0); } while (0)
; #define PG8_LDA(dst, b, h) do { _Pragma("unroll") for (int m = 0; m < 4; ++m) _Pragma("unroll") for (int k = 0; k < 2; ++k) dst[m][k] = *(const PG8_LAS bf16x8*)(lds + PG8_SA(b, h) + aoff + m * 2048 + k * 1024); } while (0)
; #define PG8_MMA(ai, bj, At, Bt) do { __builtin_amdgcn_s_setprio(1); _Pragma("unroll") for (int m = 0; m < 4; ++m) _Pragma("unroll") for (int n = 0; n < 2; ++n) _Pragma("unroll") for (int k = 0; k < 2; ++k) \
;         acc[ai][bj][m][n] = __builtin_amdgcn_mfma_f32_16x16x32_bf16(Bt[n][k], At[m][k], acc[ai][bj][m][n], 0, 0, 0); __builtin_amdgcn_s_setprio(0); } while (0)
; #define PG8_WAIT_V(n) asm volatile("s_waitcnt vmcnt(" #n ")" ::: "memory")
; #define PG8_WAIT_L(n) asm volatile("s_waitcnt lgkmcnt(" #n ")" ::: "memory")
; #define PG8_BAR __builtin_amdgcn_s_barrier()
; #define PG8_SCHED __builtin_amdgcn_sched_barrier(0)
; template <class Epi, class Sched, bool ALIGN_EPI = false, bool SP2 = false>
; __device__ __forceinline__ void gemm_phase(PG8_LAS unsigned char* lds, const Gemm g, const Sched& S, const Epi& E) {
;     ...
;             PG8_WAIT_V(8); PG8_WAIT_L(0); PG8_BAR; PG8_MMA(0, 0, At, B0); PG8_MMA(0, 1, At, B1); PG8_BAR; PG8_SCHED;
;             PG8_LDA(At, 0, 1); PG8_STAGE(PG8_SB(0, 0), b2, voffB); PG8_STAGE(PG8_SB(0, 1), b2 + hstep, voffB); PG8_STAGE(PG8_SA(0, 0), a2, voffA);
;             PG8_WAIT_V(8); PG8_WAIT_L(0); PG8_BAR; PG8_MMA(1, 0, At, B0); PG8_MMA(1, 1, At, B1); PG8_BAR; PG8_SCHED;
.Lpw_740_0:
	s_waitcnt lgkmcnt(0)
	s_barrier
	s_waitcnt lgkmcnt(0)
	v_mfma_f32_16x16x32_bf16 v[126:129], v[156:159], v[188:191], 0
	v_mfma_f32_16x16x32_bf16 v[122:125], v[164:167], v[188:191], 0
	v_mfma_f32_16x16x32_bf16 v[110:113], v[156:159], v[196:199], 0
	v_mfma_f32_16x16x32_bf16 v[106:109], v[164:167], v[196:199], 0
	v_mfma_f32_16x16x32_bf16 v[94:97], v[156:159], v[208:211], 0
	v_mfma_f32_16x16x32_bf16 v[90:93], v[164:167], v[208:211], 0
	v_mfma_f32_16x16x32_bf16 v[78:81], v[156:159], v[216:219], 0
	v_mfma_f32_16x16x32_bf16 v[74:77], v[164:167], v[216:219], 0
	v_mfma_f32_16x16x32_bf16 v[126:129], v[160:163], v[192:195], v[126:129]
	v_mfma_f32_16x16x32_bf16 v[122:125], v[168:171], v[192:195], v[122:125]
	v_mfma_f32_16x16x32_bf16 v[110:113], v[160:163], v[200:203], v[110:113]
	v_mfma_f32_16x16x32_bf16 v[106:109], v[168:171], v[200:203], v[106:109]
	v_mfma_f32_16x16x32_bf16 v[94:97], v[160:163], v[212:215], v[94:97]
	v_mfma_f32_16x16x32_bf16 v[90:93], v[168:171], v[212:215], v[90:93]
	v_mfma_f32_16x16x32_bf16 v[78:81], v[160:163], v[220:223], v[78:81]
	v_mfma_f32_16x16x32_bf16 v[74:77], v[168:171], v[220:223], v[74:77]
	v_mfma_f32_16x16x32_bf16 v[118:121], v[172:175], v[188:191], 0
	v_mfma_f32_16x16x32_bf16 v[114:117], v[180:183], v[188:191], 0
	v_mfma_f32_16x16x32_bf16 v[102:105], v[172:175], v[196:199], 0
	v_mfma_f32_16x16x32_bf16 v[98:101], v[180:183], v[196:199], 0
	v_mfma_f32_16x16x32_bf16 v[86:89], v[172:175], v[208:211], 0
	v_mfma_f32_16x16x32_bf16 v[82:85], v[180:183], v[208:211], 0
	v_mfma_f32_16x16x32_bf16 v[70:73], v[172:175], v[216:219], 0
	v_mfma_f32_16x16x32_bf16 v[66:69], v[180:183], v[216:219], 0
	v_mfma_f32_16x16x32_bf16 v[118:121], v[176:179], v[192:195], v[118:121]
	v_mfma_f32_16x16x32_bf16 v[114:117], v[184:187], v[192:195], v[114:117]
	v_mfma_f32_16x16x32_bf16 v[102:105], v[176:179], v[200:203], v[102:105]
	v_mfma_f32_16x16x32_bf16 v[98:101], v[184:187], v[200:203], v[98:101]
	v_mfma_f32_16x16x32_bf16 v[86:89], v[176:179], v[212:215], v[86:89]
	v_mfma_f32_16x16x32_bf16 v[82:85], v[184:187], v[212:215], v[82:85]
	v_mfma_f32_16x16x32_bf16 v[70:73], v[176:179], v[220:223], v[70:73]
	v_mfma_f32_16x16x32_bf16 v[66:69], v[184:187], v[220:223], v[66:69]
	s_barrier
	s_add_i32 s72, s66, s47
	s_mov_b32 m0, s72
	ds_read_b128 v[188:191], v154 offset:16384
	ds_read_b128 v[192:195], v154 offset:17408
	ds_read_b128 v[196:199], v154 offset:18432
	ds_read_b128 v[200:203], v154 offset:19456
	ds_read_b128 v[208:211], v154 offset:20480
	ds_read_b128 v[212:215], v154 offset:21504
	ds_read_b128 v[216:219], v154 offset:22528
	ds_read_b128 v[220:223], v154 offset:23552
	global_load_lds_dwordx4 v132, s[40:41]
	s_add_i32 m0, s72, 0x2000
	s_add_u32 s72, s40, 0x40000
	v_lshl_add_u64 v[204:205], s[40:41], 0, v[136:137]
	s_addc_u32 s73, s41, 0
	s_add_i32 s74, s67, s47
	global_load_lds_dwordx4 v136, s[40:41]
	s_mov_b32 m0, s74
	v_lshl_add_u64 v[226:227], s[44:45], 0, v[134:135]
	global_load_lds_dwordx4 v132, s[72:73]
	s_add_i32 m0, s74, 0x2000
	s_nop 0
	global_load_lds_dwordx4 v136, s[72:73]
	v_lshl_add_u64 v[224:225], s[44:45], 0, v[130:131]
	s_mov_b32 m0, s48
	s_nop 0
	global_load_lds_dwordx4 v130, s[44:45]
	s_mov_b32 m0, s49
	s_nop 0
	global_load_lds_dwordx4 v134, s[44:45]
	s_waitcnt vmcnt(16)
	s_cmp_gt_u32 s69, 1
	s_cbranch_scc1 .Lpw_740_1
	s_waitcnt vmcnt(8)
.Lpw_740_1:
	s_waitcnt lgkmcnt(0)
	s_barrier
	s_waitcnt lgkmcnt(0)
	v_mfma_f32_16x16x32_bf16 v[62:65], v[156:159], v[188:191], 0
	v_mfma_f32_16x16x32_bf16 v[58:61], v[164:167], v[188:191], 0
	v_mfma_f32_16x16x32_bf16 v[46:49], v[156:159], v[196:199], 0
	v_mfma_f32_16x16x32_bf16 v[42:45], v[164:167], v[196:199], 0
	v_mfma_f32_16x16x32_bf16 v[30:33], v[156:159], v[208:211], 0
	v_mfma_f32_16x16x32_bf16 v[26:29], v[164:167], v[208:211], 0
	v_mfma_f32_16x16x32_bf16 v[14:17], v[156:159], v[216:219], 0
	v_mfma_f32_16x16x32_bf16 v[10:13], v[164:167], v[216:219], 0
	v_mfma_f32_16x16x32_bf16 v[62:65], v[160:163], v[192:195], v[62:65]
	v_mfma_f32_16x16x32_bf16 v[58:61], v[168:171], v[192:195], v[58:61]
	v_mfma_f32_16x16x32_bf16 v[46:49], v[160:163], v[200:203], v[46:49]
	v_mfma_f32_16x16x32_bf16 v[42:45], v[168:171], v[200:203], v[42:45]
	v_mfma_f32_16x16x32_bf16 v[30:33], v[160:163], v[212:215], v[30:33]
	v_mfma_f32_16x16x32_bf16 v[26:29], v[168:171], v[212:215], v[26:29]
	v_mfma_f32_16x16x32_bf16 v[14:17], v[160:163], v[220:223], v[14:17]
	v_mfma_f32_16x16x32_bf16 v[10:13], v[168:171], v[220:223], v[10:13]
	v_mfma_f32_16x16x32_bf16 v[54:57], v[172:175], v[188:191], 0
	v_mfma_f32_16x16x32_bf16 v[50:53], v[180:183], v[188:191], 0
	v_mfma_f32_16x16x32_bf16 v[38:41], v[172:175], v[196:199], 0
	v_mfma_f32_16x16x32_bf16 v[34:37], v[180:183], v[196:199], 0
	v_mfma_f32_16x16x32_bf16 v[22:25], v[172:175], v[208:211], 0
	v_mfma_f32_16x16x32_bf16 v[18:21], v[180:183], v[208:211], 0
	v_mfma_f32_16x16x32_bf16 v[6:9], v[172:175], v[216:219], 0
	v_mfma_f32_16x16x32_bf16 v[2:5], v[180:183], v[216:219], 0
	v_mfma_f32_16x16x32_bf16 v[54:57], v[176:179], v[192:195], v[54:57]
	v_mfma_f32_16x16x32_bf16 v[50:53], v[184:187], v[192:195], v[50:53]
	v_mfma_f32_16x16x32_bf16 v[38:41], v[176:179], v[200:203], v[38:41]
	v_mfma_f32_16x16x32_bf16 v[34:37], v[184:187], v[200:203], v[34:37]
	v_mfma_f32_16x16x32_bf16 v[22:25], v[176:179], v[212:215], v[22:25]
	v_mfma_f32_16x16x32_bf16 v[18:21], v[184:187], v[212:215], v[18:21]
	v_mfma_f32_16x16x32_bf16 v[6:9], v[176:179], v[220:223], v[6:9]
	v_mfma_f32_16x16x32_bf16 v[2:5], v[184:187], v[220:223], v[2:5]
	s_barrier
; #define PG8_STAGE(bufoff, gbase, voff) do { _Pragma("unroll") for (int _i = 0; _i < 2; ++_i) \
;         __builtin_amdgcn_global_load_lds((const unsigned*)((const char*)(gbase) + (voff)[_i]), (PG8_LAS unsigned*)(lds + (bufoff) + ldsw + _i * 8192), 16, 0, 0); } while (0)
; #define PG8_LDA(dst, b, h) do { _Pragma("unroll") for (int m = 0; m < 4; ++m) _Pragma("unroll") for (int k = 0; k < 2; ++k) dst[m][k] = *(const PG8_LAS bf16x8*)(lds + PG8_SA(b, h) + aoff + m * 2048 + k * 1024); } while (0)
; #define PG8_LDB(dst, b, h) do { _Pragma("unroll") for (int n = 0; n < 2; ++n) _Pragma("unroll") for (int k = 0; k < 2; ++k) dst[n][k] = *(const PG8_LAS bf16x8*)(lds + PG8_SB(b, h) + boff + n * 2048 + k * 1024); } while (0)
; #define PG8_MMA(ai, bj, At, Bt) do { __builtin_amdgcn_s_setprio(1); _Pragma("unroll") for (int m = 0; m < 4; ++m) _Pragma("unroll") for (int n = 0; n < 2; ++n) _Pragma("unroll") for (int k = 0; k < 2; ++k) \
;         acc[ai][bj][m][n] = __builtin_amdgcn_mfma_f32_16x16x32_bf16(Bt[n][k], At[m][k], acc[ai][bj][m][n], 0, 0, 0); __builtin_amdgcn_s_setprio(0); } while (0)
; #define PG8_WAIT_V(n) asm volatile("s_waitcnt vmcnt(" #n ")" ::: "memory")
; #define PG8_WAIT_L(n) asm volatile("s_waitcnt lgkmcnt(" #n ")" ::: "memory")
; #define PG8_BAR __builtin_amdgcn_s_barrier()
; #define PG8_SCHED __builtin_amdgcn_sched_barrier(0)
; template <class Epi, class Sched, bool ALIGN_EPI = false, bool SP2 = false>
; __device__ __forceinline__ void gemm_phase(PG8_LAS unsigned char* lds, const Gemm g, const Sched& S, const Epi& E) {
;     ...
;             PG8_LDB(B0, 1, 0); PG8_LDB(B1, 1, 1); PG8_SCHED; PG8_LDA(At, 1, 0); PG8_STAGE(PG8_SA(0, 1), a2 + hstep, voffA);
;             PG8_WAIT_V(8); PG8_WAIT_L(0); PG8_BAR; PG8_MMA(0, 0, At, B0); PG8_MMA(0, 1, At, B1); PG8_BAR; PG8_SCHED;
;             PG8_LDA(At, 1, 1); PG8_STAGE(PG8_SB(1, 0), b3, voffB); PG8_STAGE(PG8_SB(1, 1), b3 + hstep, voffB); PG8_STAGE(PG8_SA(1, 0), a3, voffA);
;             PG8_WAIT_V(8); PG8_WAIT_L(0); PG8_BAR; PG8_MMA(1, 0, At, B0); PG8_MMA(1, 1, At, B1); PG8_BAR; PG8_SCHED;
	s_add_i32 s72, 0, 0x18000
	v_add_u32_e32 v150, s72, v151
	s_add_i32 s73, 0, 0x1c000
	ds_read_b128 v[156:159], v150
	ds_read_b128 v[160:163], v150 offset:1024
	ds_read_b128 v[164:167], v150 offset:2048
	ds_read_b128 v[168:171], v150 offset:3072
	v_add_u32_e32 v150, s73, v151
	ds_read_b128 v[172:175], v150
	ds_read_b128 v[176:179], v150 offset:1024
	ds_read_b128 v[180:183], v150 offset:2048
	ds_read_b128 v[184:187], v150 offset:3072
	s_add_u32 s44, s44, 0x40000
	s_addc_u32 s45, s45, 0
	s_mov_b32 m0, s50
	ds_read_b128 v[188:191], v154 offset:32768
	ds_read_b128 v[192:195], v154 offset:33792
	ds_read_b128 v[196:199], v154 offset:34816
	ds_read_b128 v[200:203], v154 offset:35840
	ds_read_b128 v[208:211], v154 offset:36864
	ds_read_b128 v[212:215], v154 offset:37888
	ds_read_b128 v[216:219], v154 offset:38912
	ds_read_b128 v[220:223], v154 offset:39936
	global_load_lds_dwordx4 v130, s[44:45]
	s_mov_b32 m0, s51
	s_nop 0
	global_load_lds_dwordx4 v134, s[44:45]
	s_waitcnt vmcnt(8)
	s_waitcnt lgkmcnt(0)
	s_barrier
	s_waitcnt lgkmcnt(0)
	v_mfma_f32_16x16x32_bf16 v[126:129], v[156:159], v[188:191], v[126:129]
	v_mfma_f32_16x16x32_bf16 v[122:125], v[164:167], v[188:191], v[122:125]
	v_mfma_f32_16x16x32_bf16 v[110:113], v[156:159], v[196:199], v[110:113]
	v_mfma_f32_16x16x32_bf16 v[106:109], v[164:167], v[196:199], v[106:109]
	v_mfma_f32_16x16x32_bf16 v[94:97], v[156:159], v[208:211], v[94:97]
	v_mfma_f32_16x16x32_bf16 v[90:93], v[164:167], v[208:211], v[90:93]
	v_mfma_f32_16x16x32_bf16 v[78:81], v[156:159], v[216:219], v[78:81]
	v_mfma_f32_16x16x32_bf16 v[74:77], v[164:167], v[216:219], v[74:77]
	v_mfma_f32_16x16x32_bf16 v[126:129], v[160:163], v[192:195], v[126:129]
	v_mfma_f32_16x16x32_bf16 v[122:125], v[168:171], v[192:195], v[122:125]
	v_mfma_f32_16x16x32_bf16 v[110:113], v[160:163], v[200:203], v[110:113]
	v_mfma_f32_16x16x32_bf16 v[106:109], v[168:171], v[200:203], v[106:109]
	v_mfma_f32_16x16x32_bf16 v[94:97], v[160:163], v[212:215], v[94:97]
	v_mfma_f32_16x16x32_bf16 v[90:93], v[168:171], v[212:215], v[90:93]
	v_mfma_f32_16x16x32_bf16 v[78:81], v[160:163], v[220:223], v[78:81]
	v_mfma_f32_16x16x32_bf16 v[74:77], v[168:171], v[220:223], v[74:77]
	v_mfma_f32_16x16x32_bf16 v[118:121], v[172:175], v[188:191], v[118:121]
	v_mfma_f32_16x16x32_bf16 v[114:117], v[180:183], v[188:191], v[114:117]
	v_mfma_f32_16x16x32_bf16 v[102:105], v[172:175], v[196:199], v[102:105]
	v_mfma_f32_16x16x32_bf16 v[98:101], v[180:183], v[196:199], v[98:101]
	v_mfma_f32_16x16x32_bf16 v[86:89], v[172:175], v[208:211], v[86:89]
	v_mfma_f32_16x16x32_bf16 v[82:85], v[180:183], v[208:211], v[82:85]
	v_mfma_f32_16x16x32_bf16 v[70:73], v[172:175], v[216:219], v[70:73]
	v_mfma_f32_16x16x32_bf16 v[66:69], v[180:183], v[216:219], v[66:69]
	v_mfma_f32_16x16x32_bf16 v[118:121], v[176:179], v[192:195], v[118:121]
	v_mfma_f32_16x16x32_bf16 v[114:117], v[184:187], v[192:195], v[114:117]
	v_mfma_f32_16x16x32_bf16 v[102:105], v[176:179], v[200:203], v[102:105]
	v_mfma_f32_16x16x32_bf16 v[98:101], v[184:187], v[200:203], v[98:101]
	v_mfma_f32_16x16x32_bf16 v[86:89], v[176:179], v[212:215], v[86:89]
	v_mfma_f32_16x16x32_bf16 v[82:85], v[184:187], v[212:215], v[82:85]
	v_mfma_f32_16x16x32_bf16 v[70:73], v[176:179], v[220:223], v[70:73]
	v_mfma_f32_16x16x32_bf16 v[66:69], v[184:187], v[220:223], v[66:69]
	s_barrier
	s_add_i32 s44, s72, s47
	s_mov_b32 m0, s44
	ds_read_b128 v[188:191], v154 offset:49152
	ds_read_b128 v[192:195], v154 offset:50176
	ds_read_b128 v[196:199], v154 offset:51200
	ds_read_b128 v[200:203], v154 offset:52224
	ds_read_b128 v[208:211], v154 offset:53248
	ds_read_b128 v[212:215], v154 offset:54272
	ds_read_b128 v[216:219], v154 offset:55296
	ds_read_b128 v[220:223], v154 offset:56320
	s_add_u32 s98, s40, s12
	s_addc_u32 s99, s41, s13
	global_load_lds_dwordx4 v132, s[98:99]
	s_add_i32 m0, s44, 0x2000
	s_add_u32 s40, s40, 0x40080
	v_lshl_add_u64 v[148:149], v[204:205], 0, s[12:13]
	s_addc_u32 s41, s41, 0
	s_add_i32 s44, s73, s47
	global_load_lds_dwordx4 v[148:149], off
	s_mov_b32 m0, s44
	s_nop 0
	global_load_lds_dwordx4 v132, s[40:41]
	s_add_i32 m0, s44, 0x2000
	s_nop 0
	global_load_lds_dwordx4 v136, s[40:41]
	v_lshl_add_u64 v[148:149], v[224:225], 0, s[12:13]
	s_mov_b32 m0, s61
	s_nop 0
	global_load_lds_dwordx4 v[148:149], off
	v_lshl_add_u64 v[148:149], v[226:227], 0, s[12:13]
	s_mov_b32 m0, s62
	s_nop 0
	global_load_lds_dwordx4 v[148:149], off
	s_waitcnt vmcnt(8)
	s_waitcnt lgkmcnt(0)
	s_barrier
	s_waitcnt lgkmcnt(0)
	v_mfma_f32_16x16x32_bf16 v[62:65], v[156:159], v[188:191], v[62:65]
	v_mfma_f32_16x16x32_bf16 v[58:61], v[164:167], v[188:191], v[58:61]
	v_mfma_f32_16x16x32_bf16 v[46:49], v[156:159], v[196:199], v[46:49]
	v_mfma_f32_16x16x32_bf16 v[42:45], v[164:167], v[196:199], v[42:45]
	v_mfma_f32_16x16x32_bf16 v[30:33], v[156:159], v[208:211], v[30:33]
	v_mfma_f32_16x16x32_bf16 v[26:29], v[164:167], v[208:211], v[26:29]
	v_mfma_f32_16x16x32_bf16 v[14:17], v[156:159], v[216:219], v[14:17]
	v_mfma_f32_16x16x32_bf16 v[10:13], v[164:167], v[216:219], v[10:13]
	v_mfma_f32_16x16x32_bf16 v[62:65], v[160:163], v[192:195], v[62:65]
	v_mfma_f32_16x16x32_bf16 v[58:61], v[168:171], v[192:195], v[58:61]
	v_mfma_f32_16x16x32_bf16 v[46:49], v[160:163], v[200:203], v[46:49]
	v_mfma_f32_16x16x32_bf16 v[42:45], v[168:171], v[200:203], v[42:45]
	v_mfma_f32_16x16x32_bf16 v[30:33], v[160:163], v[212:215], v[30:33]
	v_mfma_f32_16x16x32_bf16 v[26:29], v[168:171], v[212:215], v[26:29]
	v_mfma_f32_16x16x32_bf16 v[14:17], v[160:163], v[220:223], v[14:17]
	v_mfma_f32_16x16x32_bf16 v[10:13], v[168:171], v[220:223], v[10:13]
	v_mfma_f32_16x16x32_bf16 v[54:57], v[172:175], v[188:191], v[54:57]
	v_mfma_f32_16x16x32_bf16 v[50:53], v[180:183], v[188:191], v[50:53]
	v_mfma_f32_16x16x32_bf16 v[38:41], v[172:175], v[196:199], v[38:41]
	v_mfma_f32_16x16x32_bf16 v[34:37], v[180:183], v[196:199], v[34:37]
	v_mfma_f32_16x16x32_bf16 v[22:25], v[172:175], v[208:211], v[22:25]
	v_mfma_f32_16x16x32_bf16 v[18:21], v[180:183], v[208:211], v[18:21]
	v_mfma_f32_16x16x32_bf16 v[6:9], v[172:175], v[216:219], v[6:9]
	v_mfma_f32_16x16x32_bf16 v[2:5], v[180:183], v[216:219], v[2:5]
	v_mfma_f32_16x16x32_bf16 v[54:57], v[176:179], v[192:195], v[54:57]
	v_mfma_f32_16x16x32_bf16 v[50:53], v[184:187], v[192:195], v[50:53]
	v_mfma_f32_16x16x32_bf16 v[38:41], v[176:179], v[200:203], v[38:41]
	v_mfma_f32_16x16x32_bf16 v[34:37], v[184:187], v[200:203], v[34:37]
	v_mfma_f32_16x16x32_bf16 v[22:25], v[176:179], v[212:215], v[22:25]
	v_mfma_f32_16x16x32_bf16 v[18:21], v[184:187], v[212:215], v[18:21]
	v_mfma_f32_16x16x32_bf16 v[6:9], v[176:179], v[220:223], v[6:9]
	v_mfma_f32_16x16x32_bf16 v[2:5], v[184:187], v[220:223], v[2:5]
	s_add_i32 s71, s71, 2
	s_add_u32 s30, s30, 0x100
	s_addc_u32 s31, s31, 0
	s_add_u32 s33, s33, 0x100
	s_addc_u32 s70, s70, 0
	s_cmp_gt_u32 s71, 13
	s_barrier
; #define PG8_STAGE(bufoff, gbase, voff) do { _Pragma("unroll") for (int _i = 0; _i < 2; ++_i) \
;         __builtin_amdgcn_global_load_lds((const unsigned*)((const char*)(gbase) + (voff)[_i]), (PG8_LAS unsigned*)(lds + (bufoff) + ldsw + _i * 8192), 16, 0, 0); } while (0)
; #define PG8_LDA(dst, b, h) do { _Pragma("unroll") for (int m = 0; m < 4; ++m) _Pragma("unroll") for (int k = 0; k < 2; ++k) dst[m][k] = *(const PG8_LAS bf16x8*)(lds + PG8_SA(b, h) + aoff + m * 2048 + k * 1024); } while (0)
; #define PG8_LDB(dst, b, h) do { _Pragma("unroll") for (int n = 0; n < 2; ++n) _Pragma("unroll") for (int k = 0; k < 2; ++k) dst[n][k] = *(const PG8_LAS bf16x8*)(lds + PG8_SB(b, h) + boff + n * 2048 + k * 1024); } while (0)
; #define PG8_MMA(ai, bj, At, Bt) do { __builtin_amdgcn_s_setprio(1); _Pragma("unroll") for (int m = 0; m < 4; ++m) _Pragma("unroll") for (int n = 0; n < 2; ++n) _Pragma("unroll") for (int k = 0; k < 2; ++k) \
;         acc[ai][bj][m][n] = __builtin_amdgcn_mfma_f32_16x16x32_bf16(Bt[n][k], At[m][k], acc[ai][bj][m][n], 0, 0, 0); __builtin_amdgcn_s_setprio(0); } while (0)
; #define PG8_WAIT_V(n) asm volatile("s_waitcnt vmcnt(" #n ")" ::: "memory")
; #define PG8_WAIT_L(n) asm volatile("s_waitcnt lgkmcnt(" #n ")" ::: "memory")
; template <class Epi, class Sched, bool ALIGN_EPI = false, bool SP2 = false>
; __device__ __forceinline__ void gemm_phase(PG8_LAS unsigned char* lds, const Gemm g, const Sched& S, const Epi& E) {
;     ...
;             const bool last = (t == nt - 2);
;             const char* a1 = cA + (size_t)(t + 1) * kstep;
;             const char* a2 = last ? nA : cA + (size_t)(t + 2) * kstep; const char* b2 = last ? nB : cB + (size_t)(t + 2) * kstep;
;             const char* a3 = a2 + kstep; const char* b3 = b2 + kstep;
;             if (last && has_next) S.a_ready(nxt);
;             if constexpr (SP2) {
;             PG8_LDB(B0, 0, 0); PG8_LDB(B1, 0, 1); PG8_SCHED; PG8_LDA(At, 0, 0); PG8_STAGE(PG8_SA(1, 1), a1 + hstep, voffA);
;             PG8_WAIT_V(8); PG8_WAIT_L(0); PG8_BAR; PG8_MMA(0, 0, At, B0); PG8_MMA(0, 1, At, B1); PG8_BAR; PG8_SCHED;
;             PG8_LDA(At, 0, 1); PG8_STAGE(PG8_SB(0, 0), b2, voffB); PG8_STAGE(PG8_SB(0, 1), b2 + hstep, voffB); PG8_STAGE(PG8_SA(0, 0), a2, voffA);
;             PG8_WAIT_V(8); PG8_WAIT_L(0); PG8_BAR; PG8_MMA(1, 0, At, B0); PG8_MMA(1, 1, At, B1); PG8_BAR; PG8_SCHED;
.LBB0_740:
	ds_read_b128 v[156:159], v152
	ds_read_b128 v[160:163], v152 offset:1024
	ds_read_b128 v[164:167], v152 offset:2048
	ds_read_b128 v[168:171], v152 offset:3072
	ds_read_b128 v[172:175], v153
	ds_read_b128 v[176:179], v153 offset:1024
	ds_read_b128 v[180:183], v153 offset:2048
	ds_read_b128 v[184:187], v153 offset:3072
	s_add_u32 s40, s30, 0xfffc0080
	s_addc_u32 s41, s31, -1
	s_cmp_eq_u32 s71, 12
	s_cselect_b32 s45, s19, s41
	s_cselect_b32 s44, s25, s40
	s_cselect_b32 s41, s17, s70
	s_cselect_b32 s40, s27, s33
	v_lshl_add_u64 v[148:149], s[30:31], 0, v[140:141]
	s_add_i32 m0, s48, 0xc000
	ds_read_b128 v[188:191], v154
	ds_read_b128 v[192:195], v154 offset:1024
	ds_read_b128 v[196:199], v154 offset:2048
	ds_read_b128 v[200:203], v154 offset:3072
	ds_read_b128 v[208:211], v154 offset:4096
	ds_read_b128 v[212:215], v154 offset:5120
	ds_read_b128 v[216:219], v154 offset:6144
	ds_read_b128 v[220:223], v154 offset:7168
	global_load_lds_dwordx4 v[148:149], off
	v_lshl_add_u64 v[148:149], s[30:31], 0, v[142:143]
	s_add_i32 m0, s48, 0xe000
	s_nop 0
	global_load_lds_dwordx4 v[148:149], off
	s_waitcnt vmcnt(8)
	s_waitcnt lgkmcnt(0)
	s_barrier
	s_waitcnt lgkmcnt(0)
	v_mfma_f32_16x16x32_bf16 v[126:129], v[156:159], v[188:191], v[126:129]
	v_mfma_f32_16x16x32_bf16 v[122:125], v[164:167], v[188:191], v[122:125]
	v_mfma_f32_16x16x32_bf16 v[110:113], v[156:159], v[196:199], v[110:113]
	v_mfma_f32_16x16x32_bf16 v[106:109], v[164:167], v[196:199], v[106:109]
	v_mfma_f32_16x16x32_bf16 v[94:97], v[156:159], v[208:211], v[94:97]
	v_mfma_f32_16x16x32_bf16 v[90:93], v[164:167], v[208:211], v[90:93]
	v_mfma_f32_16x16x32_bf16 v[78:81], v[156:159], v[216:219], v[78:81]
	v_mfma_f32_16x16x32_bf16 v[74:77], v[164:167], v[216:219], v[74:77]
	v_mfma_f32_16x16x32_bf16 v[126:129], v[160:163], v[192:195], v[126:129]
	v_mfma_f32_16x16x32_bf16 v[122:125], v[168:171], v[192:195], v[122:125]
	v_mfma_f32_16x16x32_bf16 v[110:113], v[160:163], v[200:203], v[110:113]
	v_mfma_f32_16x16x32_bf16 v[106:109], v[168:171], v[200:203], v[106:109]
	v_mfma_f32_16x16x32_bf16 v[94:97], v[160:163], v[212:215], v[94:97]
	v_mfma_f32_16x16x32_bf16 v[90:93], v[168:171], v[212:215], v[90:93]
	v_mfma_f32_16x16x32_bf16 v[78:81], v[160:163], v[220:223], v[78:81]
	v_mfma_f32_16x16x32_bf16 v[74:77], v[168:171], v[220:223], v[74:77]
	v_mfma_f32_16x16x32_bf16 v[118:121], v[172:175], v[188:191], v[118:121]
	v_mfma_f32_16x16x32_bf16 v[114:117], v[180:183], v[188:191], v[114:117]
	v_mfma_f32_16x16x32_bf16 v[102:105], v[172:175], v[196:199], v[102:105]
	v_mfma_f32_16x16x32_bf16 v[98:101], v[180:183], v[196:199], v[98:101]
	v_mfma_f32_16x16x32_bf16 v[86:89], v[172:175], v[208:211], v[86:89]
	v_mfma_f32_16x16x32_bf16 v[82:85], v[180:183], v[208:211], v[82:85]
	v_mfma_f32_16x16x32_bf16 v[70:73], v[172:175], v[216:219], v[70:73]
	v_mfma_f32_16x16x32_bf16 v[66:69], v[180:183], v[216:219], v[66:69]
	v_mfma_f32_16x16x32_bf16 v[118:121], v[176:179], v[192:195], v[118:121]
	v_mfma_f32_16x16x32_bf16 v[114:117], v[184:187], v[192:195], v[114:117]
	v_mfma_f32_16x16x32_bf16 v[102:105], v[176:179], v[200:203], v[102:105]
	v_mfma_f32_16x16x32_bf16 v[98:101], v[184:187], v[200:203], v[98:101]
	v_mfma_f32_16x16x32_bf16 v[86:89], v[176:179], v[212:215], v[86:89]
	v_mfma_f32_16x16x32_bf16 v[82:85], v[184:187], v[212:215], v[82:85]
	v_mfma_f32_16x16x32_bf16 v[70:73], v[176:179], v[220:223], v[70:73]
	v_mfma_f32_16x16x32_bf16 v[66:69], v[184:187], v[220:223], v[66:69]
	s_barrier
	s_add_i32 s72, s66, s47
	s_mov_b32 m0, s72
	ds_read_b128 v[188:191], v154 offset:16384
	ds_read_b128 v[192:195], v154 offset:17408
	ds_read_b128 v[196:199], v154 offset:18432
	ds_read_b128 v[200:203], v154 offset:19456
	ds_read_b128 v[208:211], v154 offset:20480
	ds_read_b128 v[212:215], v154 offset:21504
	ds_read_b128 v[216:219], v154 offset:22528
	ds_read_b128 v[220:223], v154 offset:23552
	global_load_lds_dwordx4 v132, s[40:41]
	s_add_i32 m0, s72, 0x2000
	s_add_u32 s72, s40, 0x40000
	v_lshl_add_u64 v[204:205], s[40:41], 0, v[136:137]
	s_addc_u32 s73, s41, 0
	s_add_i32 s74, s67, s47
	global_load_lds_dwordx4 v136, s[40:41]
	s_mov_b32 m0, s74
	v_lshl_add_u64 v[226:227], s[44:45], 0, v[134:135]
	global_load_lds_dwordx4 v132, s[72:73]
	s_add_i32 m0, s74, 0x2000
	s_nop 0
	global_load_lds_dwordx4 v136, s[72:73]
	v_lshl_add_u64 v[224:225], s[44:45], 0, v[130:131]
	s_mov_b32 m0, s48
	s_nop 0
	global_load_lds_dwordx4 v130, s[44:45]
	s_mov_b32 m0, s49
	s_nop 0
	global_load_lds_dwordx4 v134, s[44:45]
	s_waitcnt vmcnt(8)
	s_waitcnt lgkmcnt(0)
	s_barrier
	s_waitcnt lgkmcnt(0)
	v_mfma_f32_16x16x32_bf16 v[62:65], v[156:159], v[188:191], v[62:65]
	v_mfma_f32_16x16x32_bf16 v[58:61], v[164:167], v[188:191], v[58:61]
	v_mfma_f32_16x16x32_bf16 v[46:49], v[156:159], v[196:199], v[46:49]
	v_mfma_f32_16x16x32_bf16 v[42:45], v[164:167], v[196:199], v[42:45]
	v_mfma_f32_16x16x32_bf16 v[30:33], v[156:159], v[208:211], v[30:33]
	v_mfma_f32_16x16x32_bf16 v[26:29], v[164:167], v[208:211], v[26:29]
	v_mfma_f32_16x16x32_bf16 v[14:17], v[156:159], v[216:219], v[14:17]
	v_mfma_f32_16x16x32_bf16 v[10:13], v[164:167], v[216:219], v[10:13]
	v_mfma_f32_16x16x32_bf16 v[62:65], v[160:163], v[192:195], v[62:65]
	v_mfma_f32_16x16x32_bf16 v[58:61], v[168:171], v[192:195], v[58:61]
	v_mfma_f32_16x16x32_bf16 v[46:49], v[160:163], v[200:203], v[46:49]
	v_mfma_f32_16x16x32_bf16 v[42:45], v[168:171], v[200:203], v[42:45]
	v_mfma_f32_16x16x32_bf16 v[30:33], v[160:163], v[212:215], v[30:33]
	v_mfma_f32_16x16x32_bf16 v[26:29], v[168:171], v[212:215], v[26:29]
	v_mfma_f32_16x16x32_bf16 v[14:17], v[160:163], v[220:223], v[14:17]
	v_mfma_f32_16x16x32_bf16 v[10:13], v[168:171], v[220:223], v[10:13]
	v_mfma_f32_16x16x32_bf16 v[54:57], v[172:175], v[188:191], v[54:57]
	v_mfma_f32_16x16x32_bf16 v[50:53], v[180:183], v[188:191], v[50:53]
	v_mfma_f32_16x16x32_bf16 v[38:41], v[172:175], v[196:199], v[38:41]
	v_mfma_f32_16x16x32_bf16 v[34:37], v[180:183], v[196:199], v[34:37]
	v_mfma_f32_16x16x32_bf16 v[22:25], v[172:175], v[208:211], v[22:25]
	v_mfma_f32_16x16x32_bf16 v[18:21], v[180:183], v[208:211], v[18:21]
	v_mfma_f32_16x16x32_bf16 v[6:9], v[172:175], v[216:219], v[6:9]
	v_mfma_f32_16x16x32_bf16 v[2:5], v[180:183], v[216:219], v[2:5]
	v_mfma_f32_16x16x32_bf16 v[54:57], v[176:179], v[192:195], v[54:57]
	v_mfma_f32_16x16x32_bf16 v[50:53], v[184:187], v[192:195], v[50:53]
	v_mfma_f32_16x16x32_bf16 v[38:41], v[176:179], v[200:203], v[38:41]
	v_mfma_f32_16x16x32_bf16 v[34:37], v[184:187], v[200:203], v[34:37]
	v_mfma_f32_16x16x32_bf16 v[22:25], v[176:179], v[212:215], v[22:25]
	v_mfma_f32_16x16x32_bf16 v[18:21], v[184:187], v[212:215], v[18:21]
	v_mfma_f32_16x16x32_bf16 v[6:9], v[176:179], v[220:223], v[6:9]
	v_mfma_f32_16x16x32_bf16 v[2:5], v[184:187], v[220:223], v[2:5]
	s_barrier
; #define PG8_STAGE(bufoff, gbase, voff) do { _Pragma("unroll") for (int _i = 0; _i < 2; ++_i) \
;         __builtin_amdgcn_global_load_lds((const unsigned*)((const char*)(gbase) + (voff)[_i]), (PG8_LAS unsigned*)(lds + (bufoff) + ldsw + _i * 8192), 16, 0, 0); } while (0)
; #define PG8_LDA(dst, b, h) do { _Pragma("unroll") for (int m = 0; m < 4; ++m) _Pragma("unroll") for (int k = 0; k < 2; ++k) dst[m][k] = *(const PG8_LAS bf16x8*)(lds + PG8_SA(b, h) + aoff + m * 2048 + k * 1024); } while (0)
; #define PG8_LDB(dst, b, h) do { _Pragma("unroll") for (int n = 0; n < 2; ++n) _Pragma("unroll") for (int k = 0; k < 2; ++k) dst[n][k] = *(const PG8_LAS bf16x8*)(lds + PG8_SB(b, h) + boff + n * 2048 + k * 1024); } while (0)
; #define PG8_MMA(ai, bj, At, Bt) do { __builtin_amdgcn_s_setprio(1); _Pragma("unroll") for (int m = 0; m < 4; ++m) _Pragma("unroll") for (int n = 0; n < 2; ++n) _Pragma("unroll") for (int k = 0; k < 2; ++k) \
;         acc[ai][bj][m][n] = __builtin_amdgcn_mfma_f32_16x16x32_bf16(Bt[n][k], At[m][k], acc[ai][bj][m][n], 0, 0, 0); __builtin_amdgcn_s_setprio(0); } while (0)
; #define PG8_WAIT_V(n) asm volatile("s_waitcnt vmcnt(" #n ")" ::: "memory")
; #define PG8_WAIT_L(n) asm volatile("s_waitcnt lgkmcnt(" #n ")" ::: "memory")
; #define PG8_BAR __builtin_amdgcn_s_barrier()
; #define PG8_SCHED __builtin_amdgcn_sched_barrier(0)
; template <class Epi, class Sched, bool ALIGN_EPI = false, bool SP2 = false>
; __device__ __forceinline__ void gemm_phase(PG8_LAS unsigned char* lds, const Gemm g, const Sched& S, const Epi& E) {
;     ...
;             PG8_LDB(B0, 1, 0); PG8_LDB(B1, 1, 1); PG8_SCHED; PG8_LDA(At, 1, 0); PG8_STAGE(PG8_SA(0, 1), a2 + hstep, voffA);
;             PG8_WAIT_V(8); PG8_WAIT_L(0); PG8_BAR; PG8_MMA(0, 0, At, B0); PG8_MMA(0, 1, At, B1); PG8_BAR; PG8_SCHED;
;             PG8_LDA(At, 1, 1); PG8_STAGE(PG8_SB(1, 0), b3, voffB); PG8_STAGE(PG8_SB(1, 1), b3 + hstep, voffB); PG8_STAGE(PG8_SA(1, 0), a3, voffA);
;             PG8_WAIT_V(8); PG8_WAIT_L(0); PG8_BAR; PG8_MMA(1, 0, At, B0); PG8_MMA(1, 1, At, B1); PG8_BAR; PG8_SCHED;
	s_add_i32 s72, 0, 0x18000
	v_add_u32_e32 v150, s72, v151
	s_add_i32 s73, 0, 0x1c000
	ds_read_b128 v[156:159], v150
	ds_read_b128 v[160:163], v150 offset:1024
	ds_read_b128 v[164:167], v150 offset:2048
	ds_read_b128 v[168:171], v150 offset:3072
	v_add_u32_e32 v150, s73, v151
	ds_read_b128 v[172:175], v150
	ds_read_b128 v[176:179], v150 offset:1024
	ds_read_b128 v[180:183], v150 offset:2048
	ds_read_b128 v[184:187], v150 offset:3072
	s_add_u32 s44, s44, 0x40000
	s_addc_u32 s45, s45, 0
	s_mov_b32 m0, s50
	ds_read_b128 v[188:191], v154 offset:32768
	ds_read_b128 v[192:195], v154 offset:33792
	ds_read_b128 v[196:199], v154 offset:34816
	ds_read_b128 v[200:203], v154 offset:35840
	ds_read_b128 v[208:211], v154 offset:36864
	ds_read_b128 v[212:215], v154 offset:37888
	ds_read_b128 v[216:219], v154 offset:38912
	ds_read_b128 v[220:223], v154 offset:39936
	global_load_lds_dwordx4 v130, s[44:45]
	s_mov_b32 m0, s51
	s_nop 0
	global_load_lds_dwordx4 v134, s[44:45]
	s_waitcnt vmcnt(8)
	s_waitcnt lgkmcnt(0)
	s_barrier
	s_waitcnt lgkmcnt(0)
	v_mfma_f32_16x16x32_bf16 v[126:129], v[156:159], v[188:191], v[126:129]
	v_mfma_f32_16x16x32_bf16 v[122:125], v[164:167], v[188:191], v[122:125]
	v_mfma_f32_16x16x32_bf16 v[110:113], v[156:159], v[196:199], v[110:113]
	v_mfma_f32_16x16x32_bf16 v[106:109], v[164:167], v[196:199], v[106:109]
	v_mfma_f32_16x16x32_bf16 v[94:97], v[156:159], v[208:211], v[94:97]
	v_mfma_f32_16x16x32_bf16 v[90:93], v[164:167], v[208:211], v[90:93]
	v_mfma_f32_16x16x32_bf16 v[78:81], v[156:159], v[216:219], v[78:81]
	v_mfma_f32_16x16x32_bf16 v[74:77], v[164:167], v[216:219], v[74:77]
	v_mfma_f32_16x16x32_bf16 v[126:129], v[160:163], v[192:195], v[126:129]
	v_mfma_f32_16x16x32_bf16 v[122:125], v[168:171], v[192:195], v[122:125]
	v_mfma_f32_16x16x32_bf16 v[110:113], v[160:163], v[200:203], v[110:113]
	v_mfma_f32_16x16x32_bf16 v[106:109], v[168:171], v[200:203], v[106:109]
	v_mfma_f32_16x16x32_bf16 v[94:97], v[160:163], v[212:215], v[94:97]
	v_mfma_f32_16x16x32_bf16 v[90:93], v[168:171], v[212:215], v[90:93]
	v_mfma_f32_16x16x32_bf16 v[78:81], v[160:163], v[220:223], v[78:81]
	v_mfma_f32_16x16x32_bf16 v[74:77], v[168:171], v[220:223], v[74:77]
	v_mfma_f32_16x16x32_bf16 v[118:121], v[172:175], v[188:191], v[118:121]
	v_mfma_f32_16x16x32_bf16 v[114:117], v[180:183], v[188:191], v[114:117]
	v_mfma_f32_16x16x32_bf16 v[102:105], v[172:175], v[196:199], v[102:105]
	v_mfma_f32_16x16x32_bf16 v[98:101], v[180:183], v[196:199], v[98:101]
	v_mfma_f32_16x16x32_bf16 v[86:89], v[172:175], v[208:211], v[86:89]
	v_mfma_f32_16x16x32_bf16 v[82:85], v[180:183], v[208:211], v[82:85]
	v_mfma_f32_16x16x32_bf16 v[70:73], v[172:175], v[216:219], v[70:73]
	v_mfma_f32_16x16x32_bf16 v[66:69], v[180:183], v[216:219], v[66:69]
	v_mfma_f32_16x16x32_bf16 v[118:121], v[176:179], v[192:195], v[118:121]
	v_mfma_f32_16x16x32_bf16 v[114:117], v[184:187], v[192:195], v[114:117]
	v_mfma_f32_16x16x32_bf16 v[102:105], v[176:179], v[200:203], v[102:105]
	v_mfma_f32_16x16x32_bf16 v[98:101], v[184:187], v[200:203], v[98:101]
	v_mfma_f32_16x16x32_bf16 v[86:89], v[176:179], v[212:215], v[86:89]
	v_mfma_f32_16x16x32_bf16 v[82:85], v[184:187], v[212:215], v[82:85]
	v_mfma_f32_16x16x32_bf16 v[70:73], v[176:179], v[220:223], v[70:73]
	v_mfma_f32_16x16x32_bf16 v[66:69], v[184:187], v[220:223], v[66:69]
	s_barrier
	s_add_i32 s44, s72, s47
	s_mov_b32 m0, s44
	ds_read_b128 v[188:191], v154 offset:49152
	ds_read_b128 v[192:195], v154 offset:50176
	ds_read_b128 v[196:199], v154 offset:51200
	ds_read_b128 v[200:203], v154 offset:52224
	ds_read_b128 v[208:211], v154 offset:53248
	ds_read_b128 v[212:215], v154 offset:54272
	ds_read_b128 v[216:219], v154 offset:55296
	ds_read_b128 v[220:223], v154 offset:56320
	s_add_u32 s98, s40, s12
	s_addc_u32 s99, s41, s13
	global_load_lds_dwordx4 v132, s[98:99]
	s_add_i32 m0, s44, 0x2000
	s_add_u32 s40, s40, 0x40080
	v_lshl_add_u64 v[148:149], v[204:205], 0, s[12:13]
	s_addc_u32 s41, s41, 0
	s_add_i32 s44, s73, s47
	global_load_lds_dwordx4 v[148:149], off
	s_mov_b32 m0, s44
	s_nop 0
	global_load_lds_dwordx4 v132, s[40:41]
	s_add_i32 m0, s44, 0x2000
	s_nop 0
	global_load_lds_dwordx4 v136, s[40:41]
	v_lshl_add_u64 v[148:149], v[224:225], 0, s[12:13]
	s_mov_b32 m0, s61
	s_nop 0
	global_load_lds_dwordx4 v[148:149], off
	v_lshl_add_u64 v[148:149], v[226:227], 0, s[12:13]
	s_mov_b32 m0, s62
	s_nop 0
	global_load_lds_dwordx4 v[148:149], off
	s_waitcnt vmcnt(8)
	s_waitcnt lgkmcnt(0)
	s_barrier
	s_waitcnt lgkmcnt(0)
	v_mfma_f32_16x16x32_bf16 v[62:65], v[156:159], v[188:191], v[62:65]
	v_mfma_f32_16x16x32_bf16 v[58:61], v[164:167], v[188:191], v[58:61]
	v_mfma_f32_16x16x32_bf16 v[46:49], v[156:159], v[196:199], v[46:49]
	v_mfma_f32_16x16x32_bf16 v[42:45], v[164:167], v[196:199], v[42:45]
	v_mfma_f32_16x16x32_bf16 v[30:33], v[156:159], v[208:211], v[30:33]
	v_mfma_f32_16x16x32_bf16 v[26:29], v[164:167], v[208:211], v[26:29]
	v_mfma_f32_16x16x32_bf16 v[14:17], v[156:159], v[216:219], v[14:17]
	v_mfma_f32_16x16x32_bf16 v[10:13], v[164:167], v[216:219], v[10:13]
	v_mfma_f32_16x16x32_bf16 v[62:65], v[160:163], v[192:195], v[62:65]
	v_mfma_f32_16x16x32_bf16 v[58:61], v[168:171], v[192:195], v[58:61]
	v_mfma_f32_16x16x32_bf16 v[46:49], v[160:163], v[200:203], v[46:49]
	v_mfma_f32_16x16x32_bf16 v[42:45], v[168:171], v[200:203], v[42:45]
	v_mfma_f32_16x16x32_bf16 v[30:33], v[160:163], v[212:215], v[30:33]
	v_mfma_f32_16x16x32_bf16 v[26:29], v[168:171], v[212:215], v[26:29]
	v_mfma_f32_16x16x32_bf16 v[14:17], v[160:163], v[220:223], v[14:17]
	v_mfma_f32_16x16x32_bf16 v[10:13], v[168:171], v[220:223], v[10:13]
	v_mfma_f32_16x16x32_bf16 v[54:57], v[172:175], v[188:191], v[54:57]
	v_mfma_f32_16x16x32_bf16 v[50:53], v[180:183], v[188:191], v[50:53]
	v_mfma_f32_16x16x32_bf16 v[38:41], v[172:175], v[196:199], v[38:41]
	v_mfma_f32_16x16x32_bf16 v[34:37], v[180:183], v[196:199], v[34:37]
	v_mfma_f32_16x16x32_bf16 v[22:25], v[172:175], v[208:211], v[22:25]
	v_mfma_f32_16x16x32_bf16 v[18:21], v[180:183], v[208:211], v[18:21]
	v_mfma_f32_16x16x32_bf16 v[6:9], v[172:175], v[216:219], v[6:9]
	v_mfma_f32_16x16x32_bf16 v[2:5], v[180:183], v[216:219], v[2:5]
	v_mfma_f32_16x16x32_bf16 v[54:57], v[176:179], v[192:195], v[54:57]
	v_mfma_f32_16x16x32_bf16 v[50:53], v[184:187], v[192:195], v[50:53]
	v_mfma_f32_16x16x32_bf16 v[38:41], v[176:179], v[200:203], v[38:41]
	v_mfma_f32_16x16x32_bf16 v[34:37], v[184:187], v[200:203], v[34:37]
	v_mfma_f32_16x16x32_bf16 v[22:25], v[176:179], v[212:215], v[22:25]
	v_mfma_f32_16x16x32_bf16 v[18:21], v[184:187], v[212:215], v[18:21]
	v_mfma_f32_16x16x32_bf16 v[6:9], v[176:179], v[220:223], v[6:9]
	v_mfma_f32_16x16x32_bf16 v[2:5], v[184:187], v[220:223], v[2:5]
	s_add_i32 s71, s71, 2
	s_add_u32 s30, s30, 0x100
	s_addc_u32 s31, s31, 0
	s_add_u32 s33, s33, 0x100
	s_addc_u32 s70, s70, 0
	s_cmp_gt_u32 s71, 13
	s_barrier
	s_cbranch_scc0 .LBB0_740
	s_and_b64 vcc, exec, s[14:15]
	s_cbranch_vccz .LBB0_743
	s_barrier

; #define PG8_STAGE(bufoff, gbase, voff) do { _Pragma("unroll") for (int _i = 0; _i < 2; ++_i) \
;         __builtin_amdgcn_global_load_lds((const unsigned*)((const char*)(gbase) + (voff)[_i]), (PG8_LAS unsigned*)(lds + (bufoff) + ldsw + _i * 8192), 16, 0, 0); } while (0)
; #define PG8_LDA(dst, b, h) do { _Pragma("unroll") for (int m = 0; m < 4; ++m) _Pragma("unroll") for (int k = 0; k < 2; ++k) dst[m][k] = *(const PG8_LAS bf16x8*)(lds + PG8_SA(b, h) + aoff + m * 2048 + k * 1024); } while (0)
; #define PG8_LDB(dst, b, h) do { _Pragma("unroll") for (int n = 0; n < 2; ++n) _Pragma("unroll") for (int k = 0; k < 2; ++k) dst[n][k] = *(const PG8_LAS bf16x8*)(lds + PG8_SB(b, h) + boff + n * 2048 + k * 1024); } while (0)
; #define PG8_MMA(ai, bj, At, Bt) do { __builtin_amdgcn_s_setprio(1); _Pragma("unroll") for (int m = 0; m < 4; ++m) _Pragma("unroll") for (int n = 0; n < 2; ++n) _Pragma("unroll") for (int k = 0; k < 2; ++k) \
;         acc[ai][bj][m][n] = __builtin_amdgcn_mfma_f32_16x16x32_bf16(Bt[n][k], At[m][k], acc[ai][bj][m][n], 0, 0, 0); __builtin_amdgcn_s_setprio(0); } while (0)
; #define PG8_WAIT_V(n) asm volatile("s_waitcnt vmcnt(" #n ")" ::: "memory")
; #define PG8_WAIT_L(n) asm volatile("s_waitcnt lgkmcnt(" #n ")" ::: "memory")
; template <class Epi, class Sched, bool ALIGN_EPI = false, bool SP2 = false>
; __device__ __forceinline__ void gemm_phase(PG8_LAS unsigned char* lds, const Gemm g, const Sched& S, const Epi& E) {
;     ...
;             const bool last = (t == nt - 2);
;             const char* a1 = cA + (size_t)(t + 1) * kstep;
;             const char* a2 = last ? nA : cA + (size_t)(t + 2) * kstep; const char* b2 = last ? nB : cB + (size_t)(t + 2) * kstep;
;             const char* a3 = a2 + kstep; const char* b3 = b2 + kstep;
;             if (last && has_next) S.a_ready(nxt);
;             if constexpr (SP2) {
;             PG8_LDB(B0, 0, 0); PG8_LDB(B1, 0, 1); PG8_SCHED; PG8_LDA(At, 0, 0); PG8_STAGE(PG8_SA(1, 1), a1 + hstep, voffA);
;             PG8_WAIT_V(8); PG8_WAIT_L(0); PG8_BAR; PG8_MMA(0, 0, At, B0); PG8_MMA(0, 1, At, B1); PG8_BAR; PG8_SCHED;
;             PG8_LDA(At, 0, 1); PG8_STAGE(PG8_SB(0, 0), b2, voffB); PG8_STAGE(PG8_SB(0, 1), b2 + hstep, voffB); PG8_STAGE(PG8_SA(0, 0), a2, voffA);
;             PG8_WAIT_V(8); PG8_WAIT_L(0); PG8_BAR; PG8_MMA(1, 0, At, B0); PG8_MMA(1, 1, At, B1); PG8_BAR; PG8_SCHED;
.LBB0_860:
	s_add_u32 s24, s24, 0xb0080
	s_addc_u32 s25, s25, 0
	s_add_u32 s51, s26, 0x100
	s_addc_u32 s52, s27, 0
	s_mov_b32 s53, -2
	ds_read_b128 v[146:149], v153
	ds_read_b128 v[156:159], v153 offset:1024
	ds_read_b128 v[160:163], v153 offset:2048
	ds_read_b128 v[164:167], v153 offset:3072
	ds_read_b128 v[168:171], v154
	ds_read_b128 v[172:175], v154 offset:1024
	ds_read_b128 v[176:179], v154 offset:2048
	ds_read_b128 v[180:183], v154 offset:3072
	s_add_u32 s26, s24, 0xfff50080
	s_addc_u32 s27, s25, -1
	s_cmp_eq_u32 s53, 40
	s_cselect_b32 s29, s5, s27
	s_cselect_b32 s28, s4, s26
	s_cselect_b32 s27, s23, s52
	s_cselect_b32 s26, s22, s51
	v_lshl_add_u64 v[150:151], s[24:25], 0, v[138:139]
	s_add_i32 m0, s33, 0xc000
	ds_read_b128 v[184:187], v155
	ds_read_b128 v[188:191], v155 offset:1024
	ds_read_b128 v[192:195], v155 offset:2048
	ds_read_b128 v[196:199], v155 offset:3072
	ds_read_b128 v[200:203], v155 offset:4096
	ds_read_b128 v[204:207], v155 offset:5120
	ds_read_b128 v[208:211], v155 offset:6144
	ds_read_b128 v[212:215], v155 offset:7168
	global_load_lds_dwordx4 v[150:151], off
	v_lshl_add_u64 v[150:151], s[24:25], 0, v[140:141]
	s_add_i32 m0, s33, 0xe000
	s_nop 0
	global_load_lds_dwordx4 v[150:151], off
	s_waitcnt vmcnt(8)
	s_waitcnt lgkmcnt(0)
	s_barrier
	s_waitcnt lgkmcnt(0)
	v_mfma_f32_16x16x32_bf16 v[124:127], v[146:149], v[184:187], 0
	v_mfma_f32_16x16x32_bf16 v[120:123], v[160:163], v[184:187], 0
	v_mfma_f32_16x16x32_bf16 v[108:111], v[146:149], v[192:195], 0
	v_mfma_f32_16x16x32_bf16 v[104:107], v[160:163], v[192:195], 0
	v_mfma_f32_16x16x32_bf16 v[92:95], v[146:149], v[200:203], 0
	v_mfma_f32_16x16x32_bf16 v[88:91], v[160:163], v[200:203], 0
	v_mfma_f32_16x16x32_bf16 v[76:79], v[146:149], v[208:211], 0
	v_mfma_f32_16x16x32_bf16 v[72:75], v[160:163], v[208:211], 0
	v_mfma_f32_16x16x32_bf16 v[124:127], v[156:159], v[188:191], v[124:127]
	v_mfma_f32_16x16x32_bf16 v[120:123], v[164:167], v[188:191], v[120:123]
	v_mfma_f32_16x16x32_bf16 v[108:111], v[156:159], v[196:199], v[108:111]
	v_mfma_f32_16x16x32_bf16 v[104:107], v[164:167], v[196:199], v[104:107]
	v_mfma_f32_16x16x32_bf16 v[92:95], v[156:159], v[204:207], v[92:95]
	v_mfma_f32_16x16x32_bf16 v[88:91], v[164:167], v[204:207], v[88:91]
	v_mfma_f32_16x16x32_bf16 v[76:79], v[156:159], v[212:215], v[76:79]
	v_mfma_f32_16x16x32_bf16 v[72:75], v[164:167], v[212:215], v[72:75]
	v_mfma_f32_16x16x32_bf16 v[116:119], v[168:171], v[184:187], 0
	v_mfma_f32_16x16x32_bf16 v[112:115], v[176:179], v[184:187], 0
	v_mfma_f32_16x16x32_bf16 v[100:103], v[168:171], v[192:195], 0
	v_mfma_f32_16x16x32_bf16 v[96:99], v[176:179], v[192:195], 0
	v_mfma_f32_16x16x32_bf16 v[84:87], v[168:171], v[200:203], 0
	v_mfma_f32_16x16x32_bf16 v[80:83], v[176:179], v[200:203], 0
	v_mfma_f32_16x16x32_bf16 v[68:71], v[168:171], v[208:211], 0
	v_mfma_f32_16x16x32_bf16 v[64:67], v[176:179], v[208:211], 0
	v_mfma_f32_16x16x32_bf16 v[116:119], v[172:175], v[188:191], v[116:119]
	v_mfma_f32_16x16x32_bf16 v[112:115], v[180:183], v[188:191], v[112:115]
	v_mfma_f32_16x16x32_bf16 v[100:103], v[172:175], v[196:199], v[100:103]
	v_mfma_f32_16x16x32_bf16 v[96:99], v[180:183], v[196:199], v[96:99]
	v_mfma_f32_16x16x32_bf16 v[84:87], v[172:175], v[204:207], v[84:87]
	v_mfma_f32_16x16x32_bf16 v[80:83], v[180:183], v[204:207], v[80:83]
	v_mfma_f32_16x16x32_bf16 v[68:71], v[172:175], v[212:215], v[68:71]
	v_mfma_f32_16x16x32_bf16 v[64:67], v[180:183], v[212:215], v[64:67]
	s_barrier
	s_add_i32 s56, s45, s31
	s_mov_b32 m0, s56
	ds_read_b128 v[184:187], v155 offset:16384
	ds_read_b128 v[188:191], v155 offset:17408
	ds_read_b128 v[192:195], v155 offset:18432
	ds_read_b128 v[196:199], v155 offset:19456
	ds_read_b128 v[200:203], v155 offset:20480
	ds_read_b128 v[204:207], v155 offset:21504
	ds_read_b128 v[208:211], v155 offset:22528
	ds_read_b128 v[212:215], v155 offset:23552
	global_load_lds_dwordx4 v130, s[26:27]
	s_add_i32 m0, s56, 0x2000
	s_add_u32 s56, s26, 0xb0000
	v_lshl_add_u64 v[216:217], s[26:27], 0, v[134:135]
	s_addc_u32 s57, s27, 0
	s_add_i32 s58, s46, s31
	global_load_lds_dwordx4 v134, s[26:27]
	s_mov_b32 m0, s58
	v_lshl_add_u64 v[220:221], s[28:29], 0, v[132:133]
	global_load_lds_dwordx4 v130, s[56:57]
	s_add_i32 m0, s58, 0x2000
	s_nop 0
	global_load_lds_dwordx4 v134, s[56:57]
	v_lshl_add_u64 v[218:219], s[28:29], 0, v[128:129]
	s_mov_b32 m0, s33
	s_nop 0
	global_load_lds_dwordx4 v128, s[28:29]
	s_mov_b32 m0, s36
	s_nop 0
	global_load_lds_dwordx4 v132, s[28:29]
	s_waitcnt vmcnt(8)
	s_waitcnt lgkmcnt(0)
	s_barrier
	s_waitcnt lgkmcnt(0)
	v_mfma_f32_16x16x32_bf16 v[60:63], v[146:149], v[184:187], 0
	v_mfma_f32_16x16x32_bf16 v[56:59], v[160:163], v[184:187], 0
	v_mfma_f32_16x16x32_bf16 v[44:47], v[146:149], v[192:195], 0
	v_mfma_f32_16x16x32_bf16 v[40:43], v[160:163], v[192:195], 0
	v_mfma_f32_16x16x32_bf16 v[28:31], v[146:149], v[200:203], 0
	v_mfma_f32_16x16x32_bf16 v[24:27], v[160:163], v[200:203], 0
	v_mfma_f32_16x16x32_bf16 v[12:15], v[146:149], v[208:211], 0
	v_mfma_f32_16x16x32_bf16 v[8:11], v[160:163], v[208:211], 0
	v_mfma_f32_16x16x32_bf16 v[60:63], v[156:159], v[188:191], v[60:63]
	v_mfma_f32_16x16x32_bf16 v[56:59], v[164:167], v[188:191], v[56:59]
	v_mfma_f32_16x16x32_bf16 v[44:47], v[156:159], v[196:199], v[44:47]
	v_mfma_f32_16x16x32_bf16 v[40:43], v[164:167], v[196:199], v[40:43]
	v_mfma_f32_16x16x32_bf16 v[28:31], v[156:159], v[204:207], v[28:31]
	v_mfma_f32_16x16x32_bf16 v[24:27], v[164:167], v[204:207], v[24:27]
	v_mfma_f32_16x16x32_bf16 v[12:15], v[156:159], v[212:215], v[12:15]
	v_mfma_f32_16x16x32_bf16 v[8:11], v[164:167], v[212:215], v[8:11]
	v_mfma_f32_16x16x32_bf16 v[52:55], v[168:171], v[184:187], 0
	v_mfma_f32_16x16x32_bf16 v[48:51], v[176:179], v[184:187], 0
	v_mfma_f32_16x16x32_bf16 v[36:39], v[168:171], v[192:195], 0
	v_mfma_f32_16x16x32_bf16 v[32:35], v[176:179], v[192:195], 0
	v_mfma_f32_16x16x32_bf16 v[20:23], v[168:171], v[200:203], 0
	v_mfma_f32_16x16x32_bf16 v[16:19], v[176:179], v[200:203], 0
	v_mfma_f32_16x16x32_bf16 v[4:7], v[168:171], v[208:211], 0
	v_mfma_f32_16x16x32_bf16 v[0:3], v[176:179], v[208:211], 0
	v_mfma_f32_16x16x32_bf16 v[52:55], v[172:175], v[188:191], v[52:55]
	v_mfma_f32_16x16x32_bf16 v[48:51], v[180:183], v[188:191], v[48:51]
	v_mfma_f32_16x16x32_bf16 v[36:39], v[172:175], v[196:199], v[36:39]
	v_mfma_f32_16x16x32_bf16 v[32:35], v[180:183], v[196:199], v[32:35]
	v_mfma_f32_16x16x32_bf16 v[20:23], v[172:175], v[204:207], v[20:23]
	v_mfma_f32_16x16x32_bf16 v[16:19], v[180:183], v[204:207], v[16:19]
	v_mfma_f32_16x16x32_bf16 v[4:7], v[172:175], v[212:215], v[4:7]
	v_mfma_f32_16x16x32_bf16 v[0:3], v[180:183], v[212:215], v[0:3]
	s_barrier
; #define PG8_STAGE(bufoff, gbase, voff) do { _Pragma("unroll") for (int _i = 0; _i < 2; ++_i) \
;         __builtin_amdgcn_global_load_lds((const unsigned*)((const char*)(gbase) + (voff)[_i]), (PG8_LAS unsigned*)(lds + (bufoff) + ldsw + _i * 8192), 16, 0, 0); } while (0)
; #define PG8_LDA(dst, b, h) do { _Pragma("unroll") for (int m = 0; m < 4; ++m) _Pragma("unroll") for (int k = 0; k < 2; ++k) dst[m][k] = *(const PG8_LAS bf16x8*)(lds + PG8_SA(b, h) + aoff + m * 2048 + k * 1024); } while (0)
; #define PG8_LDB(dst, b, h) do { _Pragma("unroll") for (int n = 0; n < 2; ++n) _Pragma("unroll") for (int k = 0; k < 2; ++k) dst[n][k] = *(const PG8_LAS bf16x8*)(lds + PG8_SB(b, h) + boff + n * 2048 + k * 1024); } while (0)
; #define PG8_MMA(ai, bj, At, Bt) do { __builtin_amdgcn_s_setprio(1); _Pragma("unroll") for (int m = 0; m < 4; ++m) _Pragma("unroll") for (int n = 0; n < 2; ++n) _Pragma("unroll") for (int k = 0; k < 2; ++k) \
;         acc[ai][bj][m][n] = __builtin_amdgcn_mfma_f32_16x16x32_bf16(Bt[n][k], At[m][k], acc[ai][bj][m][n], 0, 0, 0); __builtin_amdgcn_s_setprio(0); } while (0)
; #define PG8_WAIT_V(n) asm volatile("s_waitcnt vmcnt(" #n ")" ::: "memory")
; #define PG8_WAIT_L(n) asm volatile("s_waitcnt lgkmcnt(" #n ")" ::: "memory")
; #define PG8_BAR __builtin_amdgcn_s_barrier()
; #define PG8_SCHED __builtin_amdgcn_sched_barrier(0)
; template <class Epi, class Sched, bool ALIGN_EPI = false, bool SP2 = false>
; __device__ __forceinline__ void gemm_phase(PG8_LAS unsigned char* lds, const Gemm g, const Sched& S, const Epi& E) {
;     ...
;             PG8_LDB(B0, 1, 0); PG8_LDB(B1, 1, 1); PG8_SCHED; PG8_LDA(At, 1, 0); PG8_STAGE(PG8_SA(0, 1), a2 + hstep, voffA);
;             PG8_WAIT_V(8); PG8_WAIT_L(0); PG8_BAR; PG8_MMA(0, 0, At, B0); PG8_MMA(0, 1, At, B1); PG8_BAR; PG8_SCHED;
;             PG8_LDA(At, 1, 1); PG8_STAGE(PG8_SB(1, 0), b3, voffB); PG8_STAGE(PG8_SB(1, 1), b3 + hstep, voffB); PG8_STAGE(PG8_SA(1, 0), a3, voffA);
;             PG8_WAIT_V(8); PG8_WAIT_L(0); PG8_BAR; PG8_MMA(1, 0, At, B0); PG8_MMA(1, 1, At, B1); PG8_BAR; PG8_SCHED;
	s_add_i32 s56, 0, 0x18000
	s_add_i32 s57, 0, 0x1c000
	v_add_u32_e32 v164, s56, v152
	v_add_u32_e32 v180, s57, v152
	ds_read_b128 v[146:149], v164
	ds_read_b128 v[156:159], v164 offset:1024
	ds_read_b128 v[160:163], v164 offset:2048
	ds_read_b128 v[164:167], v164 offset:3072
	ds_read_b128 v[168:171], v180
	ds_read_b128 v[172:175], v180 offset:1024
	ds_read_b128 v[176:179], v180 offset:2048
	ds_read_b128 v[180:183], v180 offset:3072
	s_add_u32 s28, s28, 0xb0000
	s_addc_u32 s29, s29, 0
	s_mov_b32 m0, s37
	ds_read_b128 v[184:187], v155 offset:32768
	ds_read_b128 v[188:191], v155 offset:33792
	ds_read_b128 v[192:195], v155 offset:34816
	ds_read_b128 v[196:199], v155 offset:35840
	ds_read_b128 v[200:203], v155 offset:36864
	ds_read_b128 v[204:207], v155 offset:37888
	ds_read_b128 v[208:211], v155 offset:38912
	ds_read_b128 v[212:215], v155 offset:39936
	global_load_lds_dwordx4 v128, s[28:29]
	s_mov_b32 m0, s38
	s_nop 0
	global_load_lds_dwordx4 v132, s[28:29]
	s_waitcnt vmcnt(8)
	s_waitcnt lgkmcnt(0)
	s_barrier
	s_waitcnt lgkmcnt(0)
	v_mfma_f32_16x16x32_bf16 v[124:127], v[146:149], v[184:187], v[124:127]
	v_mfma_f32_16x16x32_bf16 v[120:123], v[160:163], v[184:187], v[120:123]
	v_mfma_f32_16x16x32_bf16 v[108:111], v[146:149], v[192:195], v[108:111]
	v_mfma_f32_16x16x32_bf16 v[104:107], v[160:163], v[192:195], v[104:107]
	v_mfma_f32_16x16x32_bf16 v[92:95], v[146:149], v[200:203], v[92:95]
	v_mfma_f32_16x16x32_bf16 v[88:91], v[160:163], v[200:203], v[88:91]
	v_mfma_f32_16x16x32_bf16 v[76:79], v[146:149], v[208:211], v[76:79]
	v_mfma_f32_16x16x32_bf16 v[72:75], v[160:163], v[208:211], v[72:75]
	v_mfma_f32_16x16x32_bf16 v[124:127], v[156:159], v[188:191], v[124:127]
	v_mfma_f32_16x16x32_bf16 v[120:123], v[164:167], v[188:191], v[120:123]
	v_mfma_f32_16x16x32_bf16 v[108:111], v[156:159], v[196:199], v[108:111]
	v_mfma_f32_16x16x32_bf16 v[104:107], v[164:167], v[196:199], v[104:107]
	v_mfma_f32_16x16x32_bf16 v[92:95], v[156:159], v[204:207], v[92:95]
	v_mfma_f32_16x16x32_bf16 v[88:91], v[164:167], v[204:207], v[88:91]
	v_mfma_f32_16x16x32_bf16 v[76:79], v[156:159], v[212:215], v[76:79]
	v_mfma_f32_16x16x32_bf16 v[72:75], v[164:167], v[212:215], v[72:75]
	v_mfma_f32_16x16x32_bf16 v[116:119], v[168:171], v[184:187], v[116:119]
	v_mfma_f32_16x16x32_bf16 v[112:115], v[176:179], v[184:187], v[112:115]
	v_mfma_f32_16x16x32_bf16 v[100:103], v[168:171], v[192:195], v[100:103]
	v_mfma_f32_16x16x32_bf16 v[96:99], v[176:179], v[192:195], v[96:99]
	v_mfma_f32_16x16x32_bf16 v[84:87], v[168:171], v[200:203], v[84:87]
	v_mfma_f32_16x16x32_bf16 v[80:83], v[176:179], v[200:203], v[80:83]
	v_mfma_f32_16x16x32_bf16 v[68:71], v[168:171], v[208:211], v[68:71]
	v_mfma_f32_16x16x32_bf16 v[64:67], v[176:179], v[208:211], v[64:67]
	v_mfma_f32_16x16x32_bf16 v[116:119], v[172:175], v[188:191], v[116:119]
	v_mfma_f32_16x16x32_bf16 v[112:115], v[180:183], v[188:191], v[112:115]
	v_mfma_f32_16x16x32_bf16 v[100:103], v[172:175], v[196:199], v[100:103]
	v_mfma_f32_16x16x32_bf16 v[96:99], v[180:183], v[196:199], v[96:99]
	v_mfma_f32_16x16x32_bf16 v[84:87], v[172:175], v[204:207], v[84:87]
	v_mfma_f32_16x16x32_bf16 v[80:83], v[180:183], v[204:207], v[80:83]
	v_mfma_f32_16x16x32_bf16 v[68:71], v[172:175], v[212:215], v[68:71]
	v_mfma_f32_16x16x32_bf16 v[64:67], v[180:183], v[212:215], v[64:67]
	s_barrier
	s_add_i32 s28, s56, s31
	s_mov_b32 m0, s28
	ds_read_b128 v[184:187], v155 offset:49152
	ds_read_b128 v[188:191], v155 offset:50176
	ds_read_b128 v[192:195], v155 offset:51200
	ds_read_b128 v[196:199], v155 offset:52224
	ds_read_b128 v[200:203], v155 offset:53248
	ds_read_b128 v[204:207], v155 offset:54272
	ds_read_b128 v[208:211], v155 offset:55296
	ds_read_b128 v[212:215], v155 offset:56320
	s_add_u32 s98, s26, s10
	s_addc_u32 s99, s27, s11
	global_load_lds_dwordx4 v130, s[98:99]
	s_add_i32 m0, s28, 0x2000
	s_add_u32 s26, s26, 0xb0080
	v_lshl_add_u64 v[150:151], v[216:217], 0, s[10:11]
	s_addc_u32 s27, s27, 0
	s_add_i32 s28, s57, s31
	global_load_lds_dwordx4 v[150:151], off
	s_mov_b32 m0, s28
	s_nop 0
	global_load_lds_dwordx4 v130, s[26:27]
	s_add_i32 m0, s28, 0x2000
	s_nop 0
	global_load_lds_dwordx4 v134, s[26:27]
	v_lshl_add_u64 v[150:151], v[218:219], 0, s[10:11]
	s_mov_b32 m0, s40
	s_nop 0
	global_load_lds_dwordx4 v[150:151], off
	v_lshl_add_u64 v[150:151], v[220:221], 0, s[10:11]
	s_mov_b32 m0, s41
	s_nop 0
	global_load_lds_dwordx4 v[150:151], off
	s_waitcnt vmcnt(8)
	s_waitcnt lgkmcnt(0)
	s_barrier
	s_waitcnt lgkmcnt(0)
	v_mfma_f32_16x16x32_bf16 v[60:63], v[146:149], v[184:187], v[60:63]
	v_mfma_f32_16x16x32_bf16 v[56:59], v[160:163], v[184:187], v[56:59]
	v_mfma_f32_16x16x32_bf16 v[44:47], v[146:149], v[192:195], v[44:47]
	v_mfma_f32_16x16x32_bf16 v[40:43], v[160:163], v[192:195], v[40:43]
	v_mfma_f32_16x16x32_bf16 v[28:31], v[146:149], v[200:203], v[28:31]
	v_mfma_f32_16x16x32_bf16 v[24:27], v[160:163], v[200:203], v[24:27]
	v_mfma_f32_16x16x32_bf16 v[12:15], v[146:149], v[208:211], v[12:15]
	v_mfma_f32_16x16x32_bf16 v[8:11], v[160:163], v[208:211], v[8:11]
	v_mfma_f32_16x16x32_bf16 v[60:63], v[156:159], v[188:191], v[60:63]
	v_mfma_f32_16x16x32_bf16 v[56:59], v[164:167], v[188:191], v[56:59]
	v_mfma_f32_16x16x32_bf16 v[44:47], v[156:159], v[196:199], v[44:47]
	v_mfma_f32_16x16x32_bf16 v[40:43], v[164:167], v[196:199], v[40:43]
	v_mfma_f32_16x16x32_bf16 v[28:31], v[156:159], v[204:207], v[28:31]
	v_mfma_f32_16x16x32_bf16 v[24:27], v[164:167], v[204:207], v[24:27]
	v_mfma_f32_16x16x32_bf16 v[12:15], v[156:159], v[212:215], v[12:15]
	v_mfma_f32_16x16x32_bf16 v[8:11], v[164:167], v[212:215], v[8:11]
	v_mfma_f32_16x16x32_bf16 v[52:55], v[168:171], v[184:187], v[52:55]
	v_mfma_f32_16x16x32_bf16 v[48:51], v[176:179], v[184:187], v[48:51]
	v_mfma_f32_16x16x32_bf16 v[36:39], v[168:171], v[192:195], v[36:39]
	v_mfma_f32_16x16x32_bf16 v[32:35], v[176:179], v[192:195], v[32:35]
	v_mfma_f32_16x16x32_bf16 v[20:23], v[168:171], v[200:203], v[20:23]
	v_mfma_f32_16x16x32_bf16 v[16:19], v[176:179], v[200:203], v[16:19]
	v_mfma_f32_16x16x32_bf16 v[4:7], v[168:171], v[208:211], v[4:7]
	v_mfma_f32_16x16x32_bf16 v[0:3], v[176:179], v[208:211], v[0:3]
	v_mfma_f32_16x16x32_bf16 v[52:55], v[172:175], v[188:191], v[52:55]
	v_mfma_f32_16x16x32_bf16 v[48:51], v[180:183], v[188:191], v[48:51]
	v_mfma_f32_16x16x32_bf16 v[36:39], v[172:175], v[196:199], v[36:39]
	v_mfma_f32_16x16x32_bf16 v[32:35], v[180:183], v[196:199], v[32:35]
	v_mfma_f32_16x16x32_bf16 v[20:23], v[172:175], v[204:207], v[20:23]
	v_mfma_f32_16x16x32_bf16 v[16:19], v[180:183], v[204:207], v[16:19]
	v_mfma_f32_16x16x32_bf16 v[4:7], v[172:175], v[212:215], v[4:7]
	v_mfma_f32_16x16x32_bf16 v[0:3], v[180:183], v[212:215], v[0:3]
	s_add_i32 s53, s53, 2
	s_add_u32 s24, s24, 0x100
	s_addc_u32 s25, s25, 0
	s_add_u32 s51, s51, 0x100
	s_addc_u32 s52, s52, 0
	s_cmp_gt_u32 s53, 41
	s_barrier
; #define PG8_STAGE(bufoff, gbase, voff) do { _Pragma("unroll") for (int _i = 0; _i < 2; ++_i) \
;         __builtin_amdgcn_global_load_lds((const unsigned*)((const char*)(gbase) + (voff)[_i]), (PG8_LAS unsigned*)(lds + (bufoff) + ldsw + _i * 8192), 16, 0, 0); } while (0)
; #define PG8_LDA(dst, b, h) do { _Pragma("unroll") for (int m = 0; m < 4; ++m) _Pragma("unroll") for (int k = 0; k < 2; ++k) dst[m][k] = *(const PG8_LAS bf16x8*)(lds + PG8_SA(b, h) + aoff + m * 2048 + k * 1024); } while (0)
; #define PG8_LDB(dst, b, h) do { _Pragma("unroll") for (int n = 0; n < 2; ++n) _Pragma("unroll") for (int k = 0; k < 2; ++k) dst[n][k] = *(const PG8_LAS bf16x8*)(lds + PG8_SB(b, h) + boff + n * 2048 + k * 1024); } while (0)
; #define PG8_MMA(ai, bj, At, Bt) do { __builtin_amdgcn_s_setprio(1); _Pragma("unroll") for (int m = 0; m < 4; ++m) _Pragma("unroll") for (int n = 0; n < 2; ++n) _Pragma("unroll") for (int k = 0; k < 2; ++k) \
;         acc[ai][bj][m][n] = __builtin_amdgcn_mfma_f32_16x16x32_bf16(Bt[n][k], At[m][k], acc[ai][bj][m][n], 0, 0, 0); __builtin_amdgcn_s_setprio(0); } while (0)
; #define PG8_WAIT_V(n) asm volatile("s_waitcnt vmcnt(" #n ")" ::: "memory")
; #define PG8_WAIT_L(n) asm volatile("s_waitcnt lgkmcnt(" #n ")" ::: "memory")
; #define PG8_BAR __builtin_amdgcn_s_barrier()
; #define PG8_SCHED __builtin_amdgcn_sched_barrier(0)
; template <class Epi, class Sched, bool ALIGN_EPI = false, bool SP2 = false>
; __device__ __forceinline__ void gemm_phase(PG8_LAS unsigned char* lds, const Gemm g, const Sched& S, const Epi& E) {
;     ...
;             PG8_LDB(B0, 0, 0); PG8_LDB(B1, 0, 1); PG8_SCHED; PG8_LDA(At, 0, 0); PG8_STAGE(PG8_SA(1, 1), a1 + hstep, voffA);
;             PG8_WAIT_V(8); PG8_WAIT_L(0); PG8_BAR; PG8_MMA(0, 0, At, B0); PG8_MMA(0, 1, At, B1); PG8_BAR; PG8_SCHED;
;             PG8_LDA(At, 0, 1); PG8_STAGE(PG8_SB(0, 0), b2, voffB); PG8_STAGE(PG8_SB(0, 1), b2 + hstep, voffB); PG8_STAGE(PG8_SA(0, 0), a2, voffA);
;             PG8_WAIT_V(8); PG8_WAIT_L(0); PG8_BAR; PG8_MMA(1, 0, At, B0); PG8_MMA(1, 1, At, B1); PG8_BAR; PG8_SCHED;
.LBB0_861:
	ds_read_b128 v[146:149], v153
	ds_read_b128 v[156:159], v153 offset:1024
	ds_read_b128 v[160:163], v153 offset:2048
	ds_read_b128 v[164:167], v153 offset:3072
	ds_read_b128 v[168:171], v154
	ds_read_b128 v[172:175], v154 offset:1024
	ds_read_b128 v[176:179], v154 offset:2048
	ds_read_b128 v[180:183], v154 offset:3072
	s_add_u32 s26, s24, 0xfff50080
	s_addc_u32 s27, s25, -1
	s_cmp_eq_u32 s53, 40
	s_cselect_b32 s29, s5, s27
	s_cselect_b32 s28, s4, s26
	s_cselect_b32 s27, s23, s52
	s_cselect_b32 s26, s22, s51
	v_lshl_add_u64 v[150:151], s[24:25], 0, v[138:139]
	s_add_i32 m0, s33, 0xc000
	ds_read_b128 v[184:187], v155
	ds_read_b128 v[188:191], v155 offset:1024
	ds_read_b128 v[192:195], v155 offset:2048
	ds_read_b128 v[196:199], v155 offset:3072
	ds_read_b128 v[200:203], v155 offset:4096
	ds_read_b128 v[204:207], v155 offset:5120
	ds_read_b128 v[208:211], v155 offset:6144
	ds_read_b128 v[212:215], v155 offset:7168
	global_load_lds_dwordx4 v[150:151], off
	v_lshl_add_u64 v[150:151], s[24:25], 0, v[140:141]
	s_add_i32 m0, s33, 0xe000
	s_nop 0
	global_load_lds_dwordx4 v[150:151], off
	s_waitcnt vmcnt(8)
	s_waitcnt lgkmcnt(0)
	s_barrier
	s_waitcnt lgkmcnt(0)
	v_mfma_f32_16x16x32_bf16 v[124:127], v[146:149], v[184:187], v[124:127]
	v_mfma_f32_16x16x32_bf16 v[120:123], v[160:163], v[184:187], v[120:123]
	v_mfma_f32_16x16x32_bf16 v[108:111], v[146:149], v[192:195], v[108:111]
	v_mfma_f32_16x16x32_bf16 v[104:107], v[160:163], v[192:195], v[104:107]
	v_mfma_f32_16x16x32_bf16 v[92:95], v[146:149], v[200:203], v[92:95]
	v_mfma_f32_16x16x32_bf16 v[88:91], v[160:163], v[200:203], v[88:91]
	v_mfma_f32_16x16x32_bf16 v[76:79], v[146:149], v[208:211], v[76:79]
	v_mfma_f32_16x16x32_bf16 v[72:75], v[160:163], v[208:211], v[72:75]
	v_mfma_f32_16x16x32_bf16 v[124:127], v[156:159], v[188:191], v[124:127]
	v_mfma_f32_16x16x32_bf16 v[120:123], v[164:167], v[188:191], v[120:123]
	v_mfma_f32_16x16x32_bf16 v[108:111], v[156:159], v[196:199], v[108:111]
	v_mfma_f32_16x16x32_bf16 v[104:107], v[164:167], v[196:199], v[104:107]
	v_mfma_f32_16x16x32_bf16 v[92:95], v[156:159], v[204:207], v[92:95]
	v_mfma_f32_16x16x32_bf16 v[88:91], v[164:167], v[204:207], v[88:91]
	v_mfma_f32_16x16x32_bf16 v[76:79], v[156:159], v[212:215], v[76:79]
	v_mfma_f32_16x16x32_bf16 v[72:75], v[164:167], v[212:215], v[72:75]
	v_mfma_f32_16x16x32_bf16 v[116:119], v[168:171], v[184:187], v[116:119]
	v_mfma_f32_16x16x32_bf16 v[112:115], v[176:179], v[184:187], v[112:115]
	v_mfma_f32_16x16x32_bf16 v[100:103], v[168:171], v[192:195], v[100:103]
	v_mfma_f32_16x16x32_bf16 v[96:99], v[176:179], v[192:195], v[96:99]
	v_mfma_f32_16x16x32_bf16 v[84:87], v[168:171], v[200:203], v[84:87]
	v_mfma_f32_16x16x32_bf16 v[80:83], v[176:179], v[200:203], v[80:83]
	v_mfma_f32_16x16x32_bf16 v[68:71], v[168:171], v[208:211], v[68:71]
	v_mfma_f32_16x16x32_bf16 v[64:67], v[176:179], v[208:211], v[64:67]
	v_mfma_f32_16x16x32_bf16 v[116:119], v[172:175], v[188:191], v[116:119]
	v_mfma_f32_16x16x32_bf16 v[112:115], v[180:183], v[188:191], v[112:115]
	v_mfma_f32_16x16x32_bf16 v[100:103], v[172:175], v[196:199], v[100:103]
	v_mfma_f32_16x16x32_bf16 v[96:99], v[180:183], v[196:199], v[96:99]
	v_mfma_f32_16x16x32_bf16 v[84:87], v[172:175], v[204:207], v[84:87]
	v_mfma_f32_16x16x32_bf16 v[80:83], v[180:183], v[204:207], v[80:83]
	v_mfma_f32_16x16x32_bf16 v[68:71], v[172:175], v[212:215], v[68:71]
	v_mfma_f32_16x16x32_bf16 v[64:67], v[180:183], v[212:215], v[64:67]
	s_barrier
	s_add_i32 s56, s45, s31
	s_mov_b32 m0, s56
	ds_read_b128 v[184:187], v155 offset:16384
	ds_read_b128 v[188:191], v155 offset:17408
	ds_read_b128 v[192:195], v155 offset:18432
	ds_read_b128 v[196:199], v155 offset:19456
	ds_read_b128 v[200:203], v155 offset:20480
	ds_read_b128 v[204:207], v155 offset:21504
	ds_read_b128 v[208:211], v155 offset:22528
	ds_read_b128 v[212:215], v155 offset:23552
	global_load_lds_dwordx4 v130, s[26:27]
	s_add_i32 m0, s56, 0x2000
	s_add_u32 s56, s26, 0xb0000
	v_lshl_add_u64 v[216:217], s[26:27], 0, v[134:135]
	s_addc_u32 s57, s27, 0
	s_add_i32 s58, s46, s31
	global_load_lds_dwordx4 v134, s[26:27]
	s_mov_b32 m0, s58
	v_lshl_add_u64 v[220:221], s[28:29], 0, v[132:133]
	global_load_lds_dwordx4 v130, s[56:57]
	s_add_i32 m0, s58, 0x2000
	s_nop 0
	global_load_lds_dwordx4 v134, s[56:57]
	v_lshl_add_u64 v[218:219], s[28:29], 0, v[128:129]
	s_mov_b32 m0, s33
	s_nop 0
	global_load_lds_dwordx4 v128, s[28:29]
	s_mov_b32 m0, s36
	s_nop 0
	global_load_lds_dwordx4 v132, s[28:29]
	s_waitcnt vmcnt(8)
	s_waitcnt lgkmcnt(0)
	s_barrier
	s_waitcnt lgkmcnt(0)
	v_mfma_f32_16x16x32_bf16 v[60:63], v[146:149], v[184:187], v[60:63]
	v_mfma_f32_16x16x32_bf16 v[56:59], v[160:163], v[184:187], v[56:59]
	v_mfma_f32_16x16x32_bf16 v[44:47], v[146:149], v[192:195], v[44:47]
	v_mfma_f32_16x16x32_bf16 v[40:43], v[160:163], v[192:195], v[40:43]
	v_mfma_f32_16x16x32_bf16 v[28:31], v[146:149], v[200:203], v[28:31]
	v_mfma_f32_16x16x32_bf16 v[24:27], v[160:163], v[200:203], v[24:27]
	v_mfma_f32_16x16x32_bf16 v[12:15], v[146:149], v[208:211], v[12:15]
	v_mfma_f32_16x16x32_bf16 v[8:11], v[160:163], v[208:211], v[8:11]
	v_mfma_f32_16x16x32_bf16 v[60:63], v[156:159], v[188:191], v[60:63]
	v_mfma_f32_16x16x32_bf16 v[56:59], v[164:167], v[188:191], v[56:59]
	v_mfma_f32_16x16x32_bf16 v[44:47], v[156:159], v[196:199], v[44:47]
	v_mfma_f32_16x16x32_bf16 v[40:43], v[164:167], v[196:199], v[40:43]
	v_mfma_f32_16x16x32_bf16 v[28:31], v[156:159], v[204:207], v[28:31]
	v_mfma_f32_16x16x32_bf16 v[24:27], v[164:167], v[204:207], v[24:27]
	v_mfma_f32_16x16x32_bf16 v[12:15], v[156:159], v[212:215], v[12:15]
	v_mfma_f32_16x16x32_bf16 v[8:11], v[164:167], v[212:215], v[8:11]
	v_mfma_f32_16x16x32_bf16 v[52:55], v[168:171], v[184:187], v[52:55]
	v_mfma_f32_16x16x32_bf16 v[48:51], v[176:179], v[184:187], v[48:51]
	v_mfma_f32_16x16x32_bf16 v[36:39], v[168:171], v[192:195], v[36:39]
	v_mfma_f32_16x16x32_bf16 v[32:35], v[176:179], v[192:195], v[32:35]
	v_mfma_f32_16x16x32_bf16 v[20:23], v[168:171], v[200:203], v[20:23]
	v_mfma_f32_16x16x32_bf16 v[16:19], v[176:179], v[200:203], v[16:19]
	v_mfma_f32_16x16x32_bf16 v[4:7], v[168:171], v[208:211], v[4:7]
	v_mfma_f32_16x16x32_bf16 v[0:3], v[176:179], v[208:211], v[0:3]
	v_mfma_f32_16x16x32_bf16 v[52:55], v[172:175], v[188:191], v[52:55]
	v_mfma_f32_16x16x32_bf16 v[48:51], v[180:183], v[188:191], v[48:51]
	v_mfma_f32_16x16x32_bf16 v[36:39], v[172:175], v[196:199], v[36:39]
	v_mfma_f32_16x16x32_bf16 v[32:35], v[180:183], v[196:199], v[32:35]
	v_mfma_f32_16x16x32_bf16 v[20:23], v[172:175], v[204:207], v[20:23]
	v_mfma_f32_16x16x32_bf16 v[16:19], v[180:183], v[204:207], v[16:19]
	v_mfma_f32_16x16x32_bf16 v[4:7], v[172:175], v[212:215], v[4:7]
	v_mfma_f32_16x16x32_bf16 v[0:3], v[180:183], v[212:215], v[0:3]
	s_barrier
; #define PG8_STAGE(bufoff, gbase, voff) do { _Pragma("unroll") for (int _i = 0; _i < 2; ++_i) \
;         __builtin_amdgcn_global_load_lds((const unsigned*)((const char*)(gbase) + (voff)[_i]), (PG8_LAS unsigned*)(lds + (bufoff) + ldsw + _i * 8192), 16, 0, 0); } while (0)
; #define PG8_LDA(dst, b, h) do { _Pragma("unroll") for (int m = 0; m < 4; ++m) _Pragma("unroll") for (int k = 0; k < 2; ++k) dst[m][k] = *(const PG8_LAS bf16x8*)(lds + PG8_SA(b, h) + aoff + m * 2048 + k * 1024); } while (0)
; #define PG8_LDB(dst, b, h) do { _Pragma("unroll") for (int n = 0; n < 2; ++n) _Pragma("unroll") for (int k = 0; k < 2; ++k) dst[n][k] = *(const PG8_LAS bf16x8*)(lds + PG8_SB(b, h) + boff + n * 2048 + k * 1024); } while (0)
; #define PG8_MMA(ai, bj, At, Bt) do { __builtin_amdgcn_s_setprio(1); _Pragma("unroll") for (int m = 0; m < 4; ++m) _Pragma("unroll") for (int n = 0; n < 2; ++n) _Pragma("unroll") for (int k = 0; k < 2; ++k) \
;         acc[ai][bj][m][n] = __builtin_amdgcn_mfma_f32_16x16x32_bf16(Bt[n][k], At[m][k], acc[ai][bj][m][n], 0, 0, 0); __builtin_amdgcn_s_setprio(0); } while (0)
; #define PG8_WAIT_V(n) asm volatile("s_waitcnt vmcnt(" #n ")" ::: "memory")
; #define PG8_WAIT_L(n) asm volatile("s_waitcnt lgkmcnt(" #n ")" ::: "memory")
; #define PG8_BAR __builtin_amdgcn_s_barrier()
; #define PG8_SCHED __builtin_amdgcn_sched_barrier(0)
; template <class Epi, class Sched, bool ALIGN_EPI = false, bool SP2 = false>
; __device__ __forceinline__ void gemm_phase(PG8_LAS unsigned char* lds, const Gemm g, const Sched& S, const Epi& E) {
;     ...
;             PG8_LDB(B0, 1, 0); PG8_LDB(B1, 1, 1); PG8_SCHED; PG8_LDA(At, 1, 0); PG8_STAGE(PG8_SA(0, 1), a2 + hstep, voffA);
;             PG8_WAIT_V(8); PG8_WAIT_L(0); PG8_BAR; PG8_MMA(0, 0, At, B0); PG8_MMA(0, 1, At, B1); PG8_BAR; PG8_SCHED;
;             PG8_LDA(At, 1, 1); PG8_STAGE(PG8_SB(1, 0), b3, voffB); PG8_STAGE(PG8_SB(1, 1), b3 + hstep, voffB); PG8_STAGE(PG8_SA(1, 0), a3, voffA);
;             PG8_WAIT_V(8); PG8_WAIT_L(0); PG8_BAR; PG8_MMA(1, 0, At, B0); PG8_MMA(1, 1, At, B1); PG8_BAR; PG8_SCHED;
	s_add_i32 s56, 0, 0x18000
	s_add_i32 s57, 0, 0x1c000
	v_add_u32_e32 v164, s56, v152
	v_add_u32_e32 v180, s57, v152
	ds_read_b128 v[146:149], v164
	ds_read_b128 v[156:159], v164 offset:1024
	ds_read_b128 v[160:163], v164 offset:2048
	ds_read_b128 v[164:167], v164 offset:3072
	ds_read_b128 v[168:171], v180
	ds_read_b128 v[172:175], v180 offset:1024
	ds_read_b128 v[176:179], v180 offset:2048
	ds_read_b128 v[180:183], v180 offset:3072
	s_add_u32 s28, s28, 0xb0000
	s_addc_u32 s29, s29, 0
	s_mov_b32 m0, s37
	ds_read_b128 v[184:187], v155 offset:32768
	ds_read_b128 v[188:191], v155 offset:33792
	ds_read_b128 v[192:195], v155 offset:34816
	ds_read_b128 v[196:199], v155 offset:35840
	ds_read_b128 v[200:203], v155 offset:36864
	ds_read_b128 v[204:207], v155 offset:37888
	ds_read_b128 v[208:211], v155 offset:38912
	ds_read_b128 v[212:215], v155 offset:39936
	global_load_lds_dwordx4 v128, s[28:29]
	s_mov_b32 m0, s38
	s_nop 0
	global_load_lds_dwordx4 v132, s[28:29]
	s_waitcnt vmcnt(8)
	s_waitcnt lgkmcnt(0)
	s_barrier
	s_waitcnt lgkmcnt(0)
	v_mfma_f32_16x16x32_bf16 v[124:127], v[146:149], v[184:187], v[124:127]
	v_mfma_f32_16x16x32_bf16 v[120:123], v[160:163], v[184:187], v[120:123]
	v_mfma_f32_16x16x32_bf16 v[108:111], v[146:149], v[192:195], v[108:111]
	v_mfma_f32_16x16x32_bf16 v[104:107], v[160:163], v[192:195], v[104:107]
	v_mfma_f32_16x16x32_bf16 v[92:95], v[146:149], v[200:203], v[92:95]
	v_mfma_f32_16x16x32_bf16 v[88:91], v[160:163], v[200:203], v[88:91]
	v_mfma_f32_16x16x32_bf16 v[76:79], v[146:149], v[208:211], v[76:79]
	v_mfma_f32_16x16x32_bf16 v[72:75], v[160:163], v[208:211], v[72:75]
	v_mfma_f32_16x16x32_bf16 v[124:127], v[156:159], v[188:191], v[124:127]
	v_mfma_f32_16x16x32_bf16 v[120:123], v[164:167], v[188:191], v[120:123]
	v_mfma_f32_16x16x32_bf16 v[108:111], v[156:159], v[196:199], v[108:111]
	v_mfma_f32_16x16x32_bf16 v[104:107], v[164:167], v[196:199], v[104:107]
	v_mfma_f32_16x16x32_bf16 v[92:95], v[156:159], v[204:207], v[92:95]
	v_mfma_f32_16x16x32_bf16 v[88:91], v[164:167], v[204:207], v[88:91]
	v_mfma_f32_16x16x32_bf16 v[76:79], v[156:159], v[212:215], v[76:79]
	v_mfma_f32_16x16x32_bf16 v[72:75], v[164:167], v[212:215], v[72:75]
	v_mfma_f32_16x16x32_bf16 v[116:119], v[168:171], v[184:187], v[116:119]
	v_mfma_f32_16x16x32_bf16 v[112:115], v[176:179], v[184:187], v[112:115]
	v_mfma_f32_16x16x32_bf16 v[100:103], v[168:171], v[192:195], v[100:103]
	v_mfma_f32_16x16x32_bf16 v[96:99], v[176:179], v[192:195], v[96:99]
	v_mfma_f32_16x16x32_bf16 v[84:87], v[168:171], v[200:203], v[84:87]
	v_mfma_f32_16x16x32_bf16 v[80:83], v[176:179], v[200:203], v[80:83]
	v_mfma_f32_16x16x32_bf16 v[68:71], v[168:171], v[208:211], v[68:71]
	v_mfma_f32_16x16x32_bf16 v[64:67], v[176:179], v[208:211], v[64:67]
	v_mfma_f32_16x16x32_bf16 v[116:119], v[172:175], v[188:191], v[116:119]
	v_mfma_f32_16x16x32_bf16 v[112:115], v[180:183], v[188:191], v[112:115]
	v_mfma_f32_16x16x32_bf16 v[100:103], v[172:175], v[196:199], v[100:103]
	v_mfma_f32_16x16x32_bf16 v[96:99], v[180:183], v[196:199], v[96:99]
	v_mfma_f32_16x16x32_bf16 v[84:87], v[172:175], v[204:207], v[84:87]
	v_mfma_f32_16x16x32_bf16 v[80:83], v[180:183], v[204:207], v[80:83]
	v_mfma_f32_16x16x32_bf16 v[68:71], v[172:175], v[212:215], v[68:71]
	v_mfma_f32_16x16x32_bf16 v[64:67], v[180:183], v[212:215], v[64:67]
	s_barrier
	s_add_i32 s28, s56, s31
	s_mov_b32 m0, s28
	ds_read_b128 v[184:187], v155 offset:49152
	ds_read_b128 v[188:191], v155 offset:50176
	ds_read_b128 v[192:195], v155 offset:51200
	ds_read_b128 v[196:199], v155 offset:52224
	ds_read_b128 v[200:203], v155 offset:53248
	ds_read_b128 v[204:207], v155 offset:54272
	ds_read_b128 v[208:211], v155 offset:55296
	ds_read_b128 v[212:215], v155 offset:56320
	s_add_u32 s98, s26, s10
	s_addc_u32 s99, s27, s11
	global_load_lds_dwordx4 v130, s[98:99]
	s_add_i32 m0, s28, 0x2000
	s_add_u32 s26, s26, 0xb0080
	v_lshl_add_u64 v[150:151], v[216:217], 0, s[10:11]
	s_addc_u32 s27, s27, 0
	s_add_i32 s28, s57, s31
	global_load_lds_dwordx4 v[150:151], off
	s_mov_b32 m0, s28
	s_nop 0
	global_load_lds_dwordx4 v130, s[26:27]
	s_add_i32 m0, s28, 0x2000
	s_nop 0
	global_load_lds_dwordx4 v134, s[26:27]
	v_lshl_add_u64 v[150:151], v[218:219], 0, s[10:11]
	s_mov_b32 m0, s40
	s_nop 0
	global_load_lds_dwordx4 v[150:151], off
	v_lshl_add_u64 v[150:151], v[220:221], 0, s[10:11]
	s_mov_b32 m0, s41
	s_nop 0
	global_load_lds_dwordx4 v[150:151], off
	s_waitcnt vmcnt(8)
	s_waitcnt lgkmcnt(0)
	s_barrier
	s_waitcnt lgkmcnt(0)
	v_mfma_f32_16x16x32_bf16 v[60:63], v[146:149], v[184:187], v[60:63]
	v_mfma_f32_16x16x32_bf16 v[56:59], v[160:163], v[184:187], v[56:59]
	v_mfma_f32_16x16x32_bf16 v[44:47], v[146:149], v[192:195], v[44:47]
	v_mfma_f32_16x16x32_bf16 v[40:43], v[160:163], v[192:195], v[40:43]
	v_mfma_f32_16x16x32_bf16 v[28:31], v[146:149], v[200:203], v[28:31]
	v_mfma_f32_16x16x32_bf16 v[24:27], v[160:163], v[200:203], v[24:27]
	v_mfma_f32_16x16x32_bf16 v[12:15], v[146:149], v[208:211], v[12:15]
	v_mfma_f32_16x16x32_bf16 v[8:11], v[160:163], v[208:211], v[8:11]
	v_mfma_f32_16x16x32_bf16 v[60:63], v[156:159], v[188:191], v[60:63]
	v_mfma_f32_16x16x32_bf16 v[56:59], v[164:167], v[188:191], v[56:59]
	v_mfma_f32_16x16x32_bf16 v[44:47], v[156:159], v[196:199], v[44:47]
	v_mfma_f32_16x16x32_bf16 v[40:43], v[164:167], v[196:199], v[40:43]
	v_mfma_f32_16x16x32_bf16 v[28:31], v[156:159], v[204:207], v[28:31]
	v_mfma_f32_16x16x32_bf16 v[24:27], v[164:167], v[204:207], v[24:27]
	v_mfma_f32_16x16x32_bf16 v[12:15], v[156:159], v[212:215], v[12:15]
	v_mfma_f32_16x16x32_bf16 v[8:11], v[164:167], v[212:215], v[8:11]
	v_mfma_f32_16x16x32_bf16 v[52:55], v[168:171], v[184:187], v[52:55]
	v_mfma_f32_16x16x32_bf16 v[48:51], v[176:179], v[184:187], v[48:51]
	v_mfma_f32_16x16x32_bf16 v[36:39], v[168:171], v[192:195], v[36:39]
	v_mfma_f32_16x16x32_bf16 v[32:35], v[176:179], v[192:195], v[32:35]
	v_mfma_f32_16x16x32_bf16 v[20:23], v[168:171], v[200:203], v[20:23]
	v_mfma_f32_16x16x32_bf16 v[16:19], v[176:179], v[200:203], v[16:19]
	v_mfma_f32_16x16x32_bf16 v[4:7], v[168:171], v[208:211], v[4:7]
	v_mfma_f32_16x16x32_bf16 v[0:3], v[176:179], v[208:211], v[0:3]
	v_mfma_f32_16x16x32_bf16 v[52:55], v[172:175], v[188:191], v[52:55]
	v_mfma_f32_16x16x32_bf16 v[48:51], v[180:183], v[188:191], v[48:51]
	v_mfma_f32_16x16x32_bf16 v[36:39], v[172:175], v[196:199], v[36:39]
	v_mfma_f32_16x16x32_bf16 v[32:35], v[180:183], v[196:199], v[32:35]
	v_mfma_f32_16x16x32_bf16 v[20:23], v[172:175], v[204:207], v[20:23]
	v_mfma_f32_16x16x32_bf16 v[16:19], v[180:183], v[204:207], v[16:19]
	v_mfma_f32_16x16x32_bf16 v[4:7], v[172:175], v[212:215], v[4:7]
	v_mfma_f32_16x16x32_bf16 v[0:3], v[180:183], v[212:215], v[0:3]
	s_add_i32 s53, s53, 2
	s_add_u32 s24, s24, 0x100
	s_addc_u32 s25, s25, 0
	s_add_u32 s51, s51, 0x100
	s_addc_u32 s52, s52, 0
	s_cmp_gt_u32 s53, 41
	s_barrier
	s_cbranch_scc0 .LBB0_861
	s_and_b64 vcc, exec, s[12:13]
	s_cbranch_vccz .LBB0_864
	s_barrier
